# GEMM K-loops: keep s_setprio 1 across both 16-MFMA groups of a block (drop the s_setprio 0 / s_setprio 1 pair between them)
# baseline (speedup 1.0000x reference)
.LBB0_170:
	s_add_u32 s36, s70, 0xfff00080
	s_addc_u32 s72, s71, -1
	s_add_i32 s85, 0, 0x10000
	s_cmp_eq_u32 s84, 60
	s_cselect_b32 s73, s47, s72
	s_cselect_b32 s72, s74, s36
	v_add_u32_e32 v132, s85, v137
	s_cselect_b32 s87, s7, s81
	s_cselect_b32 s86, s75, s77
	s_add_i32 s36, 0, 0x14000
	ds_read_b128 v[156:159], v132
	ds_read_b128 v[160:163], v132 offset:1024
	ds_read_b128 v[164:167], v132 offset:2048
	ds_read_b128 v[180:183], v132 offset:3072
	v_add_u32_e32 v132, s36, v137
	ds_read_b128 v[184:187], v132
	ds_read_b128 v[188:191], v132 offset:1024
	ds_read_b128 v[192:195], v132 offset:2048
	ds_read_b128 v[196:199], v132 offset:3072
	v_lshl_add_u64 v[134:135], s[70:71], 0, v[130:131]
	s_add_i32 m0, s18, 0xc000
	ds_read_b128 v[204:207], v141
	ds_read_b128 v[208:211], v141 offset:1024
	ds_read_b128 v[212:215], v141 offset:2048
	ds_read_b128 v[216:219], v141 offset:3072
	ds_read_b128 v[220:223], v141 offset:4096
	ds_read_b128 v[224:227], v141 offset:5120
	ds_read_b128 v[228:231], v141 offset:6144
	ds_read_b128 v[232:235], v141 offset:7168
	global_load_lds_dwordx4 v[134:135], off
	v_lshl_add_u64 v[134:135], v[134:135], 0, s[56:57]
	s_add_i32 m0, s18, 0xe000
	s_nop 0
	global_load_lds_dwordx4 v[134:135], off
	s_waitcnt vmcnt(8)
	s_waitcnt lgkmcnt(0)
	s_barrier
	s_setprio 1
	s_waitcnt lgkmcnt(0)
	v_mfma_f32_16x16x32_bf16 v[124:127], v[156:159], v[204:207], v[124:127]
	v_mfma_f32_16x16x32_bf16 v[120:123], v[164:167], v[204:207], v[120:123]
	v_mfma_f32_16x16x32_bf16 v[108:111], v[156:159], v[212:215], v[108:111]
	v_mfma_f32_16x16x32_bf16 v[104:107], v[164:167], v[212:215], v[104:107]
	v_mfma_f32_16x16x32_bf16 v[92:95], v[156:159], v[220:223], v[92:95]
	v_mfma_f32_16x16x32_bf16 v[88:91], v[164:167], v[220:223], v[88:91]
	v_mfma_f32_16x16x32_bf16 v[76:79], v[156:159], v[228:231], v[76:79]
	v_mfma_f32_16x16x32_bf16 v[72:75], v[164:167], v[228:231], v[72:75]
	v_mfma_f32_16x16x32_bf16 v[124:127], v[160:163], v[208:211], v[124:127]
	v_mfma_f32_16x16x32_bf16 v[120:123], v[180:183], v[208:211], v[120:123]
	v_mfma_f32_16x16x32_bf16 v[108:111], v[160:163], v[216:219], v[108:111]
	v_mfma_f32_16x16x32_bf16 v[104:107], v[180:183], v[216:219], v[104:107]
	v_mfma_f32_16x16x32_bf16 v[92:95], v[160:163], v[224:227], v[92:95]
	v_mfma_f32_16x16x32_bf16 v[88:91], v[180:183], v[224:227], v[88:91]
	v_mfma_f32_16x16x32_bf16 v[76:79], v[160:163], v[232:235], v[76:79]
	v_mfma_f32_16x16x32_bf16 v[72:75], v[180:183], v[232:235], v[72:75]
	v_mfma_f32_16x16x32_bf16 v[116:119], v[184:187], v[204:207], v[116:119]
	v_mfma_f32_16x16x32_bf16 v[112:115], v[192:195], v[204:207], v[112:115]
	v_mfma_f32_16x16x32_bf16 v[100:103], v[184:187], v[212:215], v[100:103]
	v_mfma_f32_16x16x32_bf16 v[96:99], v[192:195], v[212:215], v[96:99]
	v_mfma_f32_16x16x32_bf16 v[84:87], v[184:187], v[220:223], v[84:87]
	v_mfma_f32_16x16x32_bf16 v[80:83], v[192:195], v[220:223], v[80:83]
	v_mfma_f32_16x16x32_bf16 v[68:71], v[184:187], v[228:231], v[68:71]
	v_mfma_f32_16x16x32_bf16 v[64:67], v[192:195], v[228:231], v[64:67]
	v_mfma_f32_16x16x32_bf16 v[116:119], v[188:191], v[208:211], v[116:119]
	v_mfma_f32_16x16x32_bf16 v[112:115], v[196:199], v[208:211], v[112:115]
	v_mfma_f32_16x16x32_bf16 v[100:103], v[188:191], v[216:219], v[100:103]
	v_mfma_f32_16x16x32_bf16 v[96:99], v[196:199], v[216:219], v[96:99]
	v_mfma_f32_16x16x32_bf16 v[84:87], v[188:191], v[224:227], v[84:87]
	v_mfma_f32_16x16x32_bf16 v[80:83], v[196:199], v[224:227], v[80:83]
	v_mfma_f32_16x16x32_bf16 v[68:71], v[188:191], v[232:235], v[68:71]
	v_mfma_f32_16x16x32_bf16 v[64:67], v[196:199], v[232:235], v[64:67]
	s_setprio 0
	s_barrier
	s_add_i32 s85, s85, s17
	v_lshl_add_u64 v[134:135], s[86:87], 0, v[144:145]
	s_mov_b32 m0, s85
	ds_read_b128 v[204:207], v141 offset:16384
	ds_read_b128 v[208:211], v141 offset:17408
	ds_read_b128 v[212:215], v141 offset:18432
	ds_read_b128 v[216:219], v141 offset:19456
	ds_read_b128 v[220:223], v141 offset:20480
	ds_read_b128 v[224:227], v141 offset:21504
	ds_read_b128 v[228:231], v141 offset:22528
	ds_read_b128 v[232:235], v141 offset:23552
	global_load_lds_dwordx4 v[134:135], off
	v_lshl_add_u64 v[142:143], v[134:135], 0, s[56:57]
	s_add_i32 m0, s85, 0x2000
	s_add_i32 s36, s36, s17
	global_load_lds_dwordx4 v[142:143], off
	v_lshl_add_u64 v[142:143], v[134:135], 0, s[54:55]
	s_mov_b32 m0, s36
	s_nop 0
	global_load_lds_dwordx4 v[142:143], off
	v_lshl_add_u64 v[142:143], v[134:135], 0, s[58:59]
	s_add_i32 m0, s36, 0x2000
	s_nop 0
	global_load_lds_dwordx4 v[142:143], off
	v_lshl_add_u64 v[142:143], s[72:73], 0, v[128:129]
	s_mov_b32 m0, s18
	v_lshl_add_u64 v[150:151], v[142:143], 0, s[56:57]
	global_load_lds_dwordx4 v[142:143], off
	s_mov_b32 m0, s19
	s_nop 0
	global_load_lds_dwordx4 v[150:151], off
	s_waitcnt vmcnt(8)
	s_waitcnt lgkmcnt(0)
	s_barrier
	s_setprio 1
	s_waitcnt lgkmcnt(0)
	v_mfma_f32_16x16x32_bf16 v[60:63], v[156:159], v[204:207], v[60:63]
	v_mfma_f32_16x16x32_bf16 v[56:59], v[164:167], v[204:207], v[56:59]
	v_mfma_f32_16x16x32_bf16 v[44:47], v[156:159], v[212:215], v[44:47]
	v_mfma_f32_16x16x32_bf16 v[40:43], v[164:167], v[212:215], v[40:43]
	v_mfma_f32_16x16x32_bf16 v[28:31], v[156:159], v[220:223], v[28:31]
	v_mfma_f32_16x16x32_bf16 v[24:27], v[164:167], v[220:223], v[24:27]
	v_mfma_f32_16x16x32_bf16 v[12:15], v[156:159], v[228:231], v[12:15]
	v_mfma_f32_16x16x32_bf16 v[8:11], v[164:167], v[228:231], v[8:11]
	v_mfma_f32_16x16x32_bf16 v[60:63], v[160:163], v[208:211], v[60:63]
	v_mfma_f32_16x16x32_bf16 v[56:59], v[180:183], v[208:211], v[56:59]
	v_mfma_f32_16x16x32_bf16 v[44:47], v[160:163], v[216:219], v[44:47]
	v_mfma_f32_16x16x32_bf16 v[40:43], v[180:183], v[216:219], v[40:43]
	v_mfma_f32_16x16x32_bf16 v[28:31], v[160:163], v[224:227], v[28:31]
	v_mfma_f32_16x16x32_bf16 v[24:27], v[180:183], v[224:227], v[24:27]
	v_mfma_f32_16x16x32_bf16 v[12:15], v[160:163], v[232:235], v[12:15]
	v_mfma_f32_16x16x32_bf16 v[8:11], v[180:183], v[232:235], v[8:11]
	v_mfma_f32_16x16x32_bf16 v[52:55], v[184:187], v[204:207], v[52:55]
	v_mfma_f32_16x16x32_bf16 v[48:51], v[192:195], v[204:207], v[48:51]
	v_mfma_f32_16x16x32_bf16 v[36:39], v[184:187], v[212:215], v[36:39]
	v_mfma_f32_16x16x32_bf16 v[32:35], v[192:195], v[212:215], v[32:35]
	v_mfma_f32_16x16x32_bf16 v[20:23], v[184:187], v[220:223], v[20:23]
	v_mfma_f32_16x16x32_bf16 v[16:19], v[192:195], v[220:223], v[16:19]
	v_mfma_f32_16x16x32_bf16 v[4:7], v[184:187], v[228:231], v[4:7]
	v_mfma_f32_16x16x32_bf16 v[0:3], v[192:195], v[228:231], v[0:3]
	v_mfma_f32_16x16x32_bf16 v[52:55], v[188:191], v[208:211], v[52:55]
	v_mfma_f32_16x16x32_bf16 v[48:51], v[196:199], v[208:211], v[48:51]
	v_mfma_f32_16x16x32_bf16 v[36:39], v[188:191], v[216:219], v[36:39]
	v_mfma_f32_16x16x32_bf16 v[32:35], v[196:199], v[216:219], v[32:35]
	v_mfma_f32_16x16x32_bf16 v[20:23], v[188:191], v[224:227], v[20:23]
	v_mfma_f32_16x16x32_bf16 v[16:19], v[196:199], v[224:227], v[16:19]
	v_mfma_f32_16x16x32_bf16 v[4:7], v[188:191], v[232:235], v[4:7]
	v_mfma_f32_16x16x32_bf16 v[0:3], v[196:199], v[232:235], v[0:3]
	s_setprio 0
	s_barrier
	s_add_i32 s36, 0, 0x18000
	v_add_u32_e32 v132, s36, v137
	s_add_i32 s72, 0, 0x1c000
	ds_read_b128 v[156:159], v132
	ds_read_b128 v[160:163], v132 offset:1024
	ds_read_b128 v[164:167], v132 offset:2048
	ds_read_b128 v[180:183], v132 offset:3072
	v_add_u32_e32 v132, s72, v137
	ds_read_b128 v[184:187], v132
	ds_read_b128 v[188:191], v132 offset:1024
	ds_read_b128 v[192:195], v132 offset:2048
	ds_read_b128 v[196:199], v132 offset:3072
	s_mov_b32 m0, s20
	v_lshl_add_u64 v[150:151], v[142:143], 0, s[54:55]
	ds_read_b128 v[204:207], v141 offset:32768
	ds_read_b128 v[208:211], v141 offset:33792
	ds_read_b128 v[212:215], v141 offset:34816
	ds_read_b128 v[216:219], v141 offset:35840
	ds_read_b128 v[220:223], v141 offset:36864
	ds_read_b128 v[224:227], v141 offset:37888
	ds_read_b128 v[228:231], v141 offset:38912
	ds_read_b128 v[232:235], v141 offset:39936
	global_load_lds_dwordx4 v[150:151], off
	v_lshl_add_u64 v[150:151], v[142:143], 0, s[58:59]
	s_mov_b32 m0, s21
	s_nop 0
	global_load_lds_dwordx4 v[150:151], off
	s_waitcnt vmcnt(8)
	s_waitcnt lgkmcnt(0)
	s_barrier
	s_setprio 1
	s_waitcnt lgkmcnt(0)
	v_mfma_f32_16x16x32_bf16 v[124:127], v[156:159], v[204:207], v[124:127]
	v_mfma_f32_16x16x32_bf16 v[120:123], v[164:167], v[204:207], v[120:123]
	v_mfma_f32_16x16x32_bf16 v[108:111], v[156:159], v[212:215], v[108:111]
	v_mfma_f32_16x16x32_bf16 v[104:107], v[164:167], v[212:215], v[104:107]
	v_mfma_f32_16x16x32_bf16 v[92:95], v[156:159], v[220:223], v[92:95]
	v_mfma_f32_16x16x32_bf16 v[88:91], v[164:167], v[220:223], v[88:91]
	v_mfma_f32_16x16x32_bf16 v[76:79], v[156:159], v[228:231], v[76:79]
	v_mfma_f32_16x16x32_bf16 v[72:75], v[164:167], v[228:231], v[72:75]
	v_mfma_f32_16x16x32_bf16 v[124:127], v[160:163], v[208:211], v[124:127]
	v_mfma_f32_16x16x32_bf16 v[120:123], v[180:183], v[208:211], v[120:123]
	v_mfma_f32_16x16x32_bf16 v[108:111], v[160:163], v[216:219], v[108:111]
	v_mfma_f32_16x16x32_bf16 v[104:107], v[180:183], v[216:219], v[104:107]
	v_mfma_f32_16x16x32_bf16 v[92:95], v[160:163], v[224:227], v[92:95]
	v_mfma_f32_16x16x32_bf16 v[88:91], v[180:183], v[224:227], v[88:91]
	v_mfma_f32_16x16x32_bf16 v[76:79], v[160:163], v[232:235], v[76:79]
	v_mfma_f32_16x16x32_bf16 v[72:75], v[180:183], v[232:235], v[72:75]
	v_mfma_f32_16x16x32_bf16 v[116:119], v[184:187], v[204:207], v[116:119]
	v_mfma_f32_16x16x32_bf16 v[112:115], v[192:195], v[204:207], v[112:115]
	v_mfma_f32_16x16x32_bf16 v[100:103], v[184:187], v[212:215], v[100:103]
	v_mfma_f32_16x16x32_bf16 v[96:99], v[192:195], v[212:215], v[96:99]
	v_mfma_f32_16x16x32_bf16 v[84:87], v[184:187], v[220:223], v[84:87]
	v_mfma_f32_16x16x32_bf16 v[80:83], v[192:195], v[220:223], v[80:83]
	v_mfma_f32_16x16x32_bf16 v[68:71], v[184:187], v[228:231], v[68:71]
	v_mfma_f32_16x16x32_bf16 v[64:67], v[192:195], v[228:231], v[64:67]
	v_mfma_f32_16x16x32_bf16 v[116:119], v[188:191], v[208:211], v[116:119]
	v_mfma_f32_16x16x32_bf16 v[112:115], v[196:199], v[208:211], v[112:115]
	v_mfma_f32_16x16x32_bf16 v[100:103], v[188:191], v[216:219], v[100:103]
	v_mfma_f32_16x16x32_bf16 v[96:99], v[196:199], v[216:219], v[96:99]
	v_mfma_f32_16x16x32_bf16 v[84:87], v[188:191], v[224:227], v[84:87]
	v_mfma_f32_16x16x32_bf16 v[80:83], v[196:199], v[224:227], v[80:83]
	v_mfma_f32_16x16x32_bf16 v[68:71], v[188:191], v[232:235], v[68:71]
	v_mfma_f32_16x16x32_bf16 v[64:67], v[196:199], v[232:235], v[64:67]
	s_setprio 0
	s_barrier
	s_add_i32 s36, s36, s17
	v_lshl_add_u64 v[150:151], v[134:135], 0, s[60:61]
	s_mov_b32 m0, s36
	ds_read_b128 v[204:207], v141 offset:49152
	ds_read_b128 v[208:211], v141 offset:50176
	ds_read_b128 v[212:215], v141 offset:51200
	ds_read_b128 v[216:219], v141 offset:52224
	ds_read_b128 v[220:223], v141 offset:53248
	ds_read_b128 v[224:227], v141 offset:54272
	ds_read_b128 v[228:231], v141 offset:55296
	ds_read_b128 v[232:235], v141 offset:56320
	global_load_lds_dwordx4 v[150:151], off
	v_lshl_add_u64 v[150:151], v[134:135], 0, s[62:63]
	s_add_i32 m0, s36, 0x2000
	s_add_i32 s36, s72, s17
	global_load_lds_dwordx4 v[150:151], off
	v_lshl_add_u64 v[150:151], v[134:135], 0, s[64:65]
	s_mov_b32 m0, s36
	v_lshl_add_u64 v[134:135], v[134:135], 0, s[66:67]
	global_load_lds_dwordx4 v[150:151], off
	s_add_i32 m0, s36, 0x2000
	s_nop 0
	global_load_lds_dwordx4 v[134:135], off
	v_lshl_add_u64 v[134:135], v[142:143], 0, s[60:61]
	s_mov_b32 m0, s22
	s_nop 0
	global_load_lds_dwordx4 v[134:135], off
	v_lshl_add_u64 v[134:135], v[142:143], 0, s[62:63]
	s_mov_b32 m0, s23
	s_nop 0
	global_load_lds_dwordx4 v[134:135], off
	s_waitcnt vmcnt(8)
	s_waitcnt lgkmcnt(0)
	s_barrier
	s_setprio 1
	s_waitcnt lgkmcnt(0)
	v_mfma_f32_16x16x32_bf16 v[60:63], v[156:159], v[204:207], v[60:63]
	v_mfma_f32_16x16x32_bf16 v[56:59], v[164:167], v[204:207], v[56:59]
	v_mfma_f32_16x16x32_bf16 v[44:47], v[156:159], v[212:215], v[44:47]
	v_mfma_f32_16x16x32_bf16 v[40:43], v[164:167], v[212:215], v[40:43]
	v_mfma_f32_16x16x32_bf16 v[28:31], v[156:159], v[220:223], v[28:31]
	v_mfma_f32_16x16x32_bf16 v[24:27], v[164:167], v[220:223], v[24:27]
	v_mfma_f32_16x16x32_bf16 v[12:15], v[156:159], v[228:231], v[12:15]
	v_mfma_f32_16x16x32_bf16 v[8:11], v[164:167], v[228:231], v[8:11]
	v_mfma_f32_16x16x32_bf16 v[60:63], v[160:163], v[208:211], v[60:63]
	v_mfma_f32_16x16x32_bf16 v[56:59], v[180:183], v[208:211], v[56:59]
	v_mfma_f32_16x16x32_bf16 v[44:47], v[160:163], v[216:219], v[44:47]
	v_mfma_f32_16x16x32_bf16 v[40:43], v[180:183], v[216:219], v[40:43]
	v_mfma_f32_16x16x32_bf16 v[28:31], v[160:163], v[224:227], v[28:31]
	v_mfma_f32_16x16x32_bf16 v[24:27], v[180:183], v[224:227], v[24:27]
	v_mfma_f32_16x16x32_bf16 v[12:15], v[160:163], v[232:235], v[12:15]
	v_mfma_f32_16x16x32_bf16 v[8:11], v[180:183], v[232:235], v[8:11]
	v_mfma_f32_16x16x32_bf16 v[52:55], v[184:187], v[204:207], v[52:55]
	v_mfma_f32_16x16x32_bf16 v[48:51], v[192:195], v[204:207], v[48:51]
	v_mfma_f32_16x16x32_bf16 v[36:39], v[184:187], v[212:215], v[36:39]
	v_mfma_f32_16x16x32_bf16 v[32:35], v[192:195], v[212:215], v[32:35]
	v_mfma_f32_16x16x32_bf16 v[20:23], v[184:187], v[220:223], v[20:23]
	v_mfma_f32_16x16x32_bf16 v[16:19], v[192:195], v[220:223], v[16:19]
	v_mfma_f32_16x16x32_bf16 v[4:7], v[184:187], v[228:231], v[4:7]
	v_mfma_f32_16x16x32_bf16 v[0:3], v[192:195], v[228:231], v[0:3]
	v_mfma_f32_16x16x32_bf16 v[52:55], v[188:191], v[208:211], v[52:55]
	v_mfma_f32_16x16x32_bf16 v[48:51], v[196:199], v[208:211], v[48:51]
	v_mfma_f32_16x16x32_bf16 v[36:39], v[188:191], v[216:219], v[36:39]
	v_mfma_f32_16x16x32_bf16 v[32:35], v[196:199], v[216:219], v[32:35]
	v_mfma_f32_16x16x32_bf16 v[20:23], v[188:191], v[224:227], v[20:23]
	v_mfma_f32_16x16x32_bf16 v[16:19], v[196:199], v[224:227], v[16:19]
	v_mfma_f32_16x16x32_bf16 v[4:7], v[188:191], v[232:235], v[4:7]
	v_mfma_f32_16x16x32_bf16 v[0:3], v[196:199], v[232:235], v[0:3]
	s_setprio 0
	s_barrier
	s_add_i32 s84, s84, 2
	s_add_u32 s70, s70, 0x100
	s_addc_u32 s71, s71, 0
	s_add_u32 s77, s77, 0x100
	s_addc_u32 s81, s81, 0
	s_cmp_gt_u32 s84, 61
	s_cbranch_scc0 .LBB0_170
	s_and_b64 vcc, exec, s[4:5]
	s_movk_i32 s77, 0x7fff
	s_cbranch_vccz .LBB0_173
	s_barrier

.LBB0_333:
	s_add_u32 s36, s70, 0xfff00080
	s_addc_u32 s72, s71, -1
	s_add_i32 s85, 0, 0x10000
	s_cmp_eq_u32 s81, 60
	s_cselect_b32 s73, s42, s72
	s_cselect_b32 s72, s47, s36
	v_add_u32_e32 v132, s85, v137
	s_cselect_b32 s87, s7, s77
	s_cselect_b32 s86, s74, s75
	s_add_i32 s36, 0, 0x14000
	ds_read_b128 v[156:159], v132
	ds_read_b128 v[160:163], v132 offset:1024
	ds_read_b128 v[164:167], v132 offset:2048
	ds_read_b128 v[180:183], v132 offset:3072
	v_add_u32_e32 v132, s36, v137
	ds_read_b128 v[184:187], v132
	ds_read_b128 v[188:191], v132 offset:1024
	ds_read_b128 v[192:195], v132 offset:2048
	ds_read_b128 v[196:199], v132 offset:3072
	v_lshl_add_u64 v[134:135], s[70:71], 0, v[130:131]
	s_add_i32 m0, s18, 0xc000
	ds_read_b128 v[204:207], v141
	ds_read_b128 v[208:211], v141 offset:1024
	ds_read_b128 v[212:215], v141 offset:2048
	ds_read_b128 v[216:219], v141 offset:3072
	ds_read_b128 v[220:223], v141 offset:4096
	ds_read_b128 v[224:227], v141 offset:5120
	ds_read_b128 v[228:231], v141 offset:6144
	ds_read_b128 v[232:235], v141 offset:7168
	global_load_lds_dwordx4 v[134:135], off
	v_lshl_add_u64 v[134:135], v[134:135], 0, s[56:57]
	s_add_i32 m0, s18, 0xe000
	s_nop 0
	global_load_lds_dwordx4 v[134:135], off
	s_waitcnt vmcnt(8)
	s_waitcnt lgkmcnt(0)
	s_barrier
	s_setprio 1
	s_waitcnt lgkmcnt(0)
	v_mfma_f32_16x16x32_bf16 v[124:127], v[156:159], v[204:207], v[124:127]
	v_mfma_f32_16x16x32_bf16 v[120:123], v[164:167], v[204:207], v[120:123]
	v_mfma_f32_16x16x32_bf16 v[108:111], v[156:159], v[212:215], v[108:111]
	v_mfma_f32_16x16x32_bf16 v[104:107], v[164:167], v[212:215], v[104:107]
	v_mfma_f32_16x16x32_bf16 v[92:95], v[156:159], v[220:223], v[92:95]
	v_mfma_f32_16x16x32_bf16 v[88:91], v[164:167], v[220:223], v[88:91]
	v_mfma_f32_16x16x32_bf16 v[76:79], v[156:159], v[228:231], v[76:79]
	v_mfma_f32_16x16x32_bf16 v[72:75], v[164:167], v[228:231], v[72:75]
	v_mfma_f32_16x16x32_bf16 v[124:127], v[160:163], v[208:211], v[124:127]
	v_mfma_f32_16x16x32_bf16 v[120:123], v[180:183], v[208:211], v[120:123]
	v_mfma_f32_16x16x32_bf16 v[108:111], v[160:163], v[216:219], v[108:111]
	v_mfma_f32_16x16x32_bf16 v[104:107], v[180:183], v[216:219], v[104:107]
	v_mfma_f32_16x16x32_bf16 v[92:95], v[160:163], v[224:227], v[92:95]
	v_mfma_f32_16x16x32_bf16 v[88:91], v[180:183], v[224:227], v[88:91]
	v_mfma_f32_16x16x32_bf16 v[76:79], v[160:163], v[232:235], v[76:79]
	v_mfma_f32_16x16x32_bf16 v[72:75], v[180:183], v[232:235], v[72:75]
	v_mfma_f32_16x16x32_bf16 v[116:119], v[184:187], v[204:207], v[116:119]
	v_mfma_f32_16x16x32_bf16 v[112:115], v[192:195], v[204:207], v[112:115]
	v_mfma_f32_16x16x32_bf16 v[100:103], v[184:187], v[212:215], v[100:103]
	v_mfma_f32_16x16x32_bf16 v[96:99], v[192:195], v[212:215], v[96:99]
	v_mfma_f32_16x16x32_bf16 v[84:87], v[184:187], v[220:223], v[84:87]
	v_mfma_f32_16x16x32_bf16 v[80:83], v[192:195], v[220:223], v[80:83]
	v_mfma_f32_16x16x32_bf16 v[68:71], v[184:187], v[228:231], v[68:71]
	v_mfma_f32_16x16x32_bf16 v[64:67], v[192:195], v[228:231], v[64:67]
	v_mfma_f32_16x16x32_bf16 v[116:119], v[188:191], v[208:211], v[116:119]
	v_mfma_f32_16x16x32_bf16 v[112:115], v[196:199], v[208:211], v[112:115]
	v_mfma_f32_16x16x32_bf16 v[100:103], v[188:191], v[216:219], v[100:103]
	v_mfma_f32_16x16x32_bf16 v[96:99], v[196:199], v[216:219], v[96:99]
	v_mfma_f32_16x16x32_bf16 v[84:87], v[188:191], v[224:227], v[84:87]
	v_mfma_f32_16x16x32_bf16 v[80:83], v[196:199], v[224:227], v[80:83]
	v_mfma_f32_16x16x32_bf16 v[68:71], v[188:191], v[232:235], v[68:71]
	v_mfma_f32_16x16x32_bf16 v[64:67], v[196:199], v[232:235], v[64:67]
	s_setprio 0
	s_barrier
	s_add_i32 s85, s85, s17
	v_lshl_add_u64 v[134:135], s[86:87], 0, v[144:145]
	s_mov_b32 m0, s85
	ds_read_b128 v[204:207], v141 offset:16384
	ds_read_b128 v[208:211], v141 offset:17408
	ds_read_b128 v[212:215], v141 offset:18432
	ds_read_b128 v[216:219], v141 offset:19456
	ds_read_b128 v[220:223], v141 offset:20480
	ds_read_b128 v[224:227], v141 offset:21504
	ds_read_b128 v[228:231], v141 offset:22528
	ds_read_b128 v[232:235], v141 offset:23552
	global_load_lds_dwordx4 v[134:135], off
	v_lshl_add_u64 v[142:143], v[134:135], 0, s[56:57]
	s_add_i32 m0, s85, 0x2000
	s_add_i32 s36, s36, s17
	global_load_lds_dwordx4 v[142:143], off
	v_lshl_add_u64 v[142:143], v[134:135], 0, s[54:55]
	s_mov_b32 m0, s36
	s_nop 0
	global_load_lds_dwordx4 v[142:143], off
	v_lshl_add_u64 v[142:143], v[134:135], 0, s[58:59]
	s_add_i32 m0, s36, 0x2000
	s_nop 0
	global_load_lds_dwordx4 v[142:143], off
	v_lshl_add_u64 v[142:143], s[72:73], 0, v[128:129]
	s_mov_b32 m0, s18
	v_lshl_add_u64 v[150:151], v[142:143], 0, s[56:57]
	global_load_lds_dwordx4 v[142:143], off
	s_mov_b32 m0, s19
	s_nop 0
	global_load_lds_dwordx4 v[150:151], off
	s_waitcnt vmcnt(8)
	s_waitcnt lgkmcnt(0)
	s_barrier
	s_setprio 1
	s_waitcnt lgkmcnt(0)
	v_mfma_f32_16x16x32_bf16 v[60:63], v[156:159], v[204:207], v[60:63]
	v_mfma_f32_16x16x32_bf16 v[56:59], v[164:167], v[204:207], v[56:59]
	v_mfma_f32_16x16x32_bf16 v[44:47], v[156:159], v[212:215], v[44:47]
	v_mfma_f32_16x16x32_bf16 v[40:43], v[164:167], v[212:215], v[40:43]
	v_mfma_f32_16x16x32_bf16 v[28:31], v[156:159], v[220:223], v[28:31]
	v_mfma_f32_16x16x32_bf16 v[24:27], v[164:167], v[220:223], v[24:27]
	v_mfma_f32_16x16x32_bf16 v[12:15], v[156:159], v[228:231], v[12:15]
	v_mfma_f32_16x16x32_bf16 v[8:11], v[164:167], v[228:231], v[8:11]
	v_mfma_f32_16x16x32_bf16 v[60:63], v[160:163], v[208:211], v[60:63]
	v_mfma_f32_16x16x32_bf16 v[56:59], v[180:183], v[208:211], v[56:59]
	v_mfma_f32_16x16x32_bf16 v[44:47], v[160:163], v[216:219], v[44:47]
	v_mfma_f32_16x16x32_bf16 v[40:43], v[180:183], v[216:219], v[40:43]
	v_mfma_f32_16x16x32_bf16 v[28:31], v[160:163], v[224:227], v[28:31]
	v_mfma_f32_16x16x32_bf16 v[24:27], v[180:183], v[224:227], v[24:27]
	v_mfma_f32_16x16x32_bf16 v[12:15], v[160:163], v[232:235], v[12:15]
	v_mfma_f32_16x16x32_bf16 v[8:11], v[180:183], v[232:235], v[8:11]
	v_mfma_f32_16x16x32_bf16 v[52:55], v[184:187], v[204:207], v[52:55]
	v_mfma_f32_16x16x32_bf16 v[48:51], v[192:195], v[204:207], v[48:51]
	v_mfma_f32_16x16x32_bf16 v[36:39], v[184:187], v[212:215], v[36:39]
	v_mfma_f32_16x16x32_bf16 v[32:35], v[192:195], v[212:215], v[32:35]
	v_mfma_f32_16x16x32_bf16 v[20:23], v[184:187], v[220:223], v[20:23]
	v_mfma_f32_16x16x32_bf16 v[16:19], v[192:195], v[220:223], v[16:19]
	v_mfma_f32_16x16x32_bf16 v[4:7], v[184:187], v[228:231], v[4:7]
	v_mfma_f32_16x16x32_bf16 v[0:3], v[192:195], v[228:231], v[0:3]
	v_mfma_f32_16x16x32_bf16 v[52:55], v[188:191], v[208:211], v[52:55]
	v_mfma_f32_16x16x32_bf16 v[48:51], v[196:199], v[208:211], v[48:51]
	v_mfma_f32_16x16x32_bf16 v[36:39], v[188:191], v[216:219], v[36:39]
	v_mfma_f32_16x16x32_bf16 v[32:35], v[196:199], v[216:219], v[32:35]
	v_mfma_f32_16x16x32_bf16 v[20:23], v[188:191], v[224:227], v[20:23]
	v_mfma_f32_16x16x32_bf16 v[16:19], v[196:199], v[224:227], v[16:19]
	v_mfma_f32_16x16x32_bf16 v[4:7], v[188:191], v[232:235], v[4:7]
	v_mfma_f32_16x16x32_bf16 v[0:3], v[196:199], v[232:235], v[0:3]
	s_setprio 0
	s_barrier
	s_add_i32 s36, 0, 0x18000
	v_add_u32_e32 v132, s36, v137
	s_add_i32 s72, 0, 0x1c000
	ds_read_b128 v[156:159], v132
	ds_read_b128 v[160:163], v132 offset:1024
	ds_read_b128 v[164:167], v132 offset:2048
	ds_read_b128 v[180:183], v132 offset:3072
	v_add_u32_e32 v132, s72, v137
	ds_read_b128 v[184:187], v132
	ds_read_b128 v[188:191], v132 offset:1024
	ds_read_b128 v[192:195], v132 offset:2048
	ds_read_b128 v[196:199], v132 offset:3072
	s_mov_b32 m0, s20
	v_lshl_add_u64 v[150:151], v[142:143], 0, s[54:55]
	ds_read_b128 v[204:207], v141 offset:32768
	ds_read_b128 v[208:211], v141 offset:33792
	ds_read_b128 v[212:215], v141 offset:34816
	ds_read_b128 v[216:219], v141 offset:35840
	ds_read_b128 v[220:223], v141 offset:36864
	ds_read_b128 v[224:227], v141 offset:37888
	ds_read_b128 v[228:231], v141 offset:38912
	ds_read_b128 v[232:235], v141 offset:39936
	global_load_lds_dwordx4 v[150:151], off
	v_lshl_add_u64 v[150:151], v[142:143], 0, s[58:59]
	s_mov_b32 m0, s21
	s_nop 0
	global_load_lds_dwordx4 v[150:151], off
	s_waitcnt vmcnt(8)
	s_waitcnt lgkmcnt(0)
	s_barrier
	s_setprio 1
	s_waitcnt lgkmcnt(0)
	v_mfma_f32_16x16x32_bf16 v[124:127], v[156:159], v[204:207], v[124:127]
	v_mfma_f32_16x16x32_bf16 v[120:123], v[164:167], v[204:207], v[120:123]
	v_mfma_f32_16x16x32_bf16 v[108:111], v[156:159], v[212:215], v[108:111]
	v_mfma_f32_16x16x32_bf16 v[104:107], v[164:167], v[212:215], v[104:107]
	v_mfma_f32_16x16x32_bf16 v[92:95], v[156:159], v[220:223], v[92:95]
	v_mfma_f32_16x16x32_bf16 v[88:91], v[164:167], v[220:223], v[88:91]
	v_mfma_f32_16x16x32_bf16 v[76:79], v[156:159], v[228:231], v[76:79]
	v_mfma_f32_16x16x32_bf16 v[72:75], v[164:167], v[228:231], v[72:75]
	v_mfma_f32_16x16x32_bf16 v[124:127], v[160:163], v[208:211], v[124:127]
	v_mfma_f32_16x16x32_bf16 v[120:123], v[180:183], v[208:211], v[120:123]
	v_mfma_f32_16x16x32_bf16 v[108:111], v[160:163], v[216:219], v[108:111]
	v_mfma_f32_16x16x32_bf16 v[104:107], v[180:183], v[216:219], v[104:107]
	v_mfma_f32_16x16x32_bf16 v[92:95], v[160:163], v[224:227], v[92:95]
	v_mfma_f32_16x16x32_bf16 v[88:91], v[180:183], v[224:227], v[88:91]
	v_mfma_f32_16x16x32_bf16 v[76:79], v[160:163], v[232:235], v[76:79]
	v_mfma_f32_16x16x32_bf16 v[72:75], v[180:183], v[232:235], v[72:75]
	v_mfma_f32_16x16x32_bf16 v[116:119], v[184:187], v[204:207], v[116:119]
	v_mfma_f32_16x16x32_bf16 v[112:115], v[192:195], v[204:207], v[112:115]
	v_mfma_f32_16x16x32_bf16 v[100:103], v[184:187], v[212:215], v[100:103]
	v_mfma_f32_16x16x32_bf16 v[96:99], v[192:195], v[212:215], v[96:99]
	v_mfma_f32_16x16x32_bf16 v[84:87], v[184:187], v[220:223], v[84:87]
	v_mfma_f32_16x16x32_bf16 v[80:83], v[192:195], v[220:223], v[80:83]
	v_mfma_f32_16x16x32_bf16 v[68:71], v[184:187], v[228:231], v[68:71]
	v_mfma_f32_16x16x32_bf16 v[64:67], v[192:195], v[228:231], v[64:67]
	v_mfma_f32_16x16x32_bf16 v[116:119], v[188:191], v[208:211], v[116:119]
	v_mfma_f32_16x16x32_bf16 v[112:115], v[196:199], v[208:211], v[112:115]
	v_mfma_f32_16x16x32_bf16 v[100:103], v[188:191], v[216:219], v[100:103]
	v_mfma_f32_16x16x32_bf16 v[96:99], v[196:199], v[216:219], v[96:99]
	v_mfma_f32_16x16x32_bf16 v[84:87], v[188:191], v[224:227], v[84:87]
	v_mfma_f32_16x16x32_bf16 v[80:83], v[196:199], v[224:227], v[80:83]
	v_mfma_f32_16x16x32_bf16 v[68:71], v[188:191], v[232:235], v[68:71]
	v_mfma_f32_16x16x32_bf16 v[64:67], v[196:199], v[232:235], v[64:67]
	s_setprio 0
	s_barrier
	s_add_i32 s36, s36, s17
	v_lshl_add_u64 v[150:151], v[134:135], 0, s[60:61]
	s_mov_b32 m0, s36
	ds_read_b128 v[204:207], v141 offset:49152
	ds_read_b128 v[208:211], v141 offset:50176
	ds_read_b128 v[212:215], v141 offset:51200
	ds_read_b128 v[216:219], v141 offset:52224
	ds_read_b128 v[220:223], v141 offset:53248
	ds_read_b128 v[224:227], v141 offset:54272
	ds_read_b128 v[228:231], v141 offset:55296
	ds_read_b128 v[232:235], v141 offset:56320
	global_load_lds_dwordx4 v[150:151], off
	v_lshl_add_u64 v[150:151], v[134:135], 0, s[62:63]
	s_add_i32 m0, s36, 0x2000
	s_add_i32 s36, s72, s17
	global_load_lds_dwordx4 v[150:151], off
	v_lshl_add_u64 v[150:151], v[134:135], 0, s[64:65]
	s_mov_b32 m0, s36
	v_lshl_add_u64 v[134:135], v[134:135], 0, s[66:67]
	global_load_lds_dwordx4 v[150:151], off
	s_add_i32 m0, s36, 0x2000
	s_nop 0
	global_load_lds_dwordx4 v[134:135], off
	v_lshl_add_u64 v[134:135], v[142:143], 0, s[60:61]
	s_mov_b32 m0, s22
	s_nop 0
	global_load_lds_dwordx4 v[134:135], off
	v_lshl_add_u64 v[134:135], v[142:143], 0, s[62:63]
	s_mov_b32 m0, s23
	s_nop 0
	global_load_lds_dwordx4 v[134:135], off
	s_waitcnt vmcnt(8)
	s_waitcnt lgkmcnt(0)
	s_barrier
	s_setprio 1
	s_waitcnt lgkmcnt(0)
	v_mfma_f32_16x16x32_bf16 v[60:63], v[156:159], v[204:207], v[60:63]
	v_mfma_f32_16x16x32_bf16 v[56:59], v[164:167], v[204:207], v[56:59]
	v_mfma_f32_16x16x32_bf16 v[44:47], v[156:159], v[212:215], v[44:47]
	v_mfma_f32_16x16x32_bf16 v[40:43], v[164:167], v[212:215], v[40:43]
	v_mfma_f32_16x16x32_bf16 v[28:31], v[156:159], v[220:223], v[28:31]
	v_mfma_f32_16x16x32_bf16 v[24:27], v[164:167], v[220:223], v[24:27]
	v_mfma_f32_16x16x32_bf16 v[12:15], v[156:159], v[228:231], v[12:15]
	v_mfma_f32_16x16x32_bf16 v[8:11], v[164:167], v[228:231], v[8:11]
	v_mfma_f32_16x16x32_bf16 v[60:63], v[160:163], v[208:211], v[60:63]
	v_mfma_f32_16x16x32_bf16 v[56:59], v[180:183], v[208:211], v[56:59]
	v_mfma_f32_16x16x32_bf16 v[44:47], v[160:163], v[216:219], v[44:47]
	v_mfma_f32_16x16x32_bf16 v[40:43], v[180:183], v[216:219], v[40:43]
	v_mfma_f32_16x16x32_bf16 v[28:31], v[160:163], v[224:227], v[28:31]
	v_mfma_f32_16x16x32_bf16 v[24:27], v[180:183], v[224:227], v[24:27]
	v_mfma_f32_16x16x32_bf16 v[12:15], v[160:163], v[232:235], v[12:15]
	v_mfma_f32_16x16x32_bf16 v[8:11], v[180:183], v[232:235], v[8:11]
	v_mfma_f32_16x16x32_bf16 v[52:55], v[184:187], v[204:207], v[52:55]
	v_mfma_f32_16x16x32_bf16 v[48:51], v[192:195], v[204:207], v[48:51]
	v_mfma_f32_16x16x32_bf16 v[36:39], v[184:187], v[212:215], v[36:39]
	v_mfma_f32_16x16x32_bf16 v[32:35], v[192:195], v[212:215], v[32:35]
	v_mfma_f32_16x16x32_bf16 v[20:23], v[184:187], v[220:223], v[20:23]
	v_mfma_f32_16x16x32_bf16 v[16:19], v[192:195], v[220:223], v[16:19]
	v_mfma_f32_16x16x32_bf16 v[4:7], v[184:187], v[228:231], v[4:7]
	v_mfma_f32_16x16x32_bf16 v[0:3], v[192:195], v[228:231], v[0:3]
	v_mfma_f32_16x16x32_bf16 v[52:55], v[188:191], v[208:211], v[52:55]
	v_mfma_f32_16x16x32_bf16 v[48:51], v[196:199], v[208:211], v[48:51]
	v_mfma_f32_16x16x32_bf16 v[36:39], v[188:191], v[216:219], v[36:39]
	v_mfma_f32_16x16x32_bf16 v[32:35], v[196:199], v[216:219], v[32:35]
	v_mfma_f32_16x16x32_bf16 v[20:23], v[188:191], v[224:227], v[20:23]
	v_mfma_f32_16x16x32_bf16 v[16:19], v[196:199], v[224:227], v[16:19]
	v_mfma_f32_16x16x32_bf16 v[4:7], v[188:191], v[232:235], v[4:7]
	v_mfma_f32_16x16x32_bf16 v[0:3], v[196:199], v[232:235], v[0:3]
	s_setprio 0
	s_barrier
	s_add_i32 s81, s81, 2
	s_add_u32 s70, s70, 0x100
	s_addc_u32 s71, s71, 0
	s_add_u32 s75, s75, 0x100
	s_addc_u32 s77, s77, 0
	s_cmp_gt_u32 s81, 61
	s_cbranch_scc0 .LBB0_333
	s_and_b64 vcc, exec, s[4:5]
	s_movk_i32 s77, 0x7fff
	s_cbranch_vccz .LBB0_336
	s_barrier

.LBB0_486:
	s_lshl_b32 s18, s92, 7
	s_and_b32 s18, s18, 0xffffff00
	s_ashr_i32 s71, s70, 31
	s_ashr_i32 s19, s18, 31
	s_lshl_b64 s[20:21], s[70:71], 21
	s_add_u32 s20, s4, s20
	s_addc_u32 s21, s5, s21
	s_lshl_b64 s[18:19], s[18:19], 1
	s_add_u32 s74, s20, s18
	s_addc_u32 s75, s21, s19
	s_and_b64 s[18:19], s[2:3], exec
	s_cselect_b32 vcc_hi, s75, s7
	s_cselect_b32 vcc_lo, s74, s6
	s_ashr_i32 s93, s92, 31
	s_lshl_b64 s[18:19], s[92:93], 17
	s_add_u32 s72, s37, s18
	s_addc_u32 s73, s38, s19
	s_and_b64 s[18:19], s[2:3], exec
	s_cselect_b32 s77, s73, s69
	s_cselect_b32 s76, s72, s68
	s_add_i32 s21, 0, 0x10000
	s_add_i32 s22, 0, 0x14000
	v_add_u32_e32 v152, s21, v179
	v_add_u32_e32 v153, s22, v179
	ds_read_b128 v[2:5], v152
	ds_read_b128 v[6:9], v152 offset:1024
	ds_read_b128 v[10:13], v152 offset:2048
	ds_read_b128 v[14:17], v152 offset:3072
	ds_read_b128 v[18:21], v153
	ds_read_b128 v[22:25], v153 offset:1024
	ds_read_b128 v[26:29], v153 offset:2048
	ds_read_b128 v[30:33], v153 offset:3072
	v_lshl_add_u64 v[0:1], s[6:7], 0, v[156:157]
	s_add_i32 s20, s79, 0xc000
	v_lshl_add_u64 v[66:67], v[0:1], 0, s[64:65]
	s_mov_b32 m0, s20
	s_add_i32 s6, s79, 0xe000
	ds_read_b128 v[34:37], v181
	ds_read_b128 v[38:41], v181 offset:1024
	ds_read_b128 v[42:45], v181 offset:2048
	ds_read_b128 v[46:49], v181 offset:3072
	ds_read_b128 v[50:53], v181 offset:4096
	ds_read_b128 v[54:57], v181 offset:5120
	ds_read_b128 v[58:61], v181 offset:6144
	ds_read_b128 v[62:65], v181 offset:7168
	global_load_lds_dwordx4 v[66:67], off
	v_lshl_add_u64 v[66:67], v[0:1], 0, s[66:67]
	s_mov_b32 m0, s6
	s_nop 0
	global_load_lds_dwordx4 v[66:67], off
	s_waitcnt vmcnt(8)
	s_waitcnt lgkmcnt(0)
	s_barrier
	s_setprio 1
	s_waitcnt lgkmcnt(0)
	v_mfma_f32_16x16x32_bf16 v[66:69], v[2:5], v[34:37], 0
	v_mfma_f32_16x16x32_bf16 v[70:73], v[10:13], v[34:37], 0
	v_mfma_f32_16x16x32_bf16 v[74:77], v[2:5], v[42:45], 0
	v_mfma_f32_16x16x32_bf16 v[78:81], v[10:13], v[42:45], 0
	s_waitcnt vmcnt(0)
	v_mfma_f32_16x16x32_bf16 v[82:85], v[2:5], v[50:53], 0
	v_mfma_f32_16x16x32_bf16 v[86:89], v[10:13], v[50:53], 0
	v_mfma_f32_16x16x32_bf16 v[90:93], v[2:5], v[58:61], 0
	v_mfma_f32_16x16x32_bf16 v[94:97], v[10:13], v[58:61], 0
	v_mfma_f32_16x16x32_bf16 v[66:69], v[6:9], v[38:41], v[66:69]
	v_mfma_f32_16x16x32_bf16 v[70:73], v[14:17], v[38:41], v[70:73]
	v_mfma_f32_16x16x32_bf16 v[74:77], v[6:9], v[46:49], v[74:77]
	v_mfma_f32_16x16x32_bf16 v[78:81], v[14:17], v[46:49], v[78:81]
	v_mfma_f32_16x16x32_bf16 v[82:85], v[6:9], v[54:57], v[82:85]
	v_mfma_f32_16x16x32_bf16 v[86:89], v[14:17], v[54:57], v[86:89]
	v_mfma_f32_16x16x32_bf16 v[90:93], v[6:9], v[62:65], v[90:93]
	v_mfma_f32_16x16x32_bf16 v[94:97], v[14:17], v[62:65], v[94:97]
	v_mfma_f32_16x16x32_bf16 v[98:101], v[18:21], v[34:37], 0
	v_mfma_f32_16x16x32_bf16 v[34:37], v[26:29], v[34:37], 0
	v_mfma_f32_16x16x32_bf16 v[98:101], v[22:25], v[38:41], v[98:101]
	v_mfma_f32_16x16x32_bf16 v[34:37], v[30:33], v[38:41], v[34:37]
	v_mfma_f32_16x16x32_bf16 v[38:41], v[18:21], v[42:45], 0
	v_mfma_f32_16x16x32_bf16 v[42:45], v[26:29], v[42:45], 0
	v_mfma_f32_16x16x32_bf16 v[38:41], v[22:25], v[46:49], v[38:41]
	v_mfma_f32_16x16x32_bf16 v[42:45], v[30:33], v[46:49], v[42:45]
	v_mfma_f32_16x16x32_bf16 v[46:49], v[18:21], v[50:53], 0
	v_mfma_f32_16x16x32_bf16 v[50:53], v[26:29], v[50:53], 0
	v_mfma_f32_16x16x32_bf16 v[46:49], v[22:25], v[54:57], v[46:49]
	v_mfma_f32_16x16x32_bf16 v[50:53], v[30:33], v[54:57], v[50:53]
	v_mfma_f32_16x16x32_bf16 v[54:57], v[18:21], v[58:61], 0
	v_mfma_f32_16x16x32_bf16 v[58:61], v[26:29], v[58:61], 0
	v_mfma_f32_16x16x32_bf16 v[54:57], v[22:25], v[62:65], v[54:57]
	v_mfma_f32_16x16x32_bf16 v[58:61], v[30:33], v[62:65], v[58:61]
	s_setprio 0
	s_barrier
	v_lshl_add_u64 v[142:143], s[68:69], 0, v[144:145]
	s_mov_b64 s[44:45], 0x100
	s_add_i32 s21, s21, s39
	v_lshl_add_u64 v[130:131], v[142:143], 0, s[44:45]
	s_mov_b32 m0, s21
	s_mov_b64 s[18:19], 0x8100
	s_add_i32 s7, s21, 0x2000
	ds_read_b128 v[62:65], v181 offset:16384
	ds_read_b128 v[102:105], v181 offset:17408
	ds_read_b128 v[106:109], v181 offset:18432
	ds_read_b128 v[110:113], v181 offset:19456
	ds_read_b128 v[114:117], v181 offset:20480
	ds_read_b128 v[118:121], v181 offset:21504
	ds_read_b128 v[122:125], v181 offset:22528
	ds_read_b128 v[126:129], v181 offset:23552
	global_load_lds_dwordx4 v[130:131], off
	v_lshl_add_u64 v[130:131], v[142:143], 0, s[18:19]
	s_mov_b32 m0, s7
	s_mov_b64 s[18:19], 0x10100
	global_load_lds_dwordx4 v[130:131], off
	v_lshl_add_u64 v[130:131], v[142:143], 0, s[18:19]
	s_add_i32 s18, s22, s39
	s_mov_b32 m0, s18
	s_mov_b64 s[22:23], 0x18100
	s_add_i32 s19, s18, 0x2000
	global_load_lds_dwordx4 v[130:131], off
	v_lshl_add_u64 v[130:131], v[142:143], 0, s[22:23]
	s_mov_b32 m0, s19
	s_mov_b64 s[22:23], 0x80100
	global_load_lds_dwordx4 v[130:131], off
	v_lshl_add_u64 v[130:131], v[0:1], 0, s[44:45]
	s_mov_b32 m0, s79
	s_nop 0
	global_load_lds_dwordx4 v[130:131], off
	v_lshl_add_u64 v[130:131], v[0:1], 0, s[22:23]
	s_mov_b32 m0, s42
	s_nop 0
	global_load_lds_dwordx4 v[130:131], off
	s_waitcnt vmcnt(8)
	s_waitcnt lgkmcnt(0)
	s_barrier
	s_setprio 1
	s_waitcnt lgkmcnt(0)
	v_mfma_f32_16x16x32_bf16 v[130:133], v[2:5], v[62:65], 0
	v_mfma_f32_16x16x32_bf16 v[138:141], v[2:5], v[106:109], 0
	v_mfma_f32_16x16x32_bf16 v[162:165], v[2:5], v[114:117], 0
	v_mfma_f32_16x16x32_bf16 v[2:5], v[2:5], v[122:125], 0
	v_mfma_f32_16x16x32_bf16 v[130:133], v[6:9], v[102:105], v[130:133]
	v_mfma_f32_16x16x32_bf16 v[134:137], v[10:13], v[62:65], 0
	v_mfma_f32_16x16x32_bf16 v[138:141], v[6:9], v[110:113], v[138:141]
	v_mfma_f32_16x16x32_bf16 v[162:165], v[6:9], v[118:121], v[162:165]
	v_mfma_f32_16x16x32_bf16 v[2:5], v[6:9], v[126:129], v[2:5]
	v_mfma_f32_16x16x32_bf16 v[6:9], v[10:13], v[122:125], 0
	v_mfma_f32_16x16x32_bf16 v[134:137], v[14:17], v[102:105], v[134:137]
	v_mfma_f32_16x16x32_bf16 v[158:161], v[10:13], v[106:109], 0
	v_mfma_f32_16x16x32_bf16 v[166:169], v[10:13], v[114:117], 0
	v_mfma_f32_16x16x32_bf16 v[6:9], v[14:17], v[126:129], v[6:9]
	v_mfma_f32_16x16x32_bf16 v[158:161], v[14:17], v[110:113], v[158:161]
	v_mfma_f32_16x16x32_bf16 v[166:169], v[14:17], v[118:121], v[166:169]
	v_mfma_f32_16x16x32_bf16 v[10:13], v[18:21], v[62:65], 0
	v_mfma_f32_16x16x32_bf16 v[14:17], v[26:29], v[62:65], 0
	v_mfma_f32_16x16x32_bf16 v[10:13], v[22:25], v[102:105], v[10:13]
	v_mfma_f32_16x16x32_bf16 v[14:17], v[30:33], v[102:105], v[14:17]
	v_mfma_f32_16x16x32_bf16 v[62:65], v[18:21], v[106:109], 0
	v_mfma_f32_16x16x32_bf16 v[102:105], v[26:29], v[106:109], 0
	v_mfma_f32_16x16x32_bf16 v[106:109], v[18:21], v[114:117], 0
	v_mfma_f32_16x16x32_bf16 v[18:21], v[18:21], v[122:125], 0
	v_mfma_f32_16x16x32_bf16 v[62:65], v[22:25], v[110:113], v[62:65]
	v_mfma_f32_16x16x32_bf16 v[102:105], v[30:33], v[110:113], v[102:105]
	v_mfma_f32_16x16x32_bf16 v[106:109], v[22:25], v[118:121], v[106:109]
	v_mfma_f32_16x16x32_bf16 v[110:113], v[26:29], v[114:117], 0
	v_mfma_f32_16x16x32_bf16 v[18:21], v[22:25], v[126:129], v[18:21]
	v_mfma_f32_16x16x32_bf16 v[22:25], v[26:29], v[122:125], 0
	v_mfma_f32_16x16x32_bf16 v[110:113], v[30:33], v[118:121], v[110:113]
	v_mfma_f32_16x16x32_bf16 v[22:25], v[30:33], v[126:129], v[22:25]
	s_setprio 0
	s_barrier
	s_add_i32 s69, 0, 0x18000
	s_add_i32 s36, 0, 0x1c000
	v_add_u32_e32 v174, s69, v179
	v_add_u32_e32 v175, s36, v179
	ds_read_b128 v[26:29], v174
	ds_read_b128 v[30:33], v174 offset:1024
	ds_read_b128 v[114:117], v174 offset:2048
	ds_read_b128 v[118:121], v174 offset:3072
	ds_read_b128 v[122:125], v175
	ds_read_b128 v[126:129], v175 offset:1024
	ds_read_b128 v[182:185], v175 offset:2048
	ds_read_b128 v[186:189], v175 offset:3072
	s_mov_b64 s[22:23], 0x100100
	s_mov_b32 m0, s43
	v_lshl_add_u64 v[150:151], v[0:1], 0, s[22:23]
	s_mov_b64 s[22:23], 0x180100
	ds_read_b128 v[190:193], v181 offset:32768
	ds_read_b128 v[194:197], v181 offset:33792
	ds_read_b128 v[204:207], v181 offset:34816
	ds_read_b128 v[208:211], v181 offset:35840
	ds_read_b128 v[212:215], v181 offset:36864
	ds_read_b128 v[216:219], v181 offset:37888
	ds_read_b128 v[220:223], v181 offset:38912
	ds_read_b128 v[224:227], v181 offset:39936
	global_load_lds_dwordx4 v[150:151], off
	v_lshl_add_u64 v[150:151], v[0:1], 0, s[22:23]
	s_mov_b32 m0, s96
	s_nop 0
	global_load_lds_dwordx4 v[150:151], off
	s_waitcnt vmcnt(8)
	s_waitcnt lgkmcnt(0)
	s_barrier
	s_setprio 1
	s_waitcnt lgkmcnt(0)
	v_mfma_f32_16x16x32_bf16 v[66:69], v[26:29], v[190:193], v[66:69]
	v_mfma_f32_16x16x32_bf16 v[70:73], v[114:117], v[190:193], v[70:73]
	v_mfma_f32_16x16x32_bf16 v[74:77], v[26:29], v[204:207], v[74:77]
	v_mfma_f32_16x16x32_bf16 v[78:81], v[114:117], v[204:207], v[78:81]
	v_mfma_f32_16x16x32_bf16 v[82:85], v[26:29], v[212:215], v[82:85]
	v_mfma_f32_16x16x32_bf16 v[86:89], v[114:117], v[212:215], v[86:89]
	v_mfma_f32_16x16x32_bf16 v[90:93], v[26:29], v[220:223], v[90:93]
	v_mfma_f32_16x16x32_bf16 v[94:97], v[114:117], v[220:223], v[94:97]
	v_mfma_f32_16x16x32_bf16 v[66:69], v[30:33], v[194:197], v[66:69]
	v_mfma_f32_16x16x32_bf16 v[70:73], v[118:121], v[194:197], v[70:73]
	v_mfma_f32_16x16x32_bf16 v[74:77], v[30:33], v[208:211], v[74:77]
	v_mfma_f32_16x16x32_bf16 v[78:81], v[118:121], v[208:211], v[78:81]
	v_mfma_f32_16x16x32_bf16 v[82:85], v[30:33], v[216:219], v[82:85]
	v_mfma_f32_16x16x32_bf16 v[86:89], v[118:121], v[216:219], v[86:89]
	v_mfma_f32_16x16x32_bf16 v[90:93], v[30:33], v[224:227], v[90:93]
	v_mfma_f32_16x16x32_bf16 v[94:97], v[118:121], v[224:227], v[94:97]
	v_mfma_f32_16x16x32_bf16 v[98:101], v[122:125], v[190:193], v[98:101]
	v_mfma_f32_16x16x32_bf16 v[34:37], v[182:185], v[190:193], v[34:37]
	v_mfma_f32_16x16x32_bf16 v[38:41], v[122:125], v[204:207], v[38:41]
	v_mfma_f32_16x16x32_bf16 v[42:45], v[182:185], v[204:207], v[42:45]
	v_mfma_f32_16x16x32_bf16 v[46:49], v[122:125], v[212:215], v[46:49]
	v_mfma_f32_16x16x32_bf16 v[50:53], v[182:185], v[212:215], v[50:53]
	v_mfma_f32_16x16x32_bf16 v[54:57], v[122:125], v[220:223], v[54:57]
	v_mfma_f32_16x16x32_bf16 v[58:61], v[182:185], v[220:223], v[58:61]
	v_mfma_f32_16x16x32_bf16 v[98:101], v[126:129], v[194:197], v[98:101]
	v_mfma_f32_16x16x32_bf16 v[34:37], v[186:189], v[194:197], v[34:37]
	v_mfma_f32_16x16x32_bf16 v[38:41], v[126:129], v[208:211], v[38:41]
	v_mfma_f32_16x16x32_bf16 v[42:45], v[186:189], v[208:211], v[42:45]
	v_mfma_f32_16x16x32_bf16 v[46:49], v[126:129], v[216:219], v[46:49]
	v_mfma_f32_16x16x32_bf16 v[50:53], v[186:189], v[216:219], v[50:53]
	v_mfma_f32_16x16x32_bf16 v[54:57], v[126:129], v[224:227], v[54:57]
	v_mfma_f32_16x16x32_bf16 v[58:61], v[186:189], v[224:227], v[58:61]
	s_setprio 0
	s_barrier
	s_mov_b64 s[30:31], 0x180
	s_add_i32 s69, s69, s39
	v_lshl_add_u64 v[150:151], v[142:143], 0, s[30:31]
	s_mov_b32 m0, s69
	s_mov_b64 s[22:23], 0x8180
	ds_read_b128 v[190:193], v181 offset:49152
	ds_read_b128 v[194:197], v181 offset:50176
	ds_read_b128 v[204:207], v181 offset:51200
	ds_read_b128 v[208:211], v181 offset:52224
	ds_read_b128 v[212:215], v181 offset:53248
	ds_read_b128 v[216:219], v181 offset:54272
	ds_read_b128 v[220:223], v181 offset:55296
	ds_read_b128 v[224:227], v181 offset:56320
	global_load_lds_dwordx4 v[150:151], off
	v_lshl_add_u64 v[150:151], v[142:143], 0, s[22:23]
	s_add_i32 s22, s69, 0x2000
	s_mov_b32 m0, s22
	s_mov_b64 s[44:45], 0x10180
	s_add_i32 s23, s36, s39
	global_load_lds_dwordx4 v[150:151], off
	v_lshl_add_u64 v[150:151], v[142:143], 0, s[44:45]
	s_mov_b32 m0, s23
	s_mov_b64 s[44:45], 0x18180
	s_add_i32 s68, s23, 0x2000
	global_load_lds_dwordx4 v[150:151], off
	v_lshl_add_u64 v[142:143], v[142:143], 0, s[44:45]
	s_mov_b32 m0, s68
	s_mov_b64 s[44:45], 0x80180
	global_load_lds_dwordx4 v[142:143], off
	v_lshl_add_u64 v[142:143], v[0:1], 0, s[30:31]
	s_mov_b32 m0, s40
	s_nop 0
	global_load_lds_dwordx4 v[142:143], off
	v_lshl_add_u64 v[142:143], v[0:1], 0, s[44:45]
	s_mov_b32 m0, s16
	s_nop 0
	global_load_lds_dwordx4 v[142:143], off
	s_waitcnt vmcnt(8)
	s_waitcnt lgkmcnt(0)
	s_barrier
	s_setprio 1
	s_waitcnt lgkmcnt(0)
	v_mfma_f32_16x16x32_bf16 v[130:133], v[26:29], v[190:193], v[130:133]
	v_mfma_f32_16x16x32_bf16 v[134:137], v[114:117], v[190:193], v[134:137]
	v_mfma_f32_16x16x32_bf16 v[138:141], v[26:29], v[204:207], v[138:141]
	v_mfma_f32_16x16x32_bf16 v[2:5], v[26:29], v[220:223], v[2:5]
	v_mfma_f32_16x16x32_bf16 v[6:9], v[114:117], v[220:223], v[6:9]
	v_mfma_f32_16x16x32_bf16 v[130:133], v[30:33], v[194:197], v[130:133]
	v_mfma_f32_16x16x32_bf16 v[134:137], v[118:121], v[194:197], v[134:137]
	v_mfma_f32_16x16x32_bf16 v[138:141], v[30:33], v[208:211], v[138:141]
	v_mfma_f32_16x16x32_bf16 v[158:161], v[114:117], v[204:207], v[158:161]
	v_mfma_f32_16x16x32_bf16 v[162:165], v[26:29], v[212:215], v[162:165]
	v_mfma_f32_16x16x32_bf16 v[166:169], v[114:117], v[212:215], v[166:169]
	v_mfma_f32_16x16x32_bf16 v[2:5], v[30:33], v[224:227], v[2:5]
	v_mfma_f32_16x16x32_bf16 v[6:9], v[118:121], v[224:227], v[6:9]
	v_mfma_f32_16x16x32_bf16 v[158:161], v[118:121], v[208:211], v[158:161]
	v_mfma_f32_16x16x32_bf16 v[162:165], v[30:33], v[216:219], v[162:165]
	v_mfma_f32_16x16x32_bf16 v[166:169], v[118:121], v[216:219], v[166:169]
	v_mfma_f32_16x16x32_bf16 v[10:13], v[122:125], v[190:193], v[10:13]
	v_mfma_f32_16x16x32_bf16 v[14:17], v[182:185], v[190:193], v[14:17]
	v_mfma_f32_16x16x32_bf16 v[26:29], v[122:125], v[204:207], v[62:65]
	v_mfma_f32_16x16x32_bf16 v[30:33], v[182:185], v[204:207], v[102:105]
	v_mfma_f32_16x16x32_bf16 v[62:65], v[122:125], v[212:215], v[106:109]
	v_mfma_f32_16x16x32_bf16 v[102:105], v[182:185], v[212:215], v[110:113]
	v_mfma_f32_16x16x32_bf16 v[18:21], v[122:125], v[220:223], v[18:21]
	v_mfma_f32_16x16x32_bf16 v[22:25], v[182:185], v[220:223], v[22:25]
	v_mfma_f32_16x16x32_bf16 v[10:13], v[126:129], v[194:197], v[10:13]
	v_mfma_f32_16x16x32_bf16 v[14:17], v[186:189], v[194:197], v[14:17]
	v_mfma_f32_16x16x32_bf16 v[26:29], v[126:129], v[208:211], v[26:29]
	v_mfma_f32_16x16x32_bf16 v[30:33], v[186:189], v[208:211], v[30:33]
	v_mfma_f32_16x16x32_bf16 v[62:65], v[126:129], v[216:219], v[62:65]
	v_mfma_f32_16x16x32_bf16 v[102:105], v[186:189], v[216:219], v[102:105]
	v_mfma_f32_16x16x32_bf16 v[18:21], v[126:129], v[224:227], v[18:21]
	v_mfma_f32_16x16x32_bf16 v[22:25], v[186:189], v[224:227], v[22:25]
	s_setprio 0
	s_barrier
	ds_read_b128 v[106:109], v152
	ds_read_b128 v[110:113], v152 offset:1024
	ds_read_b128 v[114:117], v152 offset:2048
	ds_read_b128 v[118:121], v152 offset:3072
	ds_read_b128 v[122:125], v153
	ds_read_b128 v[126:129], v153 offset:1024
	ds_read_b128 v[182:185], v153 offset:2048
	ds_read_b128 v[186:189], v153 offset:3072
	s_mov_b64 s[44:45], 0x100180
	s_mov_b32 m0, s20
	v_lshl_add_u64 v[142:143], v[0:1], 0, s[44:45]
	s_mov_b64 s[44:45], 0x180180
	ds_read_b128 v[190:193], v181
	ds_read_b128 v[194:197], v181 offset:1024
	ds_read_b128 v[204:207], v181 offset:2048
	ds_read_b128 v[208:211], v181 offset:3072
	ds_read_b128 v[212:215], v181 offset:4096
	ds_read_b128 v[216:219], v181 offset:5120
	ds_read_b128 v[220:223], v181 offset:6144
	ds_read_b128 v[224:227], v181 offset:7168
	global_load_lds_dwordx4 v[142:143], off
	v_lshl_add_u64 v[0:1], v[0:1], 0, s[44:45]
	s_mov_b32 m0, s6
	s_nop 0
	global_load_lds_dwordx4 v[0:1], off
	s_waitcnt vmcnt(8)
	s_waitcnt lgkmcnt(0)
	s_barrier
	s_setprio 1
	s_waitcnt lgkmcnt(0)
	v_mfma_f32_16x16x32_bf16 v[90:93], v[106:109], v[220:223], v[90:93]
	v_mfma_f32_16x16x32_bf16 v[66:69], v[106:109], v[190:193], v[66:69]
	v_mfma_f32_16x16x32_bf16 v[70:73], v[114:117], v[190:193], v[70:73]
	v_mfma_f32_16x16x32_bf16 v[74:77], v[106:109], v[204:207], v[74:77]
	v_mfma_f32_16x16x32_bf16 v[78:81], v[114:117], v[204:207], v[78:81]
	v_mfma_f32_16x16x32_bf16 v[82:85], v[106:109], v[212:215], v[82:85]
	v_mfma_f32_16x16x32_bf16 v[86:89], v[114:117], v[212:215], v[86:89]
	v_mfma_f32_16x16x32_bf16 v[228:231], v[110:113], v[224:227], v[90:93]
	v_mfma_f32_16x16x32_bf16 v[90:93], v[114:117], v[220:223], v[94:97]
	v_mfma_f32_16x16x32_bf16 v[66:69], v[110:113], v[194:197], v[66:69]
	v_mfma_f32_16x16x32_bf16 v[70:73], v[118:121], v[194:197], v[70:73]
	v_mfma_f32_16x16x32_bf16 v[74:77], v[110:113], v[208:211], v[74:77]
	v_mfma_f32_16x16x32_bf16 v[78:81], v[118:121], v[208:211], v[78:81]
	v_mfma_f32_16x16x32_bf16 v[82:85], v[110:113], v[216:219], v[82:85]
	v_mfma_f32_16x16x32_bf16 v[86:89], v[118:121], v[216:219], v[86:89]
	v_mfma_f32_16x16x32_bf16 v[92:95], v[118:121], v[224:227], v[90:93]
	v_mfma_f32_16x16x32_bf16 v[34:37], v[182:185], v[190:193], v[34:37]
	v_mfma_f32_16x16x32_bf16 v[38:41], v[122:125], v[204:207], v[38:41]
	v_mfma_f32_16x16x32_bf16 v[42:45], v[182:185], v[204:207], v[42:45]
	v_mfma_f32_16x16x32_bf16 v[46:49], v[122:125], v[212:215], v[46:49]
	v_mfma_f32_16x16x32_bf16 v[50:53], v[182:185], v[212:215], v[50:53]
	v_mfma_f32_16x16x32_bf16 v[54:57], v[122:125], v[220:223], v[54:57]
	v_mfma_f32_16x16x32_bf16 v[58:61], v[182:185], v[220:223], v[58:61]
	v_mfma_f32_16x16x32_bf16 v[96:99], v[122:125], v[190:193], v[98:101]
	v_mfma_f32_16x16x32_bf16 v[34:37], v[186:189], v[194:197], v[34:37]
	v_mfma_f32_16x16x32_bf16 v[38:41], v[126:129], v[208:211], v[38:41]
	v_mfma_f32_16x16x32_bf16 v[42:45], v[186:189], v[208:211], v[42:45]
	v_mfma_f32_16x16x32_bf16 v[46:49], v[126:129], v[216:219], v[46:49]
	v_mfma_f32_16x16x32_bf16 v[50:53], v[186:189], v[216:219], v[50:53]
	v_mfma_f32_16x16x32_bf16 v[54:57], v[126:129], v[224:227], v[54:57]
	v_mfma_f32_16x16x32_bf16 v[58:61], v[186:189], v[224:227], v[58:61]
	v_mfma_f32_16x16x32_bf16 v[232:235], v[126:129], v[194:197], v[96:99]
	s_setprio 0
	s_barrier
	s_mov_b32 m0, s21
	v_lshl_add_u64 v[198:199], s[76:77], 0, v[144:145]
	s_mov_b64 s[20:21], 0x8000
	ds_read_b128 v[96:99], v181 offset:16384
	ds_read_b128 v[190:193], v181 offset:17408
	ds_read_b128 v[194:197], v181 offset:18432
	ds_read_b128 v[204:207], v181 offset:19456
	ds_read_b128 v[208:211], v181 offset:20480
	ds_read_b128 v[212:215], v181 offset:21504
	ds_read_b128 v[216:219], v181 offset:22528
	ds_read_b128 v[220:223], v181 offset:23552
	global_load_lds_dwordx4 v[198:199], off
	v_lshl_add_u64 v[0:1], v[198:199], 0, s[20:21]
	s_mov_b32 m0, s7
	s_mov_b64 s[6:7], 0x10000
	global_load_lds_dwordx4 v[0:1], off
	v_lshl_add_u64 v[0:1], v[198:199], 0, s[6:7]
	s_mov_b32 m0, s18
	s_mov_b64 s[6:7], 0x18000
	global_load_lds_dwordx4 v[0:1], off
	v_lshl_add_u64 v[0:1], v[198:199], 0, s[6:7]
	s_mov_b32 m0, s19
	v_lshl_add_u64 v[154:155], vcc, 0, v[156:157]
	global_load_lds_dwordx4 v[0:1], off
	s_mov_b32 m0, s79
	v_lshl_add_u64 v[0:1], v[154:155], 0, s[56:57]
	global_load_lds_dwordx4 v[154:155], off
	s_mov_b32 m0, s42
	s_nop 0
	global_load_lds_dwordx4 v[0:1], off
	s_waitcnt vmcnt(8)
	s_waitcnt lgkmcnt(0)
	s_barrier
	s_setprio 1
	s_waitcnt lgkmcnt(0)
	v_mfma_f32_16x16x32_bf16 v[130:133], v[106:109], v[96:99], v[130:133]
	v_mfma_f32_16x16x32_bf16 v[224:227], v[110:113], v[190:193], v[130:133]
	v_mfma_f32_16x16x32_bf16 v[130:133], v[114:117], v[96:99], v[134:137]
	v_mfma_f32_16x16x32_bf16 v[136:139], v[106:109], v[194:197], v[138:141]
	v_mfma_f32_16x16x32_bf16 v[236:239], v[110:113], v[204:207], v[136:139]
	v_mfma_f32_16x16x32_bf16 v[136:139], v[114:117], v[194:197], v[158:161]
	v_mfma_f32_16x16x32_bf16 v[158:161], v[118:121], v[204:207], v[136:139]
	v_mfma_f32_16x16x32_bf16 v[136:139], v[106:109], v[208:211], v[162:165]
	v_mfma_f32_16x16x32_bf16 v[0:3], v[106:109], v[216:219], v[2:5]
	v_mfma_f32_16x16x32_bf16 v[4:7], v[114:117], v[216:219], v[6:9]
	v_mfma_f32_16x16x32_bf16 v[162:165], v[110:113], v[212:215], v[136:139]
	v_mfma_f32_16x16x32_bf16 v[136:139], v[114:117], v[208:211], v[166:169]
	v_mfma_f32_16x16x32_bf16 v[0:3], v[110:113], v[220:223], v[0:3]
	v_mfma_f32_16x16x32_bf16 v[4:7], v[118:121], v[220:223], v[4:7]
	v_mfma_f32_16x16x32_bf16 v[132:135], v[118:121], v[190:193], v[130:133]
	v_mfma_f32_16x16x32_bf16 v[166:169], v[118:121], v[212:215], v[136:139]
	v_mfma_f32_16x16x32_bf16 v[8:11], v[122:125], v[96:99], v[10:13]
	v_mfma_f32_16x16x32_bf16 v[12:15], v[182:185], v[96:99], v[14:17]
	v_mfma_f32_16x16x32_bf16 v[112:115], v[186:189], v[190:193], v[12:15]
	v_mfma_f32_16x16x32_bf16 v[12:15], v[122:125], v[194:197], v[26:29]
	v_mfma_f32_16x16x32_bf16 v[8:11], v[126:129], v[190:193], v[8:11]
	v_mfma_f32_16x16x32_bf16 v[190:193], v[126:129], v[204:207], v[12:15]
	v_mfma_f32_16x16x32_bf16 v[12:15], v[182:185], v[194:197], v[30:33]
	v_mfma_f32_16x16x32_bf16 v[28:31], v[186:189], v[204:207], v[12:15]
	v_mfma_f32_16x16x32_bf16 v[12:15], v[122:125], v[208:211], v[62:65]
	v_mfma_f32_16x16x32_bf16 v[194:197], v[126:129], v[212:215], v[12:15]
	v_mfma_f32_16x16x32_bf16 v[12:15], v[182:185], v[208:211], v[102:105]
	v_mfma_f32_16x16x32_bf16 v[204:207], v[186:189], v[212:215], v[12:15]
	v_mfma_f32_16x16x32_bf16 v[12:15], v[122:125], v[216:219], v[18:21]
	v_mfma_f32_16x16x32_bf16 v[16:19], v[126:129], v[220:223], v[12:15]
	v_mfma_f32_16x16x32_bf16 v[12:15], v[182:185], v[216:219], v[22:25]
	v_mfma_f32_16x16x32_bf16 v[20:23], v[186:189], v[220:223], v[12:15]
	s_setprio 0
	s_barrier
	s_nop 4
	ds_read_b128 v[12:15], v174
	ds_read_b128 v[182:185], v174 offset:1024
	ds_read_b128 v[186:189], v174 offset:2048
	ds_read_b128 v[208:211], v174 offset:3072
	ds_read_b128 v[212:215], v175
	ds_read_b128 v[216:219], v175 offset:1024
	ds_read_b128 v[220:223], v175 offset:2048
	ds_read_b128 v[240:243], v175 offset:3072
	s_mov_b32 m0, s43
	v_lshl_add_u64 v[32:33], v[154:155], 0, s[54:55]
	ds_read_b128 v[24:27], v181 offset:32768
	ds_read_b128 v[62:65], v181 offset:33792
	ds_read_b128 v[100:103], v181 offset:34816
	ds_read_b128 v[108:111], v181 offset:35840
	ds_read_b128 v[244:247], v181 offset:36864
	ds_read_b128 v[248:251], v181 offset:37888
	ds_read_b128 v[174:177], v181 offset:38912
	ds_read_b128 v[150:153], v181 offset:39936
	global_load_lds_dwordx4 v[32:33], off
	v_lshl_add_u64 v[32:33], v[154:155], 0, s[58:59]
	s_mov_b32 m0, s96
	s_nop 0
	global_load_lds_dwordx4 v[32:33], off
	s_waitcnt vmcnt(8)
	s_waitcnt lgkmcnt(0)
	s_barrier
	s_setprio 1
	s_waitcnt lgkmcnt(0)
	v_mfma_f32_16x16x32_bf16 v[66:69], v[12:15], v[24:27], v[66:69]
	v_mfma_f32_16x16x32_bf16 v[136:139], v[182:185], v[62:65], v[66:69]
	v_mfma_f32_16x16x32_bf16 v[66:69], v[186:189], v[24:27], v[70:73]
	v_mfma_f32_16x16x32_bf16 v[124:127], v[208:211], v[62:65], v[66:69]
	v_mfma_f32_16x16x32_bf16 v[66:69], v[12:15], v[100:103], v[74:77]
	v_mfma_f32_16x16x32_bf16 v[116:119], v[182:185], v[108:111], v[66:69]
	v_mfma_f32_16x16x32_bf16 v[66:69], v[186:189], v[100:103], v[78:81]
	v_mfma_f32_16x16x32_bf16 v[104:107], v[208:211], v[108:111], v[66:69]
	v_mfma_f32_16x16x32_bf16 v[66:69], v[12:15], v[244:247], v[82:85]
	v_mfma_f32_16x16x32_bf16 v[96:99], v[182:185], v[248:251], v[66:69]
	v_mfma_f32_16x16x32_bf16 v[66:69], v[186:189], v[244:247], v[86:89]
	v_mfma_f32_16x16x32_bf16 v[88:91], v[208:211], v[248:251], v[66:69]
	v_mfma_f32_16x16x32_bf16 v[66:69], v[12:15], v[174:177], v[228:231]
	v_mfma_f32_16x16x32_bf16 v[80:83], v[182:185], v[150:153], v[66:69]
	v_mfma_f32_16x16x32_bf16 v[66:69], v[186:189], v[174:177], v[92:95]
	v_mfma_f32_16x16x32_bf16 v[72:75], v[208:211], v[150:153], v[66:69]
	v_mfma_f32_16x16x32_bf16 v[66:69], v[212:215], v[24:27], v[232:235]
	v_mfma_f32_16x16x32_bf16 v[24:27], v[220:223], v[24:27], v[34:37]
	v_mfma_f32_16x16x32_bf16 v[128:131], v[240:243], v[62:65], v[24:27]
	v_mfma_f32_16x16x32_bf16 v[24:27], v[212:215], v[100:103], v[38:41]
	v_mfma_f32_16x16x32_bf16 v[120:123], v[216:219], v[108:111], v[24:27]
	v_mfma_f32_16x16x32_bf16 v[24:27], v[220:223], v[100:103], v[42:45]
	v_mfma_f32_16x16x32_bf16 v[108:111], v[240:243], v[108:111], v[24:27]
	v_mfma_f32_16x16x32_bf16 v[24:27], v[212:215], v[244:247], v[46:49]
	v_mfma_f32_16x16x32_bf16 v[100:103], v[216:219], v[248:251], v[24:27]
	v_mfma_f32_16x16x32_bf16 v[24:27], v[220:223], v[244:247], v[50:53]
	v_mfma_f32_16x16x32_bf16 v[92:95], v[240:243], v[248:251], v[24:27]
	v_mfma_f32_16x16x32_bf16 v[24:27], v[212:215], v[174:177], v[54:57]
	v_mfma_f32_16x16x32_bf16 v[84:87], v[216:219], v[150:153], v[24:27]
	v_mfma_f32_16x16x32_bf16 v[24:27], v[220:223], v[174:177], v[58:61]
	v_mfma_f32_16x16x32_bf16 v[140:143], v[216:219], v[62:65], v[66:69]
	v_mfma_f32_16x16x32_bf16 v[76:79], v[240:243], v[150:153], v[24:27]
	s_setprio 0
	s_barrier
	s_mov_b32 m0, s69
	s_nop 2
	v_lshl_add_u64 v[24:25], v[198:199], 0, s[60:61]
	s_mov_b64 s[6:7], 0x8080
	ds_read_b128 v[36:39], v181 offset:49152
	ds_read_b128 v[44:47], v181 offset:50176
	ds_read_b128 v[150:153], v181 offset:51200
	ds_read_b128 v[174:177], v181 offset:52224
	ds_read_b128 v[228:231], v181 offset:53248
	ds_read_b128 v[232:235], v181 offset:54272
	ds_read_b128 v[244:247], v181 offset:55296
	ds_read_b128 v[248:251], v181 offset:56320
	global_load_lds_dwordx4 v[24:25], off
	v_lshl_add_u64 v[24:25], v[198:199], 0, s[6:7]
	s_mov_b32 m0, s22
	s_mov_b64 s[6:7], 0x10080
	global_load_lds_dwordx4 v[24:25], off
	v_lshl_add_u64 v[24:25], v[198:199], 0, s[6:7]
	s_mov_b32 m0, s23
	s_mov_b64 s[6:7], 0x18080
	global_load_lds_dwordx4 v[24:25], off
	v_lshl_add_u64 v[24:25], v[198:199], 0, s[6:7]
	s_mov_b32 m0, s68
	s_nop 0
	global_load_lds_dwordx4 v[24:25], off
	v_lshl_add_u64 v[24:25], v[154:155], 0, s[60:61]
	s_mov_b32 m0, s40
	s_nop 0
	global_load_lds_dwordx4 v[24:25], off
	v_lshl_add_u64 v[24:25], v[154:155], 0, s[62:63]
	s_mov_b32 m0, s16
	s_nop 0
	global_load_lds_dwordx4 v[24:25], off
	s_waitcnt vmcnt(8)
	s_waitcnt lgkmcnt(0)
	s_barrier
	s_setprio 1
	s_waitcnt lgkmcnt(0)
	v_mfma_f32_16x16x32_bf16 v[24:27], v[12:15], v[36:39], v[224:227]
	v_mfma_f32_16x16x32_bf16 v[64:67], v[182:185], v[44:47], v[24:27]
	v_mfma_f32_16x16x32_bf16 v[24:27], v[186:189], v[36:39], v[132:135]
	v_mfma_f32_16x16x32_bf16 v[56:59], v[208:211], v[44:47], v[24:27]
	v_mfma_f32_16x16x32_bf16 v[24:27], v[12:15], v[150:153], v[236:239]
	v_mfma_f32_16x16x32_bf16 v[48:51], v[182:185], v[174:177], v[24:27]
	v_mfma_f32_16x16x32_bf16 v[24:27], v[186:189], v[150:153], v[158:161]
	v_mfma_f32_16x16x32_bf16 v[40:43], v[208:211], v[174:177], v[24:27]
	v_mfma_f32_16x16x32_bf16 v[24:27], v[12:15], v[228:231], v[162:165]
	v_mfma_f32_16x16x32_bf16 v[0:3], v[12:15], v[244:247], v[0:3]
	v_mfma_f32_16x16x32_bf16 v[32:35], v[182:185], v[232:235], v[24:27]
	v_mfma_f32_16x16x32_bf16 v[24:27], v[186:189], v[228:231], v[166:169]
	v_mfma_f32_16x16x32_bf16 v[12:15], v[182:185], v[248:251], v[0:3]
	v_mfma_f32_16x16x32_bf16 v[0:3], v[186:189], v[244:247], v[4:7]
	v_mfma_f32_16x16x32_bf16 v[24:27], v[208:211], v[232:235], v[24:27]
	v_mfma_f32_16x16x32_bf16 v[0:3], v[208:211], v[248:251], v[0:3]
	v_mfma_f32_16x16x32_bf16 v[4:7], v[212:215], v[36:39], v[8:11]
	v_mfma_f32_16x16x32_bf16 v[68:71], v[216:219], v[44:47], v[4:7]
	v_mfma_f32_16x16x32_bf16 v[4:7], v[220:223], v[36:39], v[112:115]
	v_mfma_f32_16x16x32_bf16 v[60:63], v[240:243], v[44:47], v[4:7]
	v_mfma_f32_16x16x32_bf16 v[4:7], v[212:215], v[150:153], v[190:193]
	v_mfma_f32_16x16x32_bf16 v[52:55], v[216:219], v[174:177], v[4:7]
	v_mfma_f32_16x16x32_bf16 v[4:7], v[220:223], v[150:153], v[28:31]
	v_mfma_f32_16x16x32_bf16 v[44:47], v[240:243], v[174:177], v[4:7]
	v_mfma_f32_16x16x32_bf16 v[4:7], v[212:215], v[228:231], v[194:197]
	v_mfma_f32_16x16x32_bf16 v[36:39], v[216:219], v[232:235], v[4:7]
	v_mfma_f32_16x16x32_bf16 v[4:7], v[220:223], v[228:231], v[204:207]
	v_mfma_f32_16x16x32_bf16 v[28:31], v[240:243], v[232:235], v[4:7]
	v_mfma_f32_16x16x32_bf16 v[4:7], v[212:215], v[244:247], v[16:19]
	v_mfma_f32_16x16x32_bf16 v[16:19], v[216:219], v[248:251], v[4:7]
	v_mfma_f32_16x16x32_bf16 v[4:7], v[220:223], v[244:247], v[20:23]
	v_mfma_f32_16x16x32_bf16 v[4:7], v[240:243], v[248:251], v[4:7]
	s_setprio 0
	s_barrier
	s_andn2_b64 vcc, exec, s[88:89]
	s_cbranch_vccnz .LBB0_488
	s_barrier

.LBB0_836:
	s_add_u32 s36, s70, 0xfff00080
	s_addc_u32 s44, s71, -1
	s_add_i32 s45, 0, 0x10000
	s_cmp_eq_u32 s92, 60
	s_cselect_b32 s73, s37, s44
	s_cselect_b32 s72, s38, s36
	s_cselect_b32 s47, s69, s79
	s_cselect_b32 s46, s74, s75
	s_add_i32 s36, 0, 0x14000
	v_add_u32_e32 v150, s45, v160
	v_add_u32_e32 v154, s36, v160
	ds_read_b128 v[128:131], v150
	ds_read_b128 v[132:135], v150 offset:1024
	ds_read_b128 v[140:143], v150 offset:2048
	ds_read_b128 v[150:153], v150 offset:3072
	ds_read_b128 v[156:159], v154
	ds_read_b128 v[164:167], v154 offset:1024
	ds_read_b128 v[174:177], v154 offset:2048
	ds_read_b128 v[180:183], v154 offset:3072
	v_lshl_add_u64 v[154:155], s[70:71], 0, v[138:139]
	s_add_i32 m0, s20, 0xc000
	ds_read_b128 v[184:187], v162
	ds_read_b128 v[188:191], v162 offset:1024
	ds_read_b128 v[192:195], v162 offset:2048
	ds_read_b128 v[196:199], v162 offset:3072
	ds_read_b128 v[204:207], v162 offset:4096
	ds_read_b128 v[208:211], v162 offset:5120
	ds_read_b128 v[212:215], v162 offset:6144
	ds_read_b128 v[216:219], v162 offset:7168
	global_load_lds_dwordx4 v[154:155], off
	v_lshl_add_u64 v[154:155], v[154:155], 0, s[56:57]
	s_add_i32 m0, s20, 0xe000
	s_nop 0
	global_load_lds_dwordx4 v[154:155], off
	s_waitcnt vmcnt(8)
	s_waitcnt lgkmcnt(0)
	s_barrier
	s_setprio 1
	s_waitcnt lgkmcnt(0)
	v_mfma_f32_16x16x32_bf16 v[124:127], v[128:131], v[184:187], v[124:127]
	v_mfma_f32_16x16x32_bf16 v[120:123], v[140:143], v[184:187], v[120:123]
	v_mfma_f32_16x16x32_bf16 v[108:111], v[128:131], v[192:195], v[108:111]
	v_mfma_f32_16x16x32_bf16 v[104:107], v[140:143], v[192:195], v[104:107]
	v_mfma_f32_16x16x32_bf16 v[92:95], v[128:131], v[204:207], v[92:95]
	v_mfma_f32_16x16x32_bf16 v[88:91], v[140:143], v[204:207], v[88:91]
	v_mfma_f32_16x16x32_bf16 v[76:79], v[128:131], v[212:215], v[76:79]
	v_mfma_f32_16x16x32_bf16 v[72:75], v[140:143], v[212:215], v[72:75]
	v_mfma_f32_16x16x32_bf16 v[124:127], v[132:135], v[188:191], v[124:127]
	v_mfma_f32_16x16x32_bf16 v[120:123], v[150:153], v[188:191], v[120:123]
	v_mfma_f32_16x16x32_bf16 v[108:111], v[132:135], v[196:199], v[108:111]
	v_mfma_f32_16x16x32_bf16 v[104:107], v[150:153], v[196:199], v[104:107]
	v_mfma_f32_16x16x32_bf16 v[92:95], v[132:135], v[208:211], v[92:95]
	v_mfma_f32_16x16x32_bf16 v[88:91], v[150:153], v[208:211], v[88:91]
	v_mfma_f32_16x16x32_bf16 v[76:79], v[132:135], v[216:219], v[76:79]
	v_mfma_f32_16x16x32_bf16 v[72:75], v[150:153], v[216:219], v[72:75]
	v_mfma_f32_16x16x32_bf16 v[116:119], v[156:159], v[184:187], v[116:119]
	v_mfma_f32_16x16x32_bf16 v[112:115], v[174:177], v[184:187], v[112:115]
	v_mfma_f32_16x16x32_bf16 v[100:103], v[156:159], v[192:195], v[100:103]
	v_mfma_f32_16x16x32_bf16 v[96:99], v[174:177], v[192:195], v[96:99]
	v_mfma_f32_16x16x32_bf16 v[84:87], v[156:159], v[204:207], v[84:87]
	v_mfma_f32_16x16x32_bf16 v[80:83], v[174:177], v[204:207], v[80:83]
	v_mfma_f32_16x16x32_bf16 v[68:71], v[156:159], v[212:215], v[68:71]
	v_mfma_f32_16x16x32_bf16 v[64:67], v[174:177], v[212:215], v[64:67]
	v_mfma_f32_16x16x32_bf16 v[116:119], v[164:167], v[188:191], v[116:119]
	v_mfma_f32_16x16x32_bf16 v[112:115], v[180:183], v[188:191], v[112:115]
	v_mfma_f32_16x16x32_bf16 v[100:103], v[164:167], v[196:199], v[100:103]
	v_mfma_f32_16x16x32_bf16 v[96:99], v[180:183], v[196:199], v[96:99]
	v_mfma_f32_16x16x32_bf16 v[84:87], v[164:167], v[208:211], v[84:87]
	v_mfma_f32_16x16x32_bf16 v[80:83], v[180:183], v[208:211], v[80:83]
	v_mfma_f32_16x16x32_bf16 v[68:71], v[164:167], v[216:219], v[68:71]
	v_mfma_f32_16x16x32_bf16 v[64:67], v[180:183], v[216:219], v[64:67]
	s_setprio 0
	s_barrier
	s_add_i32 s44, s45, s17
	v_lshl_add_u64 v[154:155], s[46:47], 0, v[144:145]
	s_mov_b32 m0, s44
	ds_read_b128 v[184:187], v162 offset:16384
	ds_read_b128 v[188:191], v162 offset:17408
	ds_read_b128 v[192:195], v162 offset:18432
	ds_read_b128 v[196:199], v162 offset:19456
	ds_read_b128 v[204:207], v162 offset:20480
	ds_read_b128 v[208:211], v162 offset:21504
	ds_read_b128 v[212:215], v162 offset:22528
	ds_read_b128 v[216:219], v162 offset:23552
	global_load_lds_dwordx4 v[154:155], off
	v_lshl_add_u64 v[168:169], v[154:155], 0, s[56:57]
	s_add_i32 m0, s44, 0x2000
	s_add_i32 s36, s36, s17
	global_load_lds_dwordx4 v[168:169], off
	v_lshl_add_u64 v[168:169], v[154:155], 0, s[54:55]
	s_mov_b32 m0, s36
	s_nop 0
	global_load_lds_dwordx4 v[168:169], off
	v_lshl_add_u64 v[168:169], v[154:155], 0, s[58:59]
	s_add_i32 m0, s36, 0x2000
	s_nop 0
	global_load_lds_dwordx4 v[168:169], off
	v_lshl_add_u64 v[168:169], s[72:73], 0, v[136:137]
	s_mov_b32 m0, s20
	v_lshl_add_u64 v[220:221], v[168:169], 0, s[56:57]
	global_load_lds_dwordx4 v[168:169], off
	s_mov_b32 m0, s21
	s_nop 0
	global_load_lds_dwordx4 v[220:221], off
	s_waitcnt vmcnt(8)
	s_waitcnt lgkmcnt(0)
	s_barrier
	s_setprio 1
	s_waitcnt lgkmcnt(0)
	v_mfma_f32_16x16x32_bf16 v[60:63], v[128:131], v[184:187], v[60:63]
	v_mfma_f32_16x16x32_bf16 v[56:59], v[140:143], v[184:187], v[56:59]
	v_mfma_f32_16x16x32_bf16 v[44:47], v[128:131], v[192:195], v[44:47]
	v_mfma_f32_16x16x32_bf16 v[40:43], v[140:143], v[192:195], v[40:43]
	v_mfma_f32_16x16x32_bf16 v[28:31], v[128:131], v[204:207], v[28:31]
	v_mfma_f32_16x16x32_bf16 v[24:27], v[140:143], v[204:207], v[24:27]
	v_mfma_f32_16x16x32_bf16 v[12:15], v[128:131], v[212:215], v[12:15]
	v_mfma_f32_16x16x32_bf16 v[8:11], v[140:143], v[212:215], v[8:11]
	v_mfma_f32_16x16x32_bf16 v[60:63], v[132:135], v[188:191], v[60:63]
	v_mfma_f32_16x16x32_bf16 v[56:59], v[150:153], v[188:191], v[56:59]
	v_mfma_f32_16x16x32_bf16 v[44:47], v[132:135], v[196:199], v[44:47]
	v_mfma_f32_16x16x32_bf16 v[40:43], v[150:153], v[196:199], v[40:43]
	v_mfma_f32_16x16x32_bf16 v[28:31], v[132:135], v[208:211], v[28:31]
	v_mfma_f32_16x16x32_bf16 v[24:27], v[150:153], v[208:211], v[24:27]
	v_mfma_f32_16x16x32_bf16 v[12:15], v[132:135], v[216:219], v[12:15]
	v_mfma_f32_16x16x32_bf16 v[8:11], v[150:153], v[216:219], v[8:11]
	v_mfma_f32_16x16x32_bf16 v[52:55], v[156:159], v[184:187], v[52:55]
	v_mfma_f32_16x16x32_bf16 v[48:51], v[174:177], v[184:187], v[48:51]
	v_mfma_f32_16x16x32_bf16 v[36:39], v[156:159], v[192:195], v[36:39]
	v_mfma_f32_16x16x32_bf16 v[32:35], v[174:177], v[192:195], v[32:35]
	v_mfma_f32_16x16x32_bf16 v[20:23], v[156:159], v[204:207], v[20:23]
	v_mfma_f32_16x16x32_bf16 v[16:19], v[174:177], v[204:207], v[16:19]
	v_mfma_f32_16x16x32_bf16 v[4:7], v[156:159], v[212:215], v[4:7]
	v_mfma_f32_16x16x32_bf16 v[0:3], v[174:177], v[212:215], v[0:3]
	v_mfma_f32_16x16x32_bf16 v[52:55], v[164:167], v[188:191], v[52:55]
	v_mfma_f32_16x16x32_bf16 v[48:51], v[180:183], v[188:191], v[48:51]
	v_mfma_f32_16x16x32_bf16 v[36:39], v[164:167], v[196:199], v[36:39]
	v_mfma_f32_16x16x32_bf16 v[32:35], v[180:183], v[196:199], v[32:35]
	v_mfma_f32_16x16x32_bf16 v[20:23], v[164:167], v[208:211], v[20:23]
	v_mfma_f32_16x16x32_bf16 v[16:19], v[180:183], v[208:211], v[16:19]
	v_mfma_f32_16x16x32_bf16 v[4:7], v[164:167], v[216:219], v[4:7]
	v_mfma_f32_16x16x32_bf16 v[0:3], v[180:183], v[216:219], v[0:3]
	s_setprio 0
	s_barrier
	s_add_i32 s36, 0, 0x18000
	s_add_i32 s44, 0, 0x1c000
	v_add_u32_e32 v150, s36, v160
	v_add_u32_e32 v163, s44, v160
	ds_read_b128 v[128:131], v150
	ds_read_b128 v[132:135], v150 offset:1024
	ds_read_b128 v[140:143], v150 offset:2048
	ds_read_b128 v[150:153], v150 offset:3072
	ds_read_b128 v[156:159], v163
	ds_read_b128 v[164:167], v163 offset:1024
	ds_read_b128 v[174:177], v163 offset:2048
	ds_read_b128 v[180:183], v163 offset:3072
	s_mov_b32 m0, s22
	v_lshl_add_u64 v[220:221], v[168:169], 0, s[54:55]
	ds_read_b128 v[184:187], v162 offset:32768
	ds_read_b128 v[188:191], v162 offset:33792
	ds_read_b128 v[192:195], v162 offset:34816
	ds_read_b128 v[196:199], v162 offset:35840
	ds_read_b128 v[204:207], v162 offset:36864
	ds_read_b128 v[208:211], v162 offset:37888
	ds_read_b128 v[212:215], v162 offset:38912
	ds_read_b128 v[216:219], v162 offset:39936
	global_load_lds_dwordx4 v[220:221], off
	v_lshl_add_u64 v[220:221], v[168:169], 0, s[58:59]
	s_mov_b32 m0, s23
	s_nop 0
	global_load_lds_dwordx4 v[220:221], off
	s_waitcnt vmcnt(8)
	s_waitcnt lgkmcnt(0)
	s_barrier
	s_setprio 1
	s_waitcnt lgkmcnt(0)
	v_mfma_f32_16x16x32_bf16 v[124:127], v[128:131], v[184:187], v[124:127]
	v_mfma_f32_16x16x32_bf16 v[120:123], v[140:143], v[184:187], v[120:123]
	v_mfma_f32_16x16x32_bf16 v[108:111], v[128:131], v[192:195], v[108:111]
	v_mfma_f32_16x16x32_bf16 v[104:107], v[140:143], v[192:195], v[104:107]
	v_mfma_f32_16x16x32_bf16 v[92:95], v[128:131], v[204:207], v[92:95]
	v_mfma_f32_16x16x32_bf16 v[88:91], v[140:143], v[204:207], v[88:91]
	v_mfma_f32_16x16x32_bf16 v[76:79], v[128:131], v[212:215], v[76:79]
	v_mfma_f32_16x16x32_bf16 v[72:75], v[140:143], v[212:215], v[72:75]
	v_mfma_f32_16x16x32_bf16 v[124:127], v[132:135], v[188:191], v[124:127]
	v_mfma_f32_16x16x32_bf16 v[120:123], v[150:153], v[188:191], v[120:123]
	v_mfma_f32_16x16x32_bf16 v[108:111], v[132:135], v[196:199], v[108:111]
	v_mfma_f32_16x16x32_bf16 v[104:107], v[150:153], v[196:199], v[104:107]
	v_mfma_f32_16x16x32_bf16 v[92:95], v[132:135], v[208:211], v[92:95]
	v_mfma_f32_16x16x32_bf16 v[88:91], v[150:153], v[208:211], v[88:91]
	v_mfma_f32_16x16x32_bf16 v[76:79], v[132:135], v[216:219], v[76:79]
	v_mfma_f32_16x16x32_bf16 v[72:75], v[150:153], v[216:219], v[72:75]
	v_mfma_f32_16x16x32_bf16 v[116:119], v[156:159], v[184:187], v[116:119]
	v_mfma_f32_16x16x32_bf16 v[112:115], v[174:177], v[184:187], v[112:115]
	v_mfma_f32_16x16x32_bf16 v[100:103], v[156:159], v[192:195], v[100:103]
	v_mfma_f32_16x16x32_bf16 v[96:99], v[174:177], v[192:195], v[96:99]
	v_mfma_f32_16x16x32_bf16 v[84:87], v[156:159], v[204:207], v[84:87]
	v_mfma_f32_16x16x32_bf16 v[80:83], v[174:177], v[204:207], v[80:83]
	v_mfma_f32_16x16x32_bf16 v[68:71], v[156:159], v[212:215], v[68:71]
	v_mfma_f32_16x16x32_bf16 v[64:67], v[174:177], v[212:215], v[64:67]
	v_mfma_f32_16x16x32_bf16 v[116:119], v[164:167], v[188:191], v[116:119]
	v_mfma_f32_16x16x32_bf16 v[112:115], v[180:183], v[188:191], v[112:115]
	v_mfma_f32_16x16x32_bf16 v[100:103], v[164:167], v[196:199], v[100:103]
	v_mfma_f32_16x16x32_bf16 v[96:99], v[180:183], v[196:199], v[96:99]
	v_mfma_f32_16x16x32_bf16 v[84:87], v[164:167], v[208:211], v[84:87]
	v_mfma_f32_16x16x32_bf16 v[80:83], v[180:183], v[208:211], v[80:83]
	v_mfma_f32_16x16x32_bf16 v[68:71], v[164:167], v[216:219], v[68:71]
	v_mfma_f32_16x16x32_bf16 v[64:67], v[180:183], v[216:219], v[64:67]
	s_setprio 0
	s_barrier
	s_add_i32 s36, s36, s17
	v_lshl_add_u64 v[220:221], v[154:155], 0, s[60:61]
	s_mov_b32 m0, s36
	ds_read_b128 v[184:187], v162 offset:49152
	ds_read_b128 v[188:191], v162 offset:50176
	ds_read_b128 v[192:195], v162 offset:51200
	ds_read_b128 v[196:199], v162 offset:52224
	ds_read_b128 v[204:207], v162 offset:53248
	ds_read_b128 v[208:211], v162 offset:54272
	ds_read_b128 v[212:215], v162 offset:55296
	ds_read_b128 v[216:219], v162 offset:56320
	global_load_lds_dwordx4 v[220:221], off
	v_lshl_add_u64 v[220:221], v[154:155], 0, s[62:63]
	s_add_i32 m0, s36, 0x2000
	s_add_i32 s36, s44, s17
	global_load_lds_dwordx4 v[220:221], off
	v_lshl_add_u64 v[220:221], v[154:155], 0, s[64:65]
	s_mov_b32 m0, s36
	v_lshl_add_u64 v[154:155], v[154:155], 0, s[66:67]
	global_load_lds_dwordx4 v[220:221], off
	s_add_i32 m0, s36, 0x2000
	s_nop 0
	global_load_lds_dwordx4 v[154:155], off
	v_lshl_add_u64 v[154:155], v[168:169], 0, s[60:61]
	s_mov_b32 m0, s89
	s_nop 0
	global_load_lds_dwordx4 v[154:155], off
	v_lshl_add_u64 v[154:155], v[168:169], 0, s[62:63]
	s_mov_b32 m0, s90
	s_nop 0
	global_load_lds_dwordx4 v[154:155], off
	s_waitcnt vmcnt(8)
	s_waitcnt lgkmcnt(0)
	s_barrier
	s_setprio 1
	s_waitcnt lgkmcnt(0)
	v_mfma_f32_16x16x32_bf16 v[60:63], v[128:131], v[184:187], v[60:63]
	v_mfma_f32_16x16x32_bf16 v[56:59], v[140:143], v[184:187], v[56:59]
	v_mfma_f32_16x16x32_bf16 v[44:47], v[128:131], v[192:195], v[44:47]
	v_mfma_f32_16x16x32_bf16 v[40:43], v[140:143], v[192:195], v[40:43]
	v_mfma_f32_16x16x32_bf16 v[28:31], v[128:131], v[204:207], v[28:31]
	v_mfma_f32_16x16x32_bf16 v[24:27], v[140:143], v[204:207], v[24:27]
	v_mfma_f32_16x16x32_bf16 v[12:15], v[128:131], v[212:215], v[12:15]
	v_mfma_f32_16x16x32_bf16 v[8:11], v[140:143], v[212:215], v[8:11]
	v_mfma_f32_16x16x32_bf16 v[60:63], v[132:135], v[188:191], v[60:63]
	v_mfma_f32_16x16x32_bf16 v[56:59], v[150:153], v[188:191], v[56:59]
	v_mfma_f32_16x16x32_bf16 v[44:47], v[132:135], v[196:199], v[44:47]
	v_mfma_f32_16x16x32_bf16 v[40:43], v[150:153], v[196:199], v[40:43]
	v_mfma_f32_16x16x32_bf16 v[28:31], v[132:135], v[208:211], v[28:31]
	v_mfma_f32_16x16x32_bf16 v[24:27], v[150:153], v[208:211], v[24:27]
	v_mfma_f32_16x16x32_bf16 v[12:15], v[132:135], v[216:219], v[12:15]
	v_mfma_f32_16x16x32_bf16 v[8:11], v[150:153], v[216:219], v[8:11]
	v_mfma_f32_16x16x32_bf16 v[52:55], v[156:159], v[184:187], v[52:55]
	v_mfma_f32_16x16x32_bf16 v[48:51], v[174:177], v[184:187], v[48:51]
	v_mfma_f32_16x16x32_bf16 v[36:39], v[156:159], v[192:195], v[36:39]
	v_mfma_f32_16x16x32_bf16 v[32:35], v[174:177], v[192:195], v[32:35]
	v_mfma_f32_16x16x32_bf16 v[20:23], v[156:159], v[204:207], v[20:23]
	v_mfma_f32_16x16x32_bf16 v[16:19], v[174:177], v[204:207], v[16:19]
	v_mfma_f32_16x16x32_bf16 v[4:7], v[156:159], v[212:215], v[4:7]
	v_mfma_f32_16x16x32_bf16 v[0:3], v[174:177], v[212:215], v[0:3]
	v_mfma_f32_16x16x32_bf16 v[52:55], v[164:167], v[188:191], v[52:55]
	v_mfma_f32_16x16x32_bf16 v[48:51], v[180:183], v[188:191], v[48:51]
	v_mfma_f32_16x16x32_bf16 v[36:39], v[164:167], v[196:199], v[36:39]
	v_mfma_f32_16x16x32_bf16 v[32:35], v[180:183], v[196:199], v[32:35]
	v_mfma_f32_16x16x32_bf16 v[20:23], v[164:167], v[208:211], v[20:23]
	v_mfma_f32_16x16x32_bf16 v[16:19], v[180:183], v[208:211], v[16:19]
	v_mfma_f32_16x16x32_bf16 v[4:7], v[164:167], v[216:219], v[4:7]
	v_mfma_f32_16x16x32_bf16 v[0:3], v[180:183], v[216:219], v[0:3]
	s_setprio 0
	s_barrier
	s_add_i32 s92, s92, 2
	s_add_u32 s70, s70, 0x100
	s_addc_u32 s71, s71, 0
	s_add_u32 s75, s75, 0x100
	s_addc_u32 s79, s79, 0
	s_cmp_gt_u32 s92, 61
	s_cbranch_scc0 .LBB0_836
	s_and_b64 vcc, exec, s[52:53]
	s_cbranch_vccz .LBB0_839
	s_barrier

.LBB0_1157:
	ds_read_b128 v[146:149], v142
	ds_read_b128 v[150:153], v142 offset:1024
	ds_read_b128 v[154:157], v142 offset:2048
	ds_read_b128 v[158:161], v142 offset:3072
	ds_read_b128 v[162:165], v143
	ds_read_b128 v[166:169], v143 offset:1024
	ds_read_b128 v[170:173], v143 offset:2048
	ds_read_b128 v[174:177], v143 offset:3072
	s_add_u32 s64, s44, 0xfff00080
	s_addc_u32 s65, s45, -1
	s_cmp_eq_u32 s63, 60
	s_cselect_b32 s65, s29, s65
	s_cselect_b32 s64, s43, s64
	s_cselect_b32 s67, s27, s47
	s_cselect_b32 s66, s62, s46
	v_lshl_add_u64 v[210:211], s[44:45], 0, v[132:133]
	s_add_i32 m0, s48, 0xc000
	ds_read_b128 v[178:181], v144
	ds_read_b128 v[182:185], v144 offset:1024
	ds_read_b128 v[186:189], v144 offset:2048
	ds_read_b128 v[190:193], v144 offset:3072
	ds_read_b128 v[194:197], v144 offset:4096
	ds_read_b128 v[198:201], v144 offset:5120
	ds_read_b128 v[202:205], v144 offset:6144
	ds_read_b128 v[206:209], v144 offset:7168
	global_load_lds_dwordx4 v[210:211], off
	v_lshl_add_u64 v[210:211], v[210:211], 0, s[4:5]
	s_add_i32 m0, s48, 0xe000
	s_nop 0
	global_load_lds_dwordx4 v[210:211], off
	s_waitcnt vmcnt(8)
	s_waitcnt lgkmcnt(0)
	s_barrier
	s_setprio 1
	s_waitcnt lgkmcnt(0)
	v_mfma_f32_16x16x32_bf16 v[124:127], v[146:149], v[178:181], v[124:127]
	v_mfma_f32_16x16x32_bf16 v[120:123], v[154:157], v[178:181], v[120:123]
	v_mfma_f32_16x16x32_bf16 v[116:119], v[146:149], v[186:189], v[116:119]
	v_mfma_f32_16x16x32_bf16 v[112:115], v[154:157], v[186:189], v[112:115]
	v_mfma_f32_16x16x32_bf16 v[108:111], v[146:149], v[194:197], v[108:111]
	v_mfma_f32_16x16x32_bf16 v[100:103], v[154:157], v[194:197], v[100:103]
	v_mfma_f32_16x16x32_bf16 v[92:95], v[146:149], v[202:205], v[92:95]
	v_mfma_f32_16x16x32_bf16 v[80:83], v[154:157], v[202:205], v[80:83]
	v_mfma_f32_16x16x32_bf16 v[124:127], v[150:153], v[182:185], v[124:127]
	v_mfma_f32_16x16x32_bf16 v[120:123], v[158:161], v[182:185], v[120:123]
	v_mfma_f32_16x16x32_bf16 v[116:119], v[150:153], v[190:193], v[116:119]
	v_mfma_f32_16x16x32_bf16 v[112:115], v[158:161], v[190:193], v[112:115]
	v_mfma_f32_16x16x32_bf16 v[108:111], v[150:153], v[198:201], v[108:111]
	v_mfma_f32_16x16x32_bf16 v[100:103], v[158:161], v[198:201], v[100:103]
	v_mfma_f32_16x16x32_bf16 v[92:95], v[150:153], v[206:209], v[92:95]
	v_mfma_f32_16x16x32_bf16 v[80:83], v[158:161], v[206:209], v[80:83]
	v_mfma_f32_16x16x32_bf16 v[104:107], v[162:165], v[178:181], v[104:107]
	v_mfma_f32_16x16x32_bf16 v[96:99], v[170:173], v[178:181], v[96:99]
	v_mfma_f32_16x16x32_bf16 v[88:91], v[162:165], v[186:189], v[88:91]
	v_mfma_f32_16x16x32_bf16 v[84:87], v[170:173], v[186:189], v[84:87]
	v_mfma_f32_16x16x32_bf16 v[76:79], v[162:165], v[194:197], v[76:79]
	v_mfma_f32_16x16x32_bf16 v[72:75], v[170:173], v[194:197], v[72:75]
	v_mfma_f32_16x16x32_bf16 v[68:71], v[162:165], v[202:205], v[68:71]
	v_mfma_f32_16x16x32_bf16 v[64:67], v[170:173], v[202:205], v[64:67]
	v_mfma_f32_16x16x32_bf16 v[104:107], v[166:169], v[182:185], v[104:107]
	v_mfma_f32_16x16x32_bf16 v[96:99], v[174:177], v[182:185], v[96:99]
	v_mfma_f32_16x16x32_bf16 v[88:91], v[166:169], v[190:193], v[88:91]
	v_mfma_f32_16x16x32_bf16 v[84:87], v[174:177], v[190:193], v[84:87]
	v_mfma_f32_16x16x32_bf16 v[76:79], v[166:169], v[198:201], v[76:79]
	v_mfma_f32_16x16x32_bf16 v[72:75], v[174:177], v[198:201], v[72:75]
	v_mfma_f32_16x16x32_bf16 v[68:71], v[166:169], v[206:209], v[68:71]
	v_mfma_f32_16x16x32_bf16 v[64:67], v[174:177], v[206:209], v[64:67]
	s_setprio 0
	s_barrier
	v_lshl_add_u64 v[210:211], s[66:67], 0, v[128:129]
	s_add_i32 s66, s59, s34
	s_mov_b32 m0, s66
	ds_read_b128 v[178:181], v144 offset:16384
	ds_read_b128 v[182:185], v144 offset:17408
	ds_read_b128 v[186:189], v144 offset:18432
	ds_read_b128 v[190:193], v144 offset:19456
	ds_read_b128 v[194:197], v144 offset:20480
	ds_read_b128 v[198:201], v144 offset:21504
	ds_read_b128 v[202:205], v144 offset:22528
	ds_read_b128 v[206:209], v144 offset:23552
	global_load_lds_dwordx4 v[210:211], off
	v_lshl_add_u64 v[212:213], v[210:211], 0, s[4:5]
	s_add_i32 m0, s66, 0x2000
	s_add_i32 s66, s60, s34
	global_load_lds_dwordx4 v[212:213], off
	v_lshl_add_u64 v[212:213], v[210:211], 0, s[6:7]
	s_mov_b32 m0, s66
	s_nop 0
	global_load_lds_dwordx4 v[212:213], off
	v_lshl_add_u64 v[212:213], v[210:211], 0, s[8:9]
	s_add_i32 m0, s66, 0x2000
	s_nop 0
	global_load_lds_dwordx4 v[212:213], off
	v_lshl_add_u64 v[212:213], s[64:65], 0, v[128:129]
	s_mov_b32 m0, s48
	v_lshl_add_u64 v[214:215], v[212:213], 0, s[4:5]
	global_load_lds_dwordx4 v[212:213], off
	s_mov_b32 m0, s49
	s_nop 0
	global_load_lds_dwordx4 v[214:215], off
	s_waitcnt vmcnt(8)
	s_waitcnt lgkmcnt(0)
	s_barrier
	s_setprio 1
	s_waitcnt lgkmcnt(0)
	v_mfma_f32_16x16x32_bf16 v[60:63], v[146:149], v[178:181], v[60:63]
	v_mfma_f32_16x16x32_bf16 v[56:59], v[154:157], v[178:181], v[56:59]
	v_mfma_f32_16x16x32_bf16 v[52:55], v[146:149], v[186:189], v[52:55]
	v_mfma_f32_16x16x32_bf16 v[40:43], v[154:157], v[186:189], v[40:43]
	v_mfma_f32_16x16x32_bf16 v[36:39], v[146:149], v[194:197], v[36:39]
	v_mfma_f32_16x16x32_bf16 v[24:27], v[154:157], v[194:197], v[24:27]
	v_mfma_f32_16x16x32_bf16 v[20:23], v[146:149], v[202:205], v[20:23]
	v_mfma_f32_16x16x32_bf16 v[8:11], v[154:157], v[202:205], v[8:11]
	v_mfma_f32_16x16x32_bf16 v[60:63], v[150:153], v[182:185], v[60:63]
	v_mfma_f32_16x16x32_bf16 v[56:59], v[158:161], v[182:185], v[56:59]
	v_mfma_f32_16x16x32_bf16 v[52:55], v[150:153], v[190:193], v[52:55]
	v_mfma_f32_16x16x32_bf16 v[40:43], v[158:161], v[190:193], v[40:43]
	v_mfma_f32_16x16x32_bf16 v[36:39], v[150:153], v[198:201], v[36:39]
	v_mfma_f32_16x16x32_bf16 v[24:27], v[158:161], v[198:201], v[24:27]
	v_mfma_f32_16x16x32_bf16 v[20:23], v[150:153], v[206:209], v[20:23]
	v_mfma_f32_16x16x32_bf16 v[8:11], v[158:161], v[206:209], v[8:11]
	v_mfma_f32_16x16x32_bf16 v[48:51], v[162:165], v[178:181], v[48:51]
	v_mfma_f32_16x16x32_bf16 v[44:47], v[170:173], v[178:181], v[44:47]
	v_mfma_f32_16x16x32_bf16 v[32:35], v[162:165], v[186:189], v[32:35]
	v_mfma_f32_16x16x32_bf16 v[28:31], v[170:173], v[186:189], v[28:31]
	v_mfma_f32_16x16x32_bf16 v[16:19], v[162:165], v[194:197], v[16:19]
	v_mfma_f32_16x16x32_bf16 v[12:15], v[170:173], v[194:197], v[12:15]
	v_mfma_f32_16x16x32_bf16 v[4:7], v[162:165], v[202:205], v[4:7]
	v_mfma_f32_16x16x32_bf16 v[0:3], v[170:173], v[202:205], v[0:3]
	v_mfma_f32_16x16x32_bf16 v[48:51], v[166:169], v[182:185], v[48:51]
	v_mfma_f32_16x16x32_bf16 v[44:47], v[174:177], v[182:185], v[44:47]
	v_mfma_f32_16x16x32_bf16 v[32:35], v[166:169], v[190:193], v[32:35]
	v_mfma_f32_16x16x32_bf16 v[28:31], v[174:177], v[190:193], v[28:31]
	v_mfma_f32_16x16x32_bf16 v[16:19], v[166:169], v[198:201], v[16:19]
	v_mfma_f32_16x16x32_bf16 v[12:15], v[174:177], v[198:201], v[12:15]
	v_mfma_f32_16x16x32_bf16 v[4:7], v[166:169], v[206:209], v[4:7]
	v_mfma_f32_16x16x32_bf16 v[0:3], v[174:177], v[206:209], v[0:3]
	s_setprio 0
	s_barrier
	s_add_i32 s64, 0, 0x18000
	v_add_u32_e32 v130, s64, v140
	s_add_i32 s65, 0, 0x1c000
	ds_read_b128 v[146:149], v130
	ds_read_b128 v[150:153], v130 offset:1024
	ds_read_b128 v[154:157], v130 offset:2048
	ds_read_b128 v[158:161], v130 offset:3072
	v_add_u32_e32 v130, s65, v140
	ds_read_b128 v[162:165], v130
	ds_read_b128 v[166:169], v130 offset:1024
	ds_read_b128 v[170:173], v130 offset:2048
	ds_read_b128 v[174:177], v130 offset:3072
	s_mov_b32 m0, s50
	v_lshl_add_u64 v[214:215], v[212:213], 0, s[6:7]
	ds_read_b128 v[178:181], v144 offset:32768
	ds_read_b128 v[182:185], v144 offset:33792
	ds_read_b128 v[186:189], v144 offset:34816
	ds_read_b128 v[190:193], v144 offset:35840
	ds_read_b128 v[194:197], v144 offset:36864
	ds_read_b128 v[198:201], v144 offset:37888
	ds_read_b128 v[202:205], v144 offset:38912
	ds_read_b128 v[206:209], v144 offset:39936
	global_load_lds_dwordx4 v[214:215], off
	v_lshl_add_u64 v[214:215], v[212:213], 0, s[8:9]
	s_mov_b32 m0, s51
	s_nop 0
	global_load_lds_dwordx4 v[214:215], off
	s_waitcnt vmcnt(8)
	s_waitcnt lgkmcnt(0)
	s_barrier
	s_setprio 1
	s_waitcnt lgkmcnt(0)
	v_mfma_f32_16x16x32_bf16 v[124:127], v[146:149], v[178:181], v[124:127]
	v_mfma_f32_16x16x32_bf16 v[120:123], v[154:157], v[178:181], v[120:123]
	v_mfma_f32_16x16x32_bf16 v[116:119], v[146:149], v[186:189], v[116:119]
	v_mfma_f32_16x16x32_bf16 v[112:115], v[154:157], v[186:189], v[112:115]
	v_mfma_f32_16x16x32_bf16 v[108:111], v[146:149], v[194:197], v[108:111]
	v_mfma_f32_16x16x32_bf16 v[100:103], v[154:157], v[194:197], v[100:103]
	v_mfma_f32_16x16x32_bf16 v[92:95], v[146:149], v[202:205], v[92:95]
	v_mfma_f32_16x16x32_bf16 v[80:83], v[154:157], v[202:205], v[80:83]
	v_mfma_f32_16x16x32_bf16 v[124:127], v[150:153], v[182:185], v[124:127]
	v_mfma_f32_16x16x32_bf16 v[120:123], v[158:161], v[182:185], v[120:123]
	v_mfma_f32_16x16x32_bf16 v[116:119], v[150:153], v[190:193], v[116:119]
	v_mfma_f32_16x16x32_bf16 v[112:115], v[158:161], v[190:193], v[112:115]
	v_mfma_f32_16x16x32_bf16 v[108:111], v[150:153], v[198:201], v[108:111]
	v_mfma_f32_16x16x32_bf16 v[100:103], v[158:161], v[198:201], v[100:103]
	v_mfma_f32_16x16x32_bf16 v[92:95], v[150:153], v[206:209], v[92:95]
	v_mfma_f32_16x16x32_bf16 v[80:83], v[158:161], v[206:209], v[80:83]
	v_mfma_f32_16x16x32_bf16 v[104:107], v[162:165], v[178:181], v[104:107]
	v_mfma_f32_16x16x32_bf16 v[96:99], v[170:173], v[178:181], v[96:99]
	v_mfma_f32_16x16x32_bf16 v[88:91], v[162:165], v[186:189], v[88:91]
	v_mfma_f32_16x16x32_bf16 v[84:87], v[170:173], v[186:189], v[84:87]
	v_mfma_f32_16x16x32_bf16 v[76:79], v[162:165], v[194:197], v[76:79]
	v_mfma_f32_16x16x32_bf16 v[72:75], v[170:173], v[194:197], v[72:75]
	v_mfma_f32_16x16x32_bf16 v[68:71], v[162:165], v[202:205], v[68:71]
	v_mfma_f32_16x16x32_bf16 v[64:67], v[170:173], v[202:205], v[64:67]
	v_mfma_f32_16x16x32_bf16 v[104:107], v[166:169], v[182:185], v[104:107]
	v_mfma_f32_16x16x32_bf16 v[96:99], v[174:177], v[182:185], v[96:99]
	v_mfma_f32_16x16x32_bf16 v[88:91], v[166:169], v[190:193], v[88:91]
	v_mfma_f32_16x16x32_bf16 v[84:87], v[174:177], v[190:193], v[84:87]
	v_mfma_f32_16x16x32_bf16 v[76:79], v[166:169], v[198:201], v[76:79]
	v_mfma_f32_16x16x32_bf16 v[72:75], v[174:177], v[198:201], v[72:75]
	v_mfma_f32_16x16x32_bf16 v[68:71], v[166:169], v[206:209], v[68:71]
	v_mfma_f32_16x16x32_bf16 v[64:67], v[174:177], v[206:209], v[64:67]
	s_setprio 0
	s_barrier
	s_add_i32 s64, s64, s34
	v_lshl_add_u64 v[214:215], v[210:211], 0, s[16:17]
	s_mov_b32 m0, s64
	ds_read_b128 v[178:181], v144 offset:49152
	ds_read_b128 v[182:185], v144 offset:50176
	ds_read_b128 v[186:189], v144 offset:51200
	ds_read_b128 v[190:193], v144 offset:52224
	ds_read_b128 v[194:197], v144 offset:53248
	ds_read_b128 v[198:201], v144 offset:54272
	ds_read_b128 v[202:205], v144 offset:55296
	ds_read_b128 v[206:209], v144 offset:56320
	global_load_lds_dwordx4 v[214:215], off
	v_lshl_add_u64 v[214:215], v[210:211], 0, s[18:19]
	s_add_i32 m0, s64, 0x2000
	s_add_i32 s64, s65, s34
	global_load_lds_dwordx4 v[214:215], off
	v_lshl_add_u64 v[214:215], v[210:211], 0, s[20:21]
	s_mov_b32 m0, s64
	v_lshl_add_u64 v[210:211], v[210:211], 0, s[22:23]
	global_load_lds_dwordx4 v[214:215], off
	s_add_i32 m0, s64, 0x2000
	s_nop 0
	global_load_lds_dwordx4 v[210:211], off
	v_lshl_add_u64 v[210:211], v[212:213], 0, s[16:17]
	s_mov_b32 m0, s57
	s_nop 0
	global_load_lds_dwordx4 v[210:211], off
	v_lshl_add_u64 v[210:211], v[212:213], 0, s[18:19]
	s_mov_b32 m0, s58
	s_nop 0
	global_load_lds_dwordx4 v[210:211], off
	s_waitcnt vmcnt(8)
	s_waitcnt lgkmcnt(0)
	s_barrier
	s_setprio 1
	s_waitcnt lgkmcnt(0)
	v_mfma_f32_16x16x32_bf16 v[60:63], v[146:149], v[178:181], v[60:63]
	v_mfma_f32_16x16x32_bf16 v[56:59], v[154:157], v[178:181], v[56:59]
	v_mfma_f32_16x16x32_bf16 v[52:55], v[146:149], v[186:189], v[52:55]
	v_mfma_f32_16x16x32_bf16 v[40:43], v[154:157], v[186:189], v[40:43]
	v_mfma_f32_16x16x32_bf16 v[36:39], v[146:149], v[194:197], v[36:39]
	v_mfma_f32_16x16x32_bf16 v[24:27], v[154:157], v[194:197], v[24:27]
	v_mfma_f32_16x16x32_bf16 v[20:23], v[146:149], v[202:205], v[20:23]
	v_mfma_f32_16x16x32_bf16 v[8:11], v[154:157], v[202:205], v[8:11]
	v_mfma_f32_16x16x32_bf16 v[60:63], v[150:153], v[182:185], v[60:63]
	v_mfma_f32_16x16x32_bf16 v[56:59], v[158:161], v[182:185], v[56:59]
	v_mfma_f32_16x16x32_bf16 v[52:55], v[150:153], v[190:193], v[52:55]
	v_mfma_f32_16x16x32_bf16 v[40:43], v[158:161], v[190:193], v[40:43]
	v_mfma_f32_16x16x32_bf16 v[36:39], v[150:153], v[198:201], v[36:39]
	v_mfma_f32_16x16x32_bf16 v[24:27], v[158:161], v[198:201], v[24:27]
	v_mfma_f32_16x16x32_bf16 v[20:23], v[150:153], v[206:209], v[20:23]
	v_mfma_f32_16x16x32_bf16 v[8:11], v[158:161], v[206:209], v[8:11]
	v_mfma_f32_16x16x32_bf16 v[48:51], v[162:165], v[178:181], v[48:51]
	v_mfma_f32_16x16x32_bf16 v[44:47], v[170:173], v[178:181], v[44:47]
	v_mfma_f32_16x16x32_bf16 v[32:35], v[162:165], v[186:189], v[32:35]
	v_mfma_f32_16x16x32_bf16 v[28:31], v[170:173], v[186:189], v[28:31]
	v_mfma_f32_16x16x32_bf16 v[16:19], v[162:165], v[194:197], v[16:19]
	v_mfma_f32_16x16x32_bf16 v[12:15], v[170:173], v[194:197], v[12:15]
	v_mfma_f32_16x16x32_bf16 v[4:7], v[162:165], v[202:205], v[4:7]
	v_mfma_f32_16x16x32_bf16 v[0:3], v[170:173], v[202:205], v[0:3]
	v_mfma_f32_16x16x32_bf16 v[48:51], v[166:169], v[182:185], v[48:51]
	v_mfma_f32_16x16x32_bf16 v[44:47], v[174:177], v[182:185], v[44:47]
	v_mfma_f32_16x16x32_bf16 v[32:35], v[166:169], v[190:193], v[32:35]
	v_mfma_f32_16x16x32_bf16 v[28:31], v[174:177], v[190:193], v[28:31]
	v_mfma_f32_16x16x32_bf16 v[16:19], v[166:169], v[198:201], v[16:19]
	v_mfma_f32_16x16x32_bf16 v[12:15], v[174:177], v[198:201], v[12:15]
	v_mfma_f32_16x16x32_bf16 v[4:7], v[166:169], v[206:209], v[4:7]
	v_mfma_f32_16x16x32_bf16 v[0:3], v[174:177], v[206:209], v[0:3]
	s_setprio 0
	s_barrier
	s_add_i32 s63, s63, 2
	s_add_u32 s44, s44, 0x100
	s_addc_u32 s45, s45, 0
	s_add_u32 s46, s46, 0x100
	s_addc_u32 s47, s47, 0
	s_cmp_gt_u32 s63, 61
	s_cbranch_scc0 .LBB0_1157
	s_and_b64 vcc, exec, s[24:25]
	s_cbranch_vccz .LBB0_1160
	s_barrier

.LBB0_1212:
	ds_read_b128 v[40:43], v160
	ds_read_b128 v[44:47], v160 offset:1024
	ds_read_b128 v[56:59], v160 offset:2048
	ds_read_b128 v[60:63], v160 offset:3072
	ds_read_b128 v[154:157], v161
	ds_read_b128 v[164:167], v161 offset:1024
	ds_read_b128 v[168:171], v161 offset:2048
	ds_read_b128 v[172:175], v161 offset:3072
	s_add_u32 s66, s36, 0xfff80080
	s_addc_u32 s67, s37, -1
	s_cmp_eq_u32 s65, 60
	s_cselect_b32 s67, s59, s67
	s_cselect_b32 s66, s60, s66
	s_cselect_b32 s69, s61, s64
	s_cselect_b32 s68, s62, s63
	v_lshl_add_u64 v[208:209], s[36:37], 0, v[152:153]
	s_add_i32 m0, s47, 0xc000
	ds_read_b128 v[176:179], v162
	ds_read_b128 v[180:183], v162 offset:1024
	ds_read_b128 v[184:187], v162 offset:2048
	ds_read_b128 v[188:191], v162 offset:3072
	ds_read_b128 v[192:195], v162 offset:4096
	ds_read_b128 v[196:199], v162 offset:5120
	ds_read_b128 v[200:203], v162 offset:6144
	ds_read_b128 v[204:207], v162 offset:7168
	global_load_lds_dwordx4 v[208:209], off
	v_lshl_add_u64 v[208:209], v[208:209], 0, s[14:15]
	s_add_i32 m0, s47, 0xe000
	s_nop 0
	global_load_lds_dwordx4 v[208:209], off
	s_waitcnt vmcnt(8)
	s_waitcnt lgkmcnt(0)
	s_barrier
	s_setprio 1
	s_waitcnt lgkmcnt(0)
	v_mfma_f32_16x16x32_bf16 v[140:143], v[40:43], v[176:179], v[140:143]
	v_mfma_f32_16x16x32_bf16 v[136:139], v[56:59], v[176:179], v[136:139]
	v_mfma_f32_16x16x32_bf16 v[124:127], v[40:43], v[184:187], v[124:127]
	v_mfma_f32_16x16x32_bf16 v[120:123], v[56:59], v[184:187], v[120:123]
	v_mfma_f32_16x16x32_bf16 v[108:111], v[40:43], v[192:195], v[108:111]
	v_mfma_f32_16x16x32_bf16 v[104:107], v[56:59], v[192:195], v[104:107]
	v_mfma_f32_16x16x32_bf16 v[92:95], v[40:43], v[200:203], v[92:95]
	v_mfma_f32_16x16x32_bf16 v[88:91], v[56:59], v[200:203], v[88:91]
	v_mfma_f32_16x16x32_bf16 v[140:143], v[44:47], v[180:183], v[140:143]
	v_mfma_f32_16x16x32_bf16 v[136:139], v[60:63], v[180:183], v[136:139]
	v_mfma_f32_16x16x32_bf16 v[124:127], v[44:47], v[188:191], v[124:127]
	v_mfma_f32_16x16x32_bf16 v[120:123], v[60:63], v[188:191], v[120:123]
	v_mfma_f32_16x16x32_bf16 v[108:111], v[44:47], v[196:199], v[108:111]
	v_mfma_f32_16x16x32_bf16 v[104:107], v[60:63], v[196:199], v[104:107]
	v_mfma_f32_16x16x32_bf16 v[92:95], v[44:47], v[204:207], v[92:95]
	v_mfma_f32_16x16x32_bf16 v[88:91], v[60:63], v[204:207], v[88:91]
	v_mfma_f32_16x16x32_bf16 v[132:135], v[154:157], v[176:179], v[132:135]
	v_mfma_f32_16x16x32_bf16 v[128:131], v[168:171], v[176:179], v[128:131]
	v_mfma_f32_16x16x32_bf16 v[116:119], v[154:157], v[184:187], v[116:119]
	v_mfma_f32_16x16x32_bf16 v[112:115], v[168:171], v[184:187], v[112:115]
	v_mfma_f32_16x16x32_bf16 v[100:103], v[154:157], v[192:195], v[100:103]
	v_mfma_f32_16x16x32_bf16 v[96:99], v[168:171], v[192:195], v[96:99]
	v_mfma_f32_16x16x32_bf16 v[84:87], v[154:157], v[200:203], v[84:87]
	v_mfma_f32_16x16x32_bf16 v[80:83], v[168:171], v[200:203], v[80:83]
	v_mfma_f32_16x16x32_bf16 v[132:135], v[164:167], v[180:183], v[132:135]
	v_mfma_f32_16x16x32_bf16 v[128:131], v[172:175], v[180:183], v[128:131]
	v_mfma_f32_16x16x32_bf16 v[116:119], v[164:167], v[188:191], v[116:119]
	v_mfma_f32_16x16x32_bf16 v[112:115], v[172:175], v[188:191], v[112:115]
	v_mfma_f32_16x16x32_bf16 v[100:103], v[164:167], v[196:199], v[100:103]
	v_mfma_f32_16x16x32_bf16 v[96:99], v[172:175], v[196:199], v[96:99]
	v_mfma_f32_16x16x32_bf16 v[84:87], v[164:167], v[204:207], v[84:87]
	v_mfma_f32_16x16x32_bf16 v[80:83], v[172:175], v[204:207], v[80:83]
	s_setprio 0
	s_barrier
	v_lshl_add_u64 v[208:209], s[68:69], 0, v[144:145]
	s_add_i32 s68, s54, s45
	s_mov_b32 m0, s68
	ds_read_b128 v[176:179], v162 offset:16384
	ds_read_b128 v[180:183], v162 offset:17408
	ds_read_b128 v[184:187], v162 offset:18432
	ds_read_b128 v[188:191], v162 offset:19456
	ds_read_b128 v[192:195], v162 offset:20480
	ds_read_b128 v[196:199], v162 offset:21504
	ds_read_b128 v[200:203], v162 offset:22528
	ds_read_b128 v[204:207], v162 offset:23552
	global_load_lds_dwordx4 v[208:209], off
	v_lshl_add_u64 v[210:211], v[208:209], 0, s[2:3]
	s_add_i32 m0, s68, 0x2000
	s_add_i32 s68, s55, s45
	global_load_lds_dwordx4 v[210:211], off
	v_lshl_add_u64 v[210:211], v[208:209], 0, s[4:5]
	s_mov_b32 m0, s68
	s_nop 0
	global_load_lds_dwordx4 v[210:211], off
	v_lshl_add_u64 v[210:211], v[208:209], 0, s[6:7]
	s_add_i32 m0, s68, 0x2000
	s_nop 0
	global_load_lds_dwordx4 v[210:211], off
	v_lshl_add_u64 v[210:211], s[66:67], 0, v[146:147]
	s_mov_b32 m0, s47
	v_lshl_add_u64 v[212:213], v[210:211], 0, s[14:15]
	global_load_lds_dwordx4 v[210:211], off
	s_mov_b32 m0, s48
	s_nop 0
	global_load_lds_dwordx4 v[212:213], off
	s_waitcnt vmcnt(8)
	s_waitcnt lgkmcnt(0)
	s_barrier
	s_setprio 1
	s_waitcnt lgkmcnt(0)
	v_mfma_f32_16x16x32_bf16 v[76:79], v[40:43], v[176:179], v[76:79]
	v_mfma_f32_16x16x32_bf16 v[72:75], v[56:59], v[176:179], v[72:75]
	v_mfma_f32_16x16x32_bf16 v[52:55], v[40:43], v[184:187], v[52:55]
	v_mfma_f32_16x16x32_bf16 v[48:51], v[56:59], v[184:187], v[48:51]
	v_mfma_f32_16x16x32_bf16 v[28:31], v[40:43], v[192:195], v[28:31]
	v_mfma_f32_16x16x32_bf16 v[24:27], v[56:59], v[192:195], v[24:27]
	v_mfma_f32_16x16x32_bf16 v[12:15], v[40:43], v[200:203], v[12:15]
	v_mfma_f32_16x16x32_bf16 v[8:11], v[56:59], v[200:203], v[8:11]
	v_mfma_f32_16x16x32_bf16 v[76:79], v[44:47], v[180:183], v[76:79]
	v_mfma_f32_16x16x32_bf16 v[72:75], v[60:63], v[180:183], v[72:75]
	v_mfma_f32_16x16x32_bf16 v[52:55], v[44:47], v[188:191], v[52:55]
	v_mfma_f32_16x16x32_bf16 v[48:51], v[60:63], v[188:191], v[48:51]
	v_mfma_f32_16x16x32_bf16 v[28:31], v[44:47], v[196:199], v[28:31]
	v_mfma_f32_16x16x32_bf16 v[24:27], v[60:63], v[196:199], v[24:27]
	v_mfma_f32_16x16x32_bf16 v[12:15], v[44:47], v[204:207], v[12:15]
	v_mfma_f32_16x16x32_bf16 v[8:11], v[60:63], v[204:207], v[8:11]
	v_mfma_f32_16x16x32_bf16 v[36:39], v[154:157], v[184:187], v[36:39]
	v_mfma_f32_16x16x32_bf16 v[32:35], v[168:171], v[184:187], v[32:35]
	v_mfma_f32_16x16x32_bf16 v[20:23], v[154:157], v[192:195], v[20:23]
	v_mfma_f32_16x16x32_bf16 v[16:19], v[168:171], v[192:195], v[16:19]
	v_mfma_f32_16x16x32_bf16 v[4:7], v[154:157], v[200:203], v[4:7]
	v_mfma_f32_16x16x32_bf16 v[0:3], v[168:171], v[200:203], v[0:3]
	v_mfma_f32_16x16x32_bf16 v[40:43], v[154:157], v[176:179], v[68:71]
	v_mfma_f32_16x16x32_bf16 v[44:47], v[168:171], v[176:179], v[64:67]
	v_mfma_f32_16x16x32_bf16 v[36:39], v[164:167], v[188:191], v[36:39]
	v_mfma_f32_16x16x32_bf16 v[32:35], v[172:175], v[188:191], v[32:35]
	v_mfma_f32_16x16x32_bf16 v[20:23], v[164:167], v[196:199], v[20:23]
	v_mfma_f32_16x16x32_bf16 v[16:19], v[172:175], v[196:199], v[16:19]
	v_mfma_f32_16x16x32_bf16 v[4:7], v[164:167], v[204:207], v[4:7]
	v_mfma_f32_16x16x32_bf16 v[0:3], v[172:175], v[204:207], v[0:3]
	v_mfma_f32_16x16x32_bf16 v[40:43], v[164:167], v[180:183], v[40:43]
	v_mfma_f32_16x16x32_bf16 v[44:47], v[172:175], v[180:183], v[44:47]
	s_setprio 0
	s_barrier
	s_add_i32 s66, 0, 0x18000
	s_add_i32 s67, 0, 0x1c000
	v_add_u32_e32 v68, s66, v159
	v_add_u32_e32 v163, s67, v159
	ds_read_b128 v[56:59], v68
	ds_read_b128 v[60:63], v68 offset:1024
	ds_read_b128 v[64:67], v68 offset:2048
	ds_read_b128 v[68:71], v68 offset:3072
	ds_read_b128 v[154:157], v163
	ds_read_b128 v[164:167], v163 offset:1024
	ds_read_b128 v[168:171], v163 offset:2048
	ds_read_b128 v[172:175], v163 offset:3072
	s_mov_b32 m0, s49
	v_lshl_add_u64 v[212:213], v[210:211], 0, s[2:3]
	ds_read_b128 v[176:179], v162 offset:32768
	ds_read_b128 v[180:183], v162 offset:33792
	ds_read_b128 v[184:187], v162 offset:34816
	ds_read_b128 v[188:191], v162 offset:35840
	ds_read_b128 v[192:195], v162 offset:36864
	ds_read_b128 v[196:199], v162 offset:37888
	ds_read_b128 v[200:203], v162 offset:38912
	ds_read_b128 v[204:207], v162 offset:39936
	global_load_lds_dwordx4 v[212:213], off
	v_lshl_add_u64 v[212:213], v[210:211], 0, s[16:17]
	s_mov_b32 m0, s50
	s_nop 0
	global_load_lds_dwordx4 v[212:213], off
	s_waitcnt vmcnt(8)
	s_waitcnt lgkmcnt(0)
	s_barrier
	s_setprio 1
	s_waitcnt lgkmcnt(0)
	v_mfma_f32_16x16x32_bf16 v[140:143], v[56:59], v[176:179], v[140:143]
	v_mfma_f32_16x16x32_bf16 v[136:139], v[64:67], v[176:179], v[136:139]
	v_mfma_f32_16x16x32_bf16 v[124:127], v[56:59], v[184:187], v[124:127]
	v_mfma_f32_16x16x32_bf16 v[120:123], v[64:67], v[184:187], v[120:123]
	v_mfma_f32_16x16x32_bf16 v[108:111], v[56:59], v[192:195], v[108:111]
	v_mfma_f32_16x16x32_bf16 v[104:107], v[64:67], v[192:195], v[104:107]
	v_mfma_f32_16x16x32_bf16 v[92:95], v[56:59], v[200:203], v[92:95]
	v_mfma_f32_16x16x32_bf16 v[88:91], v[64:67], v[200:203], v[88:91]
	v_mfma_f32_16x16x32_bf16 v[140:143], v[60:63], v[180:183], v[140:143]
	v_mfma_f32_16x16x32_bf16 v[136:139], v[68:71], v[180:183], v[136:139]
	v_mfma_f32_16x16x32_bf16 v[124:127], v[60:63], v[188:191], v[124:127]
	v_mfma_f32_16x16x32_bf16 v[120:123], v[68:71], v[188:191], v[120:123]
	v_mfma_f32_16x16x32_bf16 v[108:111], v[60:63], v[196:199], v[108:111]
	v_mfma_f32_16x16x32_bf16 v[104:107], v[68:71], v[196:199], v[104:107]
	v_mfma_f32_16x16x32_bf16 v[92:95], v[60:63], v[204:207], v[92:95]
	v_mfma_f32_16x16x32_bf16 v[88:91], v[68:71], v[204:207], v[88:91]
	v_mfma_f32_16x16x32_bf16 v[132:135], v[154:157], v[176:179], v[132:135]
	v_mfma_f32_16x16x32_bf16 v[128:131], v[168:171], v[176:179], v[128:131]
	v_mfma_f32_16x16x32_bf16 v[116:119], v[154:157], v[184:187], v[116:119]
	v_mfma_f32_16x16x32_bf16 v[112:115], v[168:171], v[184:187], v[112:115]
	v_mfma_f32_16x16x32_bf16 v[100:103], v[154:157], v[192:195], v[100:103]
	v_mfma_f32_16x16x32_bf16 v[96:99], v[168:171], v[192:195], v[96:99]
	v_mfma_f32_16x16x32_bf16 v[84:87], v[154:157], v[200:203], v[84:87]
	v_mfma_f32_16x16x32_bf16 v[80:83], v[168:171], v[200:203], v[80:83]
	v_mfma_f32_16x16x32_bf16 v[132:135], v[164:167], v[180:183], v[132:135]
	v_mfma_f32_16x16x32_bf16 v[128:131], v[172:175], v[180:183], v[128:131]
	v_mfma_f32_16x16x32_bf16 v[116:119], v[164:167], v[188:191], v[116:119]
	v_mfma_f32_16x16x32_bf16 v[112:115], v[172:175], v[188:191], v[112:115]
	v_mfma_f32_16x16x32_bf16 v[100:103], v[164:167], v[196:199], v[100:103]
	v_mfma_f32_16x16x32_bf16 v[96:99], v[172:175], v[196:199], v[96:99]
	v_mfma_f32_16x16x32_bf16 v[84:87], v[164:167], v[204:207], v[84:87]
	v_mfma_f32_16x16x32_bf16 v[80:83], v[172:175], v[204:207], v[80:83]
	s_setprio 0
	s_barrier
	s_add_i32 s66, s66, s45
	v_lshl_add_u64 v[212:213], v[208:209], 0, s[20:21]
	s_mov_b32 m0, s66
	ds_read_b128 v[176:179], v162 offset:49152
	ds_read_b128 v[180:183], v162 offset:50176
	ds_read_b128 v[184:187], v162 offset:51200
	ds_read_b128 v[188:191], v162 offset:52224
	ds_read_b128 v[192:195], v162 offset:53248
	ds_read_b128 v[196:199], v162 offset:54272
	ds_read_b128 v[200:203], v162 offset:55296
	ds_read_b128 v[204:207], v162 offset:56320
	global_load_lds_dwordx4 v[212:213], off
	v_lshl_add_u64 v[212:213], v[208:209], 0, s[22:23]
	s_add_i32 m0, s66, 0x2000
	s_add_i32 s66, s67, s45
	global_load_lds_dwordx4 v[212:213], off
	v_lshl_add_u64 v[212:213], v[208:209], 0, s[26:27]
	s_mov_b32 m0, s66
	v_lshl_add_u64 v[208:209], v[208:209], 0, s[28:29]
	global_load_lds_dwordx4 v[212:213], off
	s_add_i32 m0, s66, 0x2000
	s_nop 0
	global_load_lds_dwordx4 v[208:209], off
	v_lshl_add_u64 v[208:209], v[210:211], 0, s[20:21]
	s_mov_b32 m0, s51
	s_nop 0
	global_load_lds_dwordx4 v[208:209], off
	v_lshl_add_u64 v[208:209], v[210:211], 0, s[24:25]
	s_mov_b32 m0, s52
	s_nop 0
	global_load_lds_dwordx4 v[208:209], off
	s_waitcnt vmcnt(8)
	s_waitcnt lgkmcnt(0)
	s_barrier
	s_setprio 1
	s_waitcnt lgkmcnt(0)
	v_mfma_f32_16x16x32_bf16 v[76:79], v[56:59], v[176:179], v[76:79]
	v_mfma_f32_16x16x32_bf16 v[72:75], v[64:67], v[176:179], v[72:75]
	v_mfma_f32_16x16x32_bf16 v[52:55], v[56:59], v[184:187], v[52:55]
	v_mfma_f32_16x16x32_bf16 v[48:51], v[64:67], v[184:187], v[48:51]
	v_mfma_f32_16x16x32_bf16 v[28:31], v[56:59], v[192:195], v[28:31]
	v_mfma_f32_16x16x32_bf16 v[24:27], v[64:67], v[192:195], v[24:27]
	v_mfma_f32_16x16x32_bf16 v[12:15], v[56:59], v[200:203], v[12:15]
	v_mfma_f32_16x16x32_bf16 v[8:11], v[64:67], v[200:203], v[8:11]
	v_mfma_f32_16x16x32_bf16 v[76:79], v[60:63], v[180:183], v[76:79]
	v_mfma_f32_16x16x32_bf16 v[72:75], v[68:71], v[180:183], v[72:75]
	v_mfma_f32_16x16x32_bf16 v[52:55], v[60:63], v[188:191], v[52:55]
	v_mfma_f32_16x16x32_bf16 v[48:51], v[68:71], v[188:191], v[48:51]
	v_mfma_f32_16x16x32_bf16 v[28:31], v[60:63], v[196:199], v[28:31]
	v_mfma_f32_16x16x32_bf16 v[24:27], v[68:71], v[196:199], v[24:27]
	v_mfma_f32_16x16x32_bf16 v[12:15], v[60:63], v[204:207], v[12:15]
	v_mfma_f32_16x16x32_bf16 v[8:11], v[68:71], v[204:207], v[8:11]
	v_mfma_f32_16x16x32_bf16 v[40:43], v[154:157], v[176:179], v[40:43]
	v_mfma_f32_16x16x32_bf16 v[68:71], v[164:167], v[180:183], v[40:43]
	v_mfma_f32_16x16x32_bf16 v[40:43], v[168:171], v[176:179], v[44:47]
	v_mfma_f32_16x16x32_bf16 v[36:39], v[154:157], v[184:187], v[36:39]
	v_mfma_f32_16x16x32_bf16 v[32:35], v[168:171], v[184:187], v[32:35]
	v_mfma_f32_16x16x32_bf16 v[20:23], v[154:157], v[192:195], v[20:23]
	v_mfma_f32_16x16x32_bf16 v[16:19], v[168:171], v[192:195], v[16:19]
	v_mfma_f32_16x16x32_bf16 v[4:7], v[154:157], v[200:203], v[4:7]
	v_mfma_f32_16x16x32_bf16 v[0:3], v[168:171], v[200:203], v[0:3]
	v_mfma_f32_16x16x32_bf16 v[64:67], v[172:175], v[180:183], v[40:43]
	v_mfma_f32_16x16x32_bf16 v[36:39], v[164:167], v[188:191], v[36:39]
	v_mfma_f32_16x16x32_bf16 v[32:35], v[172:175], v[188:191], v[32:35]
	v_mfma_f32_16x16x32_bf16 v[20:23], v[164:167], v[196:199], v[20:23]
	v_mfma_f32_16x16x32_bf16 v[16:19], v[172:175], v[196:199], v[16:19]
	v_mfma_f32_16x16x32_bf16 v[4:7], v[164:167], v[204:207], v[4:7]
	v_mfma_f32_16x16x32_bf16 v[0:3], v[172:175], v[204:207], v[0:3]
	s_setprio 0
	s_barrier
	s_add_i32 s65, s65, 2
	s_add_u32 s36, s36, 0x100
	s_addc_u32 s37, s37, 0
	s_add_u32 s63, s63, 0x100
	s_addc_u32 s64, s64, 0
	s_cmp_gt_u32 s65, 61
	s_cbranch_scc0 .LBB0_1212
	s_and_b64 vcc, exec, s[30:31]
	s_cbranch_vccz .LBB0_1215
	s_barrier

.LBB0_1403:
	s_add_u32 s38, s36, 0xfff00080
	s_addc_u32 s39, s37, -1
	s_add_i32 s61, 0, 0x10000
	s_cmp_eq_u32 s60, 60
	s_cselect_b32 s39, s5, s39
	s_cselect_b32 s38, s15, s38
	s_cselect_b32 s63, s13, s59
	s_cselect_b32 s62, s27, s58
	s_add_i32 s64, 0, 0x14000
	v_add_u32_e32 v146, s61, v157
	v_add_u32_e32 v154, s64, v157
	ds_read_b128 v[134:137], v146
	ds_read_b128 v[138:141], v146 offset:1024
	ds_read_b128 v[142:145], v146 offset:2048
	ds_read_b128 v[146:149], v146 offset:3072
	ds_read_b128 v[150:153], v154
	ds_read_b128 v[172:175], v154 offset:1024
	ds_read_b128 v[176:179], v154 offset:2048
	ds_read_b128 v[190:193], v154 offset:3072
	v_lshl_add_u64 v[154:155], s[36:37], 0, v[132:133]
	s_add_i32 m0, s45, 0xc000
	ds_read_b128 v[194:197], v160
	ds_read_b128 v[198:201], v160 offset:1024
	ds_read_b128 v[202:205], v160 offset:2048
	ds_read_b128 v[206:209], v160 offset:3072
	ds_read_b128 v[210:213], v160 offset:4096
	ds_read_b128 v[214:217], v160 offset:5120
	ds_read_b128 v[218:221], v160 offset:6144
	ds_read_b128 v[222:225], v160 offset:7168
	global_load_lds_dwordx4 v[154:155], off
	v_lshl_add_u64 v[154:155], v[154:155], 0, s[24:25]
	s_add_i32 m0, s45, 0xe000
	s_nop 0
	global_load_lds_dwordx4 v[154:155], off
	s_waitcnt vmcnt(8)
	s_waitcnt lgkmcnt(0)
	s_barrier
	s_setprio 1
	s_waitcnt lgkmcnt(0)
	v_mfma_f32_16x16x32_bf16 v[126:129], v[134:137], v[194:197], v[126:129]
	v_mfma_f32_16x16x32_bf16 v[122:125], v[142:145], v[194:197], v[122:125]
	v_mfma_f32_16x16x32_bf16 v[110:113], v[134:137], v[202:205], v[110:113]
	v_mfma_f32_16x16x32_bf16 v[106:109], v[142:145], v[202:205], v[106:109]
	v_mfma_f32_16x16x32_bf16 v[94:97], v[134:137], v[210:213], v[94:97]
	v_mfma_f32_16x16x32_bf16 v[90:93], v[142:145], v[210:213], v[90:93]
	v_mfma_f32_16x16x32_bf16 v[78:81], v[134:137], v[218:221], v[78:81]
	v_mfma_f32_16x16x32_bf16 v[74:77], v[142:145], v[218:221], v[74:77]
	v_mfma_f32_16x16x32_bf16 v[126:129], v[138:141], v[198:201], v[126:129]
	v_mfma_f32_16x16x32_bf16 v[122:125], v[146:149], v[198:201], v[122:125]
	v_mfma_f32_16x16x32_bf16 v[110:113], v[138:141], v[206:209], v[110:113]
	v_mfma_f32_16x16x32_bf16 v[106:109], v[146:149], v[206:209], v[106:109]
	v_mfma_f32_16x16x32_bf16 v[94:97], v[138:141], v[214:217], v[94:97]
	v_mfma_f32_16x16x32_bf16 v[90:93], v[146:149], v[214:217], v[90:93]
	v_mfma_f32_16x16x32_bf16 v[78:81], v[138:141], v[222:225], v[78:81]
	v_mfma_f32_16x16x32_bf16 v[74:77], v[146:149], v[222:225], v[74:77]
	v_mfma_f32_16x16x32_bf16 v[118:121], v[150:153], v[194:197], v[118:121]
	v_mfma_f32_16x16x32_bf16 v[114:117], v[176:179], v[194:197], v[114:117]
	v_mfma_f32_16x16x32_bf16 v[102:105], v[150:153], v[202:205], v[102:105]
	v_mfma_f32_16x16x32_bf16 v[98:101], v[176:179], v[202:205], v[98:101]
	v_mfma_f32_16x16x32_bf16 v[86:89], v[150:153], v[210:213], v[86:89]
	v_mfma_f32_16x16x32_bf16 v[82:85], v[176:179], v[210:213], v[82:85]
	v_mfma_f32_16x16x32_bf16 v[70:73], v[150:153], v[218:221], v[70:73]
	v_mfma_f32_16x16x32_bf16 v[66:69], v[176:179], v[218:221], v[66:69]
	v_mfma_f32_16x16x32_bf16 v[118:121], v[172:175], v[198:201], v[118:121]
	v_mfma_f32_16x16x32_bf16 v[114:117], v[190:193], v[198:201], v[114:117]
	v_mfma_f32_16x16x32_bf16 v[102:105], v[172:175], v[206:209], v[102:105]
	v_mfma_f32_16x16x32_bf16 v[98:101], v[190:193], v[206:209], v[98:101]
	v_mfma_f32_16x16x32_bf16 v[86:89], v[172:175], v[214:217], v[86:89]
	v_mfma_f32_16x16x32_bf16 v[82:85], v[190:193], v[214:217], v[82:85]
	v_mfma_f32_16x16x32_bf16 v[70:73], v[172:175], v[222:225], v[70:73]
	v_mfma_f32_16x16x32_bf16 v[66:69], v[190:193], v[222:225], v[66:69]
	s_setprio 0
	s_barrier
	s_add_i32 s61, s61, s20
	v_lshl_add_u64 v[154:155], s[62:63], 0, v[0:1]
	s_mov_b32 m0, s61
	ds_read_b128 v[194:197], v160 offset:16384
	ds_read_b128 v[198:201], v160 offset:17408
	ds_read_b128 v[202:205], v160 offset:18432
	ds_read_b128 v[206:209], v160 offset:19456
	ds_read_b128 v[210:213], v160 offset:20480
	ds_read_b128 v[214:217], v160 offset:21504
	ds_read_b128 v[218:221], v160 offset:22528
	ds_read_b128 v[222:225], v160 offset:23552
	global_load_lds_dwordx4 v[154:155], off
	v_lshl_add_u64 v[164:165], v[154:155], 0, s[24:25]
	s_add_i32 m0, s61, 0x2000
	s_add_i32 s61, s64, s20
	global_load_lds_dwordx4 v[164:165], off
	v_lshl_add_u64 v[164:165], v[154:155], 0, s[22:23]
	s_mov_b32 m0, s61
	s_nop 0
	global_load_lds_dwordx4 v[164:165], off
	v_lshl_add_u64 v[164:165], v[154:155], 0, s[28:29]
	s_add_i32 m0, s61, 0x2000
	s_nop 0
	global_load_lds_dwordx4 v[164:165], off
	v_lshl_add_u64 v[164:165], s[38:39], 0, v[130:131]
	s_mov_b32 m0, s45
	v_lshl_add_u64 v[166:167], v[164:165], 0, s[24:25]
	global_load_lds_dwordx4 v[164:165], off
	s_mov_b32 m0, s46
	s_nop 0
	global_load_lds_dwordx4 v[166:167], off
	s_waitcnt vmcnt(8)
	s_waitcnt lgkmcnt(0)
	s_barrier
	s_setprio 1
	s_waitcnt lgkmcnt(0)
	v_mfma_f32_16x16x32_bf16 v[62:65], v[134:137], v[194:197], v[62:65]
	v_mfma_f32_16x16x32_bf16 v[58:61], v[142:145], v[194:197], v[58:61]
	v_mfma_f32_16x16x32_bf16 v[46:49], v[134:137], v[202:205], v[46:49]
	v_mfma_f32_16x16x32_bf16 v[42:45], v[142:145], v[202:205], v[42:45]
	v_mfma_f32_16x16x32_bf16 v[30:33], v[134:137], v[210:213], v[30:33]
	v_mfma_f32_16x16x32_bf16 v[26:29], v[142:145], v[210:213], v[26:29]
	v_mfma_f32_16x16x32_bf16 v[14:17], v[134:137], v[218:221], v[14:17]
	v_mfma_f32_16x16x32_bf16 v[10:13], v[142:145], v[218:221], v[10:13]
	v_mfma_f32_16x16x32_bf16 v[62:65], v[138:141], v[198:201], v[62:65]
	v_mfma_f32_16x16x32_bf16 v[58:61], v[146:149], v[198:201], v[58:61]
	v_mfma_f32_16x16x32_bf16 v[46:49], v[138:141], v[206:209], v[46:49]
	v_mfma_f32_16x16x32_bf16 v[42:45], v[146:149], v[206:209], v[42:45]
	v_mfma_f32_16x16x32_bf16 v[30:33], v[138:141], v[214:217], v[30:33]
	v_mfma_f32_16x16x32_bf16 v[26:29], v[146:149], v[214:217], v[26:29]
	v_mfma_f32_16x16x32_bf16 v[14:17], v[138:141], v[222:225], v[14:17]
	v_mfma_f32_16x16x32_bf16 v[10:13], v[146:149], v[222:225], v[10:13]
	v_mfma_f32_16x16x32_bf16 v[54:57], v[150:153], v[194:197], v[54:57]
	v_mfma_f32_16x16x32_bf16 v[50:53], v[176:179], v[194:197], v[50:53]
	v_mfma_f32_16x16x32_bf16 v[38:41], v[150:153], v[202:205], v[38:41]
	v_mfma_f32_16x16x32_bf16 v[34:37], v[176:179], v[202:205], v[34:37]
	v_mfma_f32_16x16x32_bf16 v[22:25], v[150:153], v[210:213], v[22:25]
	v_mfma_f32_16x16x32_bf16 v[18:21], v[176:179], v[210:213], v[18:21]
	v_mfma_f32_16x16x32_bf16 v[6:9], v[150:153], v[218:221], v[6:9]
	v_mfma_f32_16x16x32_bf16 v[2:5], v[176:179], v[218:221], v[2:5]
	v_mfma_f32_16x16x32_bf16 v[54:57], v[172:175], v[198:201], v[54:57]
	v_mfma_f32_16x16x32_bf16 v[50:53], v[190:193], v[198:201], v[50:53]
	v_mfma_f32_16x16x32_bf16 v[38:41], v[172:175], v[206:209], v[38:41]
	v_mfma_f32_16x16x32_bf16 v[34:37], v[190:193], v[206:209], v[34:37]
	v_mfma_f32_16x16x32_bf16 v[22:25], v[172:175], v[214:217], v[22:25]
	v_mfma_f32_16x16x32_bf16 v[18:21], v[190:193], v[214:217], v[18:21]
	v_mfma_f32_16x16x32_bf16 v[6:9], v[172:175], v[222:225], v[6:9]
	v_mfma_f32_16x16x32_bf16 v[2:5], v[190:193], v[222:225], v[2:5]
	s_setprio 0
	s_barrier
	s_add_i32 s38, 0, 0x18000
	s_add_i32 s39, 0, 0x1c000
	v_add_u32_e32 v146, s38, v157
	v_add_u32_e32 v159, s39, v157
	ds_read_b128 v[134:137], v146
	ds_read_b128 v[138:141], v146 offset:1024
	ds_read_b128 v[142:145], v146 offset:2048
	ds_read_b128 v[146:149], v146 offset:3072
	ds_read_b128 v[150:153], v159
	ds_read_b128 v[172:175], v159 offset:1024
	ds_read_b128 v[176:179], v159 offset:2048
	ds_read_b128 v[190:193], v159 offset:3072
	s_mov_b32 m0, s47
	v_lshl_add_u64 v[166:167], v[164:165], 0, s[22:23]
	ds_read_b128 v[194:197], v160 offset:32768
	ds_read_b128 v[198:201], v160 offset:33792
	ds_read_b128 v[202:205], v160 offset:34816
	ds_read_b128 v[206:209], v160 offset:35840
	ds_read_b128 v[210:213], v160 offset:36864
	ds_read_b128 v[214:217], v160 offset:37888
	ds_read_b128 v[218:221], v160 offset:38912
	ds_read_b128 v[222:225], v160 offset:39936
	global_load_lds_dwordx4 v[166:167], off
	v_lshl_add_u64 v[166:167], v[164:165], 0, s[28:29]
	s_mov_b32 m0, s52
	s_nop 0
	global_load_lds_dwordx4 v[166:167], off
	s_waitcnt vmcnt(8)
	s_waitcnt lgkmcnt(0)
	s_barrier
	s_setprio 1
	s_waitcnt lgkmcnt(0)
	v_mfma_f32_16x16x32_bf16 v[126:129], v[134:137], v[194:197], v[126:129]
	v_mfma_f32_16x16x32_bf16 v[122:125], v[142:145], v[194:197], v[122:125]
	v_mfma_f32_16x16x32_bf16 v[110:113], v[134:137], v[202:205], v[110:113]
	v_mfma_f32_16x16x32_bf16 v[106:109], v[142:145], v[202:205], v[106:109]
	v_mfma_f32_16x16x32_bf16 v[94:97], v[134:137], v[210:213], v[94:97]
	v_mfma_f32_16x16x32_bf16 v[90:93], v[142:145], v[210:213], v[90:93]
	v_mfma_f32_16x16x32_bf16 v[78:81], v[134:137], v[218:221], v[78:81]
	v_mfma_f32_16x16x32_bf16 v[74:77], v[142:145], v[218:221], v[74:77]
	v_mfma_f32_16x16x32_bf16 v[126:129], v[138:141], v[198:201], v[126:129]
	v_mfma_f32_16x16x32_bf16 v[122:125], v[146:149], v[198:201], v[122:125]
	v_mfma_f32_16x16x32_bf16 v[110:113], v[138:141], v[206:209], v[110:113]
	v_mfma_f32_16x16x32_bf16 v[106:109], v[146:149], v[206:209], v[106:109]
	v_mfma_f32_16x16x32_bf16 v[94:97], v[138:141], v[214:217], v[94:97]
	v_mfma_f32_16x16x32_bf16 v[90:93], v[146:149], v[214:217], v[90:93]
	v_mfma_f32_16x16x32_bf16 v[78:81], v[138:141], v[222:225], v[78:81]
	v_mfma_f32_16x16x32_bf16 v[74:77], v[146:149], v[222:225], v[74:77]
	v_mfma_f32_16x16x32_bf16 v[118:121], v[150:153], v[194:197], v[118:121]
	v_mfma_f32_16x16x32_bf16 v[114:117], v[176:179], v[194:197], v[114:117]
	v_mfma_f32_16x16x32_bf16 v[102:105], v[150:153], v[202:205], v[102:105]
	v_mfma_f32_16x16x32_bf16 v[98:101], v[176:179], v[202:205], v[98:101]
	v_mfma_f32_16x16x32_bf16 v[86:89], v[150:153], v[210:213], v[86:89]
	v_mfma_f32_16x16x32_bf16 v[82:85], v[176:179], v[210:213], v[82:85]
	v_mfma_f32_16x16x32_bf16 v[70:73], v[150:153], v[218:221], v[70:73]
	v_mfma_f32_16x16x32_bf16 v[66:69], v[176:179], v[218:221], v[66:69]
	v_mfma_f32_16x16x32_bf16 v[118:121], v[172:175], v[198:201], v[118:121]
	v_mfma_f32_16x16x32_bf16 v[114:117], v[190:193], v[198:201], v[114:117]
	v_mfma_f32_16x16x32_bf16 v[102:105], v[172:175], v[206:209], v[102:105]
	v_mfma_f32_16x16x32_bf16 v[98:101], v[190:193], v[206:209], v[98:101]
	v_mfma_f32_16x16x32_bf16 v[86:89], v[172:175], v[214:217], v[86:89]
	v_mfma_f32_16x16x32_bf16 v[82:85], v[190:193], v[214:217], v[82:85]
	v_mfma_f32_16x16x32_bf16 v[70:73], v[172:175], v[222:225], v[70:73]
	v_mfma_f32_16x16x32_bf16 v[66:69], v[190:193], v[222:225], v[66:69]
	s_setprio 0
	s_barrier
	s_add_i32 s38, s38, s20
	v_lshl_add_u64 v[166:167], v[154:155], 0, s[30:31]
	s_mov_b32 m0, s38
	ds_read_b128 v[194:197], v160 offset:49152
	ds_read_b128 v[198:201], v160 offset:50176
	ds_read_b128 v[202:205], v160 offset:51200
	ds_read_b128 v[206:209], v160 offset:52224
	ds_read_b128 v[210:213], v160 offset:53248
	ds_read_b128 v[214:217], v160 offset:54272
	ds_read_b128 v[218:221], v160 offset:55296
	ds_read_b128 v[222:225], v160 offset:56320
	global_load_lds_dwordx4 v[166:167], off
	v_lshl_add_u64 v[166:167], v[154:155], 0, s[34:35]
	s_add_i32 m0, s38, 0x2000
	s_add_i32 s38, s39, s20
	global_load_lds_dwordx4 v[166:167], off
	v_lshl_add_u64 v[166:167], v[154:155], 0, s[88:89]
	s_mov_b32 m0, s38
	v_lshl_add_u64 v[154:155], v[154:155], 0, s[90:91]
	global_load_lds_dwordx4 v[166:167], off
	s_add_i32 m0, s38, 0x2000
	s_nop 0
	global_load_lds_dwordx4 v[154:155], off
	v_lshl_add_u64 v[154:155], v[164:165], 0, s[30:31]
	s_mov_b32 m0, s53
	s_nop 0
	global_load_lds_dwordx4 v[154:155], off
	v_lshl_add_u64 v[154:155], v[164:165], 0, s[34:35]
	s_mov_b32 m0, s54
	s_nop 0
	global_load_lds_dwordx4 v[154:155], off
	s_waitcnt vmcnt(8)
	s_waitcnt lgkmcnt(0)
	s_barrier
	s_setprio 1
	s_waitcnt lgkmcnt(0)
	v_mfma_f32_16x16x32_bf16 v[62:65], v[134:137], v[194:197], v[62:65]
	v_mfma_f32_16x16x32_bf16 v[58:61], v[142:145], v[194:197], v[58:61]
	v_mfma_f32_16x16x32_bf16 v[46:49], v[134:137], v[202:205], v[46:49]
	v_mfma_f32_16x16x32_bf16 v[42:45], v[142:145], v[202:205], v[42:45]
	v_mfma_f32_16x16x32_bf16 v[30:33], v[134:137], v[210:213], v[30:33]
	v_mfma_f32_16x16x32_bf16 v[26:29], v[142:145], v[210:213], v[26:29]
	v_mfma_f32_16x16x32_bf16 v[14:17], v[134:137], v[218:221], v[14:17]
	v_mfma_f32_16x16x32_bf16 v[10:13], v[142:145], v[218:221], v[10:13]
	v_mfma_f32_16x16x32_bf16 v[62:65], v[138:141], v[198:201], v[62:65]
	v_mfma_f32_16x16x32_bf16 v[58:61], v[146:149], v[198:201], v[58:61]
	v_mfma_f32_16x16x32_bf16 v[46:49], v[138:141], v[206:209], v[46:49]
	v_mfma_f32_16x16x32_bf16 v[42:45], v[146:149], v[206:209], v[42:45]
	v_mfma_f32_16x16x32_bf16 v[30:33], v[138:141], v[214:217], v[30:33]
	v_mfma_f32_16x16x32_bf16 v[26:29], v[146:149], v[214:217], v[26:29]
	v_mfma_f32_16x16x32_bf16 v[14:17], v[138:141], v[222:225], v[14:17]
	v_mfma_f32_16x16x32_bf16 v[10:13], v[146:149], v[222:225], v[10:13]
	v_mfma_f32_16x16x32_bf16 v[54:57], v[150:153], v[194:197], v[54:57]
	v_mfma_f32_16x16x32_bf16 v[50:53], v[176:179], v[194:197], v[50:53]
	v_mfma_f32_16x16x32_bf16 v[38:41], v[150:153], v[202:205], v[38:41]
	v_mfma_f32_16x16x32_bf16 v[34:37], v[176:179], v[202:205], v[34:37]
	v_mfma_f32_16x16x32_bf16 v[22:25], v[150:153], v[210:213], v[22:25]
	v_mfma_f32_16x16x32_bf16 v[18:21], v[176:179], v[210:213], v[18:21]
	v_mfma_f32_16x16x32_bf16 v[6:9], v[150:153], v[218:221], v[6:9]
	v_mfma_f32_16x16x32_bf16 v[2:5], v[176:179], v[218:221], v[2:5]
	v_mfma_f32_16x16x32_bf16 v[54:57], v[172:175], v[198:201], v[54:57]
	v_mfma_f32_16x16x32_bf16 v[50:53], v[190:193], v[198:201], v[50:53]
	v_mfma_f32_16x16x32_bf16 v[38:41], v[172:175], v[206:209], v[38:41]
	v_mfma_f32_16x16x32_bf16 v[34:37], v[190:193], v[206:209], v[34:37]
	v_mfma_f32_16x16x32_bf16 v[22:25], v[172:175], v[214:217], v[22:25]
	v_mfma_f32_16x16x32_bf16 v[18:21], v[190:193], v[214:217], v[18:21]
	v_mfma_f32_16x16x32_bf16 v[6:9], v[172:175], v[222:225], v[6:9]
	v_mfma_f32_16x16x32_bf16 v[2:5], v[190:193], v[222:225], v[2:5]
	s_setprio 0
	s_barrier
	s_add_i32 s60, s60, 2
	s_add_u32 s36, s36, 0x100
	s_addc_u32 s37, s37, 0
	s_add_u32 s58, s58, 0x100
	s_addc_u32 s59, s59, 0
	s_cmp_gt_u32 s60, 61
	s_cbranch_scc0 .LBB0_1403
	s_and_b64 vcc, exec, s[10:11]
	s_cbranch_vccz .LBB0_1406
	s_barrier

.LBB0_1490:
	s_add_u32 s62, s16, 0xfff00080
	s_addc_u32 s63, s17, -1
	s_add_i32 s66, 0, 0x10000
	v_add_u32_e32 v73, s66, v71
	ds_read_b128 v[74:77], v73
	ds_read_b128 v[78:81], v73 offset:1024
	ds_read_b128 v[82:85], v73 offset:2048
	ds_read_b128 v[86:89], v73 offset:3072
	s_cmp_eq_u32 s20, 4
	s_cselect_b32 s63, s13, s63
	s_cselect_b32 s62, s12, s62
	s_cselect_b32 s65, s7, s19
	s_cselect_b32 s64, s11, s18
	v_lshl_add_u64 v[122:123], s[16:17], 0, v[68:69]
	s_add_i32 m0, s39, 0xc000
	ds_read_b128 v[90:93], v72
	ds_read_b128 v[94:97], v72 offset:1024
	ds_read_b128 v[98:101], v72 offset:2048
	ds_read_b128 v[102:105], v72 offset:3072
	ds_read_b128 v[106:109], v72 offset:4096
	ds_read_b128 v[110:113], v72 offset:5120
	ds_read_b128 v[114:117], v72 offset:6144
	ds_read_b128 v[118:121], v72 offset:7168
	global_load_lds_dwordx4 v[122:123], off
	v_lshl_add_u64 v[122:123], v[122:123], 0, s[24:25]
	s_add_i32 m0, s39, 0xe000
	s_nop 0
	global_load_lds_dwordx4 v[122:123], off
	s_waitcnt vmcnt(8)
	s_waitcnt lgkmcnt(0)
	s_barrier
	s_setprio 1
	s_waitcnt lgkmcnt(0)
	v_mfma_f32_16x16x32_bf16 v[62:65], v[74:77], v[90:93], v[62:65]
	v_mfma_f32_16x16x32_bf16 v[58:61], v[82:85], v[90:93], v[58:61]
	v_mfma_f32_16x16x32_bf16 v[54:57], v[74:77], v[98:101], v[54:57]
	v_mfma_f32_16x16x32_bf16 v[50:53], v[82:85], v[98:101], v[50:53]
	v_mfma_f32_16x16x32_bf16 v[46:49], v[74:77], v[106:109], v[46:49]
	v_mfma_f32_16x16x32_bf16 v[42:45], v[82:85], v[106:109], v[42:45]
	v_mfma_f32_16x16x32_bf16 v[38:41], v[74:77], v[114:117], v[38:41]
	v_mfma_f32_16x16x32_bf16 v[34:37], v[82:85], v[114:117], v[34:37]
	v_mfma_f32_16x16x32_bf16 v[62:65], v[78:81], v[94:97], v[62:65]
	v_mfma_f32_16x16x32_bf16 v[58:61], v[86:89], v[94:97], v[58:61]
	v_mfma_f32_16x16x32_bf16 v[54:57], v[78:81], v[102:105], v[54:57]
	v_mfma_f32_16x16x32_bf16 v[50:53], v[86:89], v[102:105], v[50:53]
	v_mfma_f32_16x16x32_bf16 v[46:49], v[78:81], v[110:113], v[46:49]
	v_mfma_f32_16x16x32_bf16 v[42:45], v[86:89], v[110:113], v[42:45]
	v_mfma_f32_16x16x32_bf16 v[38:41], v[78:81], v[118:121], v[38:41]
	v_mfma_f32_16x16x32_bf16 v[34:37], v[86:89], v[118:121], v[34:37]
	s_setprio 0
	s_barrier
	v_lshl_add_u64 v[122:123], s[64:65], 0, v[0:1]
	s_add_i32 s64, s66, s36
	s_mov_b32 m0, s64
	ds_read_b128 v[90:93], v72 offset:16384
	ds_read_b128 v[94:97], v72 offset:17408
	ds_read_b128 v[98:101], v72 offset:18432
	ds_read_b128 v[102:105], v72 offset:19456
	ds_read_b128 v[106:109], v72 offset:20480
	ds_read_b128 v[110:113], v72 offset:21504
	ds_read_b128 v[114:117], v72 offset:22528
	ds_read_b128 v[118:121], v72 offset:23552
	global_load_lds_dwordx4 v[122:123], off
	v_lshl_add_u64 v[124:125], v[122:123], 0, s[24:25]
	s_add_i32 m0, s64, 0x2000
	s_nop 0
	global_load_lds_dwordx4 v[124:125], off
	v_lshl_add_u64 v[124:125], v[122:123], 0, s[22:23]
	s_mov_b32 m0, s45
	s_nop 0
	global_load_lds_dwordx4 v[124:125], off
	v_lshl_add_u64 v[124:125], v[122:123], 0, s[28:29]
	s_mov_b32 m0, s46
	s_nop 0
	global_load_lds_dwordx4 v[124:125], off
	v_lshl_add_u64 v[124:125], s[62:63], 0, v[0:1]
	s_mov_b32 m0, s39
	v_lshl_add_u64 v[126:127], v[124:125], 0, s[24:25]
	global_load_lds_dwordx4 v[124:125], off
	s_mov_b32 m0, s47
	s_nop 0
	global_load_lds_dwordx4 v[126:127], off
	s_waitcnt vmcnt(8)
	s_waitcnt lgkmcnt(0)
	s_barrier
	s_setprio 1
	s_waitcnt lgkmcnt(0)
	v_mfma_f32_16x16x32_bf16 v[30:33], v[74:77], v[90:93], v[30:33]
	v_mfma_f32_16x16x32_bf16 v[26:29], v[82:85], v[90:93], v[26:29]
	v_mfma_f32_16x16x32_bf16 v[22:25], v[74:77], v[98:101], v[22:25]
	v_mfma_f32_16x16x32_bf16 v[18:21], v[82:85], v[98:101], v[18:21]
	v_mfma_f32_16x16x32_bf16 v[14:17], v[74:77], v[106:109], v[14:17]
	v_mfma_f32_16x16x32_bf16 v[10:13], v[82:85], v[106:109], v[10:13]
	v_mfma_f32_16x16x32_bf16 v[6:9], v[74:77], v[114:117], v[6:9]
	v_mfma_f32_16x16x32_bf16 v[2:5], v[82:85], v[114:117], v[2:5]
	v_mfma_f32_16x16x32_bf16 v[30:33], v[78:81], v[94:97], v[30:33]
	v_mfma_f32_16x16x32_bf16 v[26:29], v[86:89], v[94:97], v[26:29]
	v_mfma_f32_16x16x32_bf16 v[22:25], v[78:81], v[102:105], v[22:25]
	v_mfma_f32_16x16x32_bf16 v[18:21], v[86:89], v[102:105], v[18:21]
	v_mfma_f32_16x16x32_bf16 v[14:17], v[78:81], v[110:113], v[14:17]
	v_mfma_f32_16x16x32_bf16 v[10:13], v[86:89], v[110:113], v[10:13]
	v_mfma_f32_16x16x32_bf16 v[6:9], v[78:81], v[118:121], v[6:9]
	v_mfma_f32_16x16x32_bf16 v[2:5], v[86:89], v[118:121], v[2:5]
	s_setprio 0
	s_barrier
	s_add_i32 s62, 0, 0x18000
	v_add_u32_e32 v73, s62, v71
	ds_read_b128 v[74:77], v73
	ds_read_b128 v[78:81], v73 offset:1024
	ds_read_b128 v[82:85], v73 offset:2048
	ds_read_b128 v[86:89], v73 offset:3072
	s_mov_b32 m0, s52
	v_lshl_add_u64 v[126:127], v[124:125], 0, s[22:23]
	ds_read_b128 v[90:93], v72 offset:32768
	ds_read_b128 v[94:97], v72 offset:33792
	ds_read_b128 v[98:101], v72 offset:34816
	ds_read_b128 v[102:105], v72 offset:35840
	ds_read_b128 v[106:109], v72 offset:36864
	ds_read_b128 v[110:113], v72 offset:37888
	ds_read_b128 v[114:117], v72 offset:38912
	ds_read_b128 v[118:121], v72 offset:39936
	global_load_lds_dwordx4 v[126:127], off
	v_lshl_add_u64 v[126:127], v[124:125], 0, s[28:29]
	s_mov_b32 m0, s53
	s_nop 0
	global_load_lds_dwordx4 v[126:127], off
	s_waitcnt vmcnt(8)
	s_waitcnt lgkmcnt(0)
	s_barrier
	s_setprio 1
	s_waitcnt lgkmcnt(0)
	v_mfma_f32_16x16x32_bf16 v[62:65], v[74:77], v[90:93], v[62:65]
	v_mfma_f32_16x16x32_bf16 v[58:61], v[82:85], v[90:93], v[58:61]
	v_mfma_f32_16x16x32_bf16 v[54:57], v[74:77], v[98:101], v[54:57]
	v_mfma_f32_16x16x32_bf16 v[50:53], v[82:85], v[98:101], v[50:53]
	v_mfma_f32_16x16x32_bf16 v[46:49], v[74:77], v[106:109], v[46:49]
	v_mfma_f32_16x16x32_bf16 v[42:45], v[82:85], v[106:109], v[42:45]
	v_mfma_f32_16x16x32_bf16 v[38:41], v[74:77], v[114:117], v[38:41]
	v_mfma_f32_16x16x32_bf16 v[34:37], v[82:85], v[114:117], v[34:37]
	v_mfma_f32_16x16x32_bf16 v[62:65], v[78:81], v[94:97], v[62:65]
	v_mfma_f32_16x16x32_bf16 v[58:61], v[86:89], v[94:97], v[58:61]
	v_mfma_f32_16x16x32_bf16 v[54:57], v[78:81], v[102:105], v[54:57]
	v_mfma_f32_16x16x32_bf16 v[50:53], v[86:89], v[102:105], v[50:53]
	v_mfma_f32_16x16x32_bf16 v[46:49], v[78:81], v[110:113], v[46:49]
	v_mfma_f32_16x16x32_bf16 v[42:45], v[86:89], v[110:113], v[42:45]
	v_mfma_f32_16x16x32_bf16 v[38:41], v[78:81], v[118:121], v[38:41]
	v_mfma_f32_16x16x32_bf16 v[34:37], v[86:89], v[118:121], v[34:37]
	s_setprio 0
	s_barrier
	s_add_i32 s62, s62, s36
	v_lshl_add_u64 v[126:127], v[122:123], 0, s[30:31]
	s_mov_b32 m0, s62
	ds_read_b128 v[90:93], v72 offset:49152
	ds_read_b128 v[94:97], v72 offset:50176
	ds_read_b128 v[98:101], v72 offset:51200
	ds_read_b128 v[102:105], v72 offset:52224
	ds_read_b128 v[106:109], v72 offset:53248
	ds_read_b128 v[110:113], v72 offset:54272
	ds_read_b128 v[114:117], v72 offset:55296
	ds_read_b128 v[118:121], v72 offset:56320
	global_load_lds_dwordx4 v[126:127], off
	v_lshl_add_u64 v[126:127], v[122:123], 0, s[34:35]
	s_add_i32 m0, s62, 0x2000
	s_nop 0
	global_load_lds_dwordx4 v[126:127], off
	v_lshl_add_u64 v[126:127], v[122:123], 0, s[88:89]
	s_mov_b32 m0, s57
	v_lshl_add_u64 v[122:123], v[122:123], 0, s[90:91]
	global_load_lds_dwordx4 v[126:127], off
	s_mov_b32 m0, s58
	s_nop 0
	global_load_lds_dwordx4 v[122:123], off
	v_lshl_add_u64 v[122:123], v[124:125], 0, s[30:31]
	s_mov_b32 m0, s54
	s_nop 0
	global_load_lds_dwordx4 v[122:123], off
	v_lshl_add_u64 v[122:123], v[124:125], 0, s[34:35]
	s_mov_b32 m0, s55
	s_nop 0
	global_load_lds_dwordx4 v[122:123], off
	s_waitcnt vmcnt(8)
	s_waitcnt lgkmcnt(0)
	s_barrier
	s_setprio 1
	s_waitcnt lgkmcnt(0)
	v_mfma_f32_16x16x32_bf16 v[30:33], v[74:77], v[90:93], v[30:33]
	v_mfma_f32_16x16x32_bf16 v[26:29], v[82:85], v[90:93], v[26:29]
	v_mfma_f32_16x16x32_bf16 v[22:25], v[74:77], v[98:101], v[22:25]
	v_mfma_f32_16x16x32_bf16 v[18:21], v[82:85], v[98:101], v[18:21]
	v_mfma_f32_16x16x32_bf16 v[14:17], v[74:77], v[106:109], v[14:17]
	v_mfma_f32_16x16x32_bf16 v[10:13], v[82:85], v[106:109], v[10:13]
	v_mfma_f32_16x16x32_bf16 v[6:9], v[74:77], v[114:117], v[6:9]
	v_mfma_f32_16x16x32_bf16 v[2:5], v[82:85], v[114:117], v[2:5]
	v_mfma_f32_16x16x32_bf16 v[30:33], v[78:81], v[94:97], v[30:33]
	v_mfma_f32_16x16x32_bf16 v[26:29], v[86:89], v[94:97], v[26:29]
	v_mfma_f32_16x16x32_bf16 v[22:25], v[78:81], v[102:105], v[22:25]
	v_mfma_f32_16x16x32_bf16 v[18:21], v[86:89], v[102:105], v[18:21]
	v_mfma_f32_16x16x32_bf16 v[14:17], v[78:81], v[110:113], v[14:17]
	v_mfma_f32_16x16x32_bf16 v[10:13], v[86:89], v[110:113], v[10:13]
	v_mfma_f32_16x16x32_bf16 v[6:9], v[78:81], v[118:121], v[6:9]
	v_mfma_f32_16x16x32_bf16 v[2:5], v[86:89], v[118:121], v[2:5]
	s_setprio 0
	s_barrier
	s_add_i32 s20, s20, 2
	s_add_u32 s16, s16, 0x100
	s_addc_u32 s17, s17, 0
	s_add_u32 s18, s18, 0x100
	s_addc_u32 s19, s19, 0
	s_cmp_gt_u32 s20, 5
	s_cbranch_scc0 .LBB0_1490
	s_and_b64 vcc, exec, s[4:5]
	s_cbranch_vccz .LBB0_1493
	s_barrier

.LBB0_1509:
	s_add_u32 s18, s16, 0xfff80080
	s_addc_u32 s19, s17, -1
	s_add_i32 s59, 0, 0x10000
	s_cmp_eq_u32 s58, 4
	s_cselect_b32 s19, s13, s19
	s_cselect_b32 s18, s12, s18
	v_add_u32_e32 v139, s59, v137
	s_cselect_b32 s61, s11, s57
	s_cselect_b32 s60, s20, s55
	s_add_i32 s62, 0, 0x14000
	ds_read_b128 v[140:143], v139
	ds_read_b128 v[144:147], v139 offset:1024
	ds_read_b128 v[148:151], v139 offset:2048
	ds_read_b128 v[152:155], v139 offset:3072
	v_add_u32_e32 v139, s62, v137
	ds_read_b128 v[172:175], v139
	ds_read_b128 v[176:179], v139 offset:1024
	ds_read_b128 v[190:193], v139 offset:2048
	ds_read_b128 v[194:197], v139 offset:3072
	v_lshl_add_u64 v[156:157], s[16:17], 0, v[134:135]
	s_add_i32 m0, s44, 0xc000
	ds_read_b128 v[198:201], v138
	ds_read_b128 v[202:205], v138 offset:1024
	ds_read_b128 v[206:209], v138 offset:2048
	ds_read_b128 v[210:213], v138 offset:3072
	ds_read_b128 v[214:217], v138 offset:4096
	ds_read_b128 v[218:221], v138 offset:5120
	ds_read_b128 v[222:225], v138 offset:6144
	ds_read_b128 v[226:229], v138 offset:7168
	global_load_lds_dwordx4 v[156:157], off
	v_lshl_add_u64 v[156:157], v[156:157], 0, s[48:49]
	s_add_i32 m0, s44, 0xe000
	s_nop 0
	global_load_lds_dwordx4 v[156:157], off
	s_waitcnt vmcnt(8)
	s_waitcnt lgkmcnt(0)
	s_barrier
	s_setprio 1
	s_waitcnt lgkmcnt(0)
	v_mfma_f32_16x16x32_bf16 v[126:129], v[140:143], v[198:201], v[126:129]
	v_mfma_f32_16x16x32_bf16 v[122:125], v[148:151], v[198:201], v[122:125]
	v_mfma_f32_16x16x32_bf16 v[118:121], v[140:143], v[206:209], v[118:121]
	v_mfma_f32_16x16x32_bf16 v[114:117], v[148:151], v[206:209], v[114:117]
	v_mfma_f32_16x16x32_bf16 v[106:109], v[140:143], v[214:217], v[106:109]
	v_mfma_f32_16x16x32_bf16 v[98:101], v[148:151], v[214:217], v[98:101]
	v_mfma_f32_16x16x32_bf16 v[90:93], v[140:143], v[222:225], v[90:93]
	v_mfma_f32_16x16x32_bf16 v[82:85], v[148:151], v[222:225], v[82:85]
	v_mfma_f32_16x16x32_bf16 v[126:129], v[144:147], v[202:205], v[126:129]
	v_mfma_f32_16x16x32_bf16 v[122:125], v[152:155], v[202:205], v[122:125]
	v_mfma_f32_16x16x32_bf16 v[118:121], v[144:147], v[210:213], v[118:121]
	v_mfma_f32_16x16x32_bf16 v[114:117], v[152:155], v[210:213], v[114:117]
	v_mfma_f32_16x16x32_bf16 v[106:109], v[144:147], v[218:221], v[106:109]
	v_mfma_f32_16x16x32_bf16 v[98:101], v[152:155], v[218:221], v[98:101]
	v_mfma_f32_16x16x32_bf16 v[90:93], v[144:147], v[226:229], v[90:93]
	v_mfma_f32_16x16x32_bf16 v[82:85], v[152:155], v[226:229], v[82:85]
	v_mfma_f32_16x16x32_bf16 v[110:113], v[172:175], v[198:201], v[110:113]
	v_mfma_f32_16x16x32_bf16 v[102:105], v[190:193], v[198:201], v[102:105]
	v_mfma_f32_16x16x32_bf16 v[94:97], v[172:175], v[206:209], v[94:97]
	v_mfma_f32_16x16x32_bf16 v[86:89], v[190:193], v[206:209], v[86:89]
	v_mfma_f32_16x16x32_bf16 v[78:81], v[172:175], v[214:217], v[78:81]
	v_mfma_f32_16x16x32_bf16 v[74:77], v[190:193], v[214:217], v[74:77]
	v_mfma_f32_16x16x32_bf16 v[70:73], v[172:175], v[222:225], v[70:73]
	v_mfma_f32_16x16x32_bf16 v[66:69], v[190:193], v[222:225], v[66:69]
	v_mfma_f32_16x16x32_bf16 v[110:113], v[176:179], v[202:205], v[110:113]
	v_mfma_f32_16x16x32_bf16 v[102:105], v[194:197], v[202:205], v[102:105]
	v_mfma_f32_16x16x32_bf16 v[94:97], v[176:179], v[210:213], v[94:97]
	v_mfma_f32_16x16x32_bf16 v[86:89], v[194:197], v[210:213], v[86:89]
	v_mfma_f32_16x16x32_bf16 v[78:81], v[176:179], v[218:221], v[78:81]
	v_mfma_f32_16x16x32_bf16 v[74:77], v[194:197], v[218:221], v[74:77]
	v_mfma_f32_16x16x32_bf16 v[70:73], v[176:179], v[226:229], v[70:73]
	v_mfma_f32_16x16x32_bf16 v[66:69], v[194:197], v[226:229], v[66:69]
	s_setprio 0
	s_barrier
	s_add_i32 s59, s59, s43
	v_lshl_add_u64 v[156:157], s[60:61], 0, v[0:1]
	s_mov_b32 m0, s59
	ds_read_b128 v[198:201], v138 offset:16384
	ds_read_b128 v[202:205], v138 offset:17408
	ds_read_b128 v[206:209], v138 offset:18432
	ds_read_b128 v[210:213], v138 offset:19456
	ds_read_b128 v[214:217], v138 offset:20480
	ds_read_b128 v[218:221], v138 offset:21504
	ds_read_b128 v[222:225], v138 offset:22528
	ds_read_b128 v[226:229], v138 offset:23552
	global_load_lds_dwordx4 v[156:157], off
	v_lshl_add_u64 v[158:159], v[156:157], 0, s[24:25]
	s_add_i32 m0, s59, 0x2000
	s_add_i32 s59, s62, s43
	global_load_lds_dwordx4 v[158:159], off
	v_lshl_add_u64 v[158:159], v[156:157], 0, s[22:23]
	s_mov_b32 m0, s59
	s_nop 0
	global_load_lds_dwordx4 v[158:159], off
	v_lshl_add_u64 v[158:159], v[156:157], 0, s[28:29]
	s_add_i32 m0, s59, 0x2000
	s_nop 0
	global_load_lds_dwordx4 v[158:159], off
	v_lshl_add_u64 v[158:159], s[18:19], 0, v[130:131]
	s_mov_b32 m0, s44
	v_lshl_add_u64 v[160:161], v[158:159], 0, s[48:49]
	global_load_lds_dwordx4 v[158:159], off
	s_mov_b32 m0, s45
	s_nop 0
	global_load_lds_dwordx4 v[160:161], off
	s_waitcnt vmcnt(8)
	s_waitcnt lgkmcnt(0)
	s_barrier
	s_setprio 1
	s_waitcnt lgkmcnt(0)
	v_mfma_f32_16x16x32_bf16 v[62:65], v[140:143], v[198:201], v[62:65]
	v_mfma_f32_16x16x32_bf16 v[58:61], v[148:151], v[198:201], v[58:61]
	v_mfma_f32_16x16x32_bf16 v[54:57], v[140:143], v[206:209], v[54:57]
	v_mfma_f32_16x16x32_bf16 v[50:53], v[148:151], v[206:209], v[50:53]
	v_mfma_f32_16x16x32_bf16 v[38:41], v[140:143], v[214:217], v[38:41]
	v_mfma_f32_16x16x32_bf16 v[34:37], v[148:151], v[214:217], v[34:37]
	v_mfma_f32_16x16x32_bf16 v[22:25], v[140:143], v[222:225], v[22:25]
	v_mfma_f32_16x16x32_bf16 v[18:21], v[148:151], v[222:225], v[18:21]
	v_mfma_f32_16x16x32_bf16 v[62:65], v[144:147], v[202:205], v[62:65]
	v_mfma_f32_16x16x32_bf16 v[58:61], v[152:155], v[202:205], v[58:61]
	v_mfma_f32_16x16x32_bf16 v[54:57], v[144:147], v[210:213], v[54:57]
	v_mfma_f32_16x16x32_bf16 v[50:53], v[152:155], v[210:213], v[50:53]
	v_mfma_f32_16x16x32_bf16 v[38:41], v[144:147], v[218:221], v[38:41]
	v_mfma_f32_16x16x32_bf16 v[34:37], v[152:155], v[218:221], v[34:37]
	v_mfma_f32_16x16x32_bf16 v[22:25], v[144:147], v[226:229], v[22:25]
	v_mfma_f32_16x16x32_bf16 v[18:21], v[152:155], v[226:229], v[18:21]
	v_mfma_f32_16x16x32_bf16 v[46:49], v[172:175], v[198:201], v[46:49]
	v_mfma_f32_16x16x32_bf16 v[42:45], v[190:193], v[198:201], v[42:45]
	v_mfma_f32_16x16x32_bf16 v[30:33], v[172:175], v[206:209], v[30:33]
	v_mfma_f32_16x16x32_bf16 v[26:29], v[190:193], v[206:209], v[26:29]
	v_mfma_f32_16x16x32_bf16 v[14:17], v[172:175], v[214:217], v[14:17]
	v_mfma_f32_16x16x32_bf16 v[10:13], v[190:193], v[214:217], v[10:13]
	v_mfma_f32_16x16x32_bf16 v[6:9], v[172:175], v[222:225], v[6:9]
	v_mfma_f32_16x16x32_bf16 v[2:5], v[190:193], v[222:225], v[2:5]
	v_mfma_f32_16x16x32_bf16 v[46:49], v[176:179], v[202:205], v[46:49]
	v_mfma_f32_16x16x32_bf16 v[42:45], v[194:197], v[202:205], v[42:45]
	v_mfma_f32_16x16x32_bf16 v[30:33], v[176:179], v[210:213], v[30:33]
	v_mfma_f32_16x16x32_bf16 v[26:29], v[194:197], v[210:213], v[26:29]
	v_mfma_f32_16x16x32_bf16 v[14:17], v[176:179], v[218:221], v[14:17]
	v_mfma_f32_16x16x32_bf16 v[10:13], v[194:197], v[218:221], v[10:13]
	v_mfma_f32_16x16x32_bf16 v[6:9], v[176:179], v[226:229], v[6:9]
	v_mfma_f32_16x16x32_bf16 v[2:5], v[194:197], v[226:229], v[2:5]
	s_setprio 0
	s_barrier
	s_add_i32 s18, 0, 0x18000
	v_add_u32_e32 v139, s18, v137
	s_add_i32 s19, 0, 0x1c000
	ds_read_b128 v[140:143], v139
	ds_read_b128 v[144:147], v139 offset:1024
	ds_read_b128 v[148:151], v139 offset:2048
	ds_read_b128 v[152:155], v139 offset:3072
	v_add_u32_e32 v139, s19, v137
	ds_read_b128 v[172:175], v139
	ds_read_b128 v[176:179], v139 offset:1024
	ds_read_b128 v[190:193], v139 offset:2048
	ds_read_b128 v[194:197], v139 offset:3072
	s_mov_b32 m0, s46
	v_lshl_add_u64 v[160:161], v[158:159], 0, s[24:25]
	ds_read_b128 v[198:201], v138 offset:32768
	ds_read_b128 v[202:205], v138 offset:33792
	ds_read_b128 v[206:209], v138 offset:34816
	ds_read_b128 v[210:213], v138 offset:35840
	ds_read_b128 v[214:217], v138 offset:36864
	ds_read_b128 v[218:221], v138 offset:37888
	ds_read_b128 v[222:225], v138 offset:38912
	ds_read_b128 v[226:229], v138 offset:39936
	global_load_lds_dwordx4 v[160:161], off
	v_lshl_add_u64 v[160:161], v[158:159], 0, s[64:65]
	s_mov_b32 m0, s47
	s_nop 0
	global_load_lds_dwordx4 v[160:161], off
	s_waitcnt vmcnt(8)
	s_waitcnt lgkmcnt(0)
	s_barrier
	s_setprio 1
	s_waitcnt lgkmcnt(0)
	v_mfma_f32_16x16x32_bf16 v[126:129], v[140:143], v[198:201], v[126:129]
	v_mfma_f32_16x16x32_bf16 v[122:125], v[148:151], v[198:201], v[122:125]
	v_mfma_f32_16x16x32_bf16 v[118:121], v[140:143], v[206:209], v[118:121]
	v_mfma_f32_16x16x32_bf16 v[114:117], v[148:151], v[206:209], v[114:117]
	v_mfma_f32_16x16x32_bf16 v[106:109], v[140:143], v[214:217], v[106:109]
	v_mfma_f32_16x16x32_bf16 v[98:101], v[148:151], v[214:217], v[98:101]
	v_mfma_f32_16x16x32_bf16 v[90:93], v[140:143], v[222:225], v[90:93]
	v_mfma_f32_16x16x32_bf16 v[82:85], v[148:151], v[222:225], v[82:85]
	v_mfma_f32_16x16x32_bf16 v[126:129], v[144:147], v[202:205], v[126:129]
	v_mfma_f32_16x16x32_bf16 v[122:125], v[152:155], v[202:205], v[122:125]
	v_mfma_f32_16x16x32_bf16 v[118:121], v[144:147], v[210:213], v[118:121]
	v_mfma_f32_16x16x32_bf16 v[114:117], v[152:155], v[210:213], v[114:117]
	v_mfma_f32_16x16x32_bf16 v[106:109], v[144:147], v[218:221], v[106:109]
	v_mfma_f32_16x16x32_bf16 v[98:101], v[152:155], v[218:221], v[98:101]
	v_mfma_f32_16x16x32_bf16 v[90:93], v[144:147], v[226:229], v[90:93]
	v_mfma_f32_16x16x32_bf16 v[82:85], v[152:155], v[226:229], v[82:85]
	v_mfma_f32_16x16x32_bf16 v[110:113], v[172:175], v[198:201], v[110:113]
	v_mfma_f32_16x16x32_bf16 v[102:105], v[190:193], v[198:201], v[102:105]
	v_mfma_f32_16x16x32_bf16 v[94:97], v[172:175], v[206:209], v[94:97]
	v_mfma_f32_16x16x32_bf16 v[86:89], v[190:193], v[206:209], v[86:89]
	v_mfma_f32_16x16x32_bf16 v[78:81], v[172:175], v[214:217], v[78:81]
	v_mfma_f32_16x16x32_bf16 v[74:77], v[190:193], v[214:217], v[74:77]
	v_mfma_f32_16x16x32_bf16 v[70:73], v[172:175], v[222:225], v[70:73]
	v_mfma_f32_16x16x32_bf16 v[66:69], v[190:193], v[222:225], v[66:69]
	v_mfma_f32_16x16x32_bf16 v[110:113], v[176:179], v[202:205], v[110:113]
	v_mfma_f32_16x16x32_bf16 v[102:105], v[194:197], v[202:205], v[102:105]
	v_mfma_f32_16x16x32_bf16 v[94:97], v[176:179], v[210:213], v[94:97]
	v_mfma_f32_16x16x32_bf16 v[86:89], v[194:197], v[210:213], v[86:89]
	v_mfma_f32_16x16x32_bf16 v[78:81], v[176:179], v[218:221], v[78:81]
	v_mfma_f32_16x16x32_bf16 v[74:77], v[194:197], v[218:221], v[74:77]
	v_mfma_f32_16x16x32_bf16 v[70:73], v[176:179], v[226:229], v[70:73]
	v_mfma_f32_16x16x32_bf16 v[66:69], v[194:197], v[226:229], v[66:69]
	s_setprio 0
	s_barrier
	s_add_i32 s18, s18, s43
	v_lshl_add_u64 v[160:161], v[156:157], 0, s[30:31]
	s_mov_b32 m0, s18
	ds_read_b128 v[198:201], v138 offset:49152
	ds_read_b128 v[202:205], v138 offset:50176
	ds_read_b128 v[206:209], v138 offset:51200
	ds_read_b128 v[210:213], v138 offset:52224
	ds_read_b128 v[214:217], v138 offset:53248
	ds_read_b128 v[218:221], v138 offset:54272
	ds_read_b128 v[222:225], v138 offset:55296
	ds_read_b128 v[226:229], v138 offset:56320
	global_load_lds_dwordx4 v[160:161], off
	v_lshl_add_u64 v[160:161], v[156:157], 0, s[34:35]
	s_add_i32 m0, s18, 0x2000
	s_add_i32 s18, s19, s43
	global_load_lds_dwordx4 v[160:161], off
	v_lshl_add_u64 v[160:161], v[156:157], 0, s[88:89]
	s_mov_b32 m0, s18
	v_lshl_add_u64 v[156:157], v[156:157], 0, s[90:91]
	global_load_lds_dwordx4 v[160:161], off
	s_add_i32 m0, s18, 0x2000
	s_nop 0
	global_load_lds_dwordx4 v[156:157], off
	v_lshl_add_u64 v[156:157], v[158:159], 0, s[30:31]
	s_mov_b32 m0, s52
	s_nop 0
	global_load_lds_dwordx4 v[156:157], off
	v_lshl_add_u64 v[156:157], v[158:159], 0, s[66:67]
	s_mov_b32 m0, s53
	s_nop 0
	global_load_lds_dwordx4 v[156:157], off
	s_waitcnt vmcnt(8)
	s_waitcnt lgkmcnt(0)
	s_barrier
	s_setprio 1
	s_waitcnt lgkmcnt(0)
	v_mfma_f32_16x16x32_bf16 v[62:65], v[140:143], v[198:201], v[62:65]
	v_mfma_f32_16x16x32_bf16 v[58:61], v[148:151], v[198:201], v[58:61]
	v_mfma_f32_16x16x32_bf16 v[54:57], v[140:143], v[206:209], v[54:57]
	v_mfma_f32_16x16x32_bf16 v[50:53], v[148:151], v[206:209], v[50:53]
	v_mfma_f32_16x16x32_bf16 v[38:41], v[140:143], v[214:217], v[38:41]
	v_mfma_f32_16x16x32_bf16 v[34:37], v[148:151], v[214:217], v[34:37]
	v_mfma_f32_16x16x32_bf16 v[22:25], v[140:143], v[222:225], v[22:25]
	v_mfma_f32_16x16x32_bf16 v[18:21], v[148:151], v[222:225], v[18:21]
	v_mfma_f32_16x16x32_bf16 v[62:65], v[144:147], v[202:205], v[62:65]
	v_mfma_f32_16x16x32_bf16 v[58:61], v[152:155], v[202:205], v[58:61]
	v_mfma_f32_16x16x32_bf16 v[54:57], v[144:147], v[210:213], v[54:57]
	v_mfma_f32_16x16x32_bf16 v[50:53], v[152:155], v[210:213], v[50:53]
	v_mfma_f32_16x16x32_bf16 v[38:41], v[144:147], v[218:221], v[38:41]
	v_mfma_f32_16x16x32_bf16 v[34:37], v[152:155], v[218:221], v[34:37]
	v_mfma_f32_16x16x32_bf16 v[22:25], v[144:147], v[226:229], v[22:25]
	v_mfma_f32_16x16x32_bf16 v[18:21], v[152:155], v[226:229], v[18:21]
	v_mfma_f32_16x16x32_bf16 v[46:49], v[172:175], v[198:201], v[46:49]
	v_mfma_f32_16x16x32_bf16 v[42:45], v[190:193], v[198:201], v[42:45]
	v_mfma_f32_16x16x32_bf16 v[30:33], v[172:175], v[206:209], v[30:33]
	v_mfma_f32_16x16x32_bf16 v[26:29], v[190:193], v[206:209], v[26:29]
	v_mfma_f32_16x16x32_bf16 v[14:17], v[172:175], v[214:217], v[14:17]
	v_mfma_f32_16x16x32_bf16 v[10:13], v[190:193], v[214:217], v[10:13]
	v_mfma_f32_16x16x32_bf16 v[6:9], v[172:175], v[222:225], v[6:9]
	v_mfma_f32_16x16x32_bf16 v[2:5], v[190:193], v[222:225], v[2:5]
	v_mfma_f32_16x16x32_bf16 v[46:49], v[176:179], v[202:205], v[46:49]
	v_mfma_f32_16x16x32_bf16 v[42:45], v[194:197], v[202:205], v[42:45]
	v_mfma_f32_16x16x32_bf16 v[30:33], v[176:179], v[210:213], v[30:33]
	v_mfma_f32_16x16x32_bf16 v[26:29], v[194:197], v[210:213], v[26:29]
	v_mfma_f32_16x16x32_bf16 v[14:17], v[176:179], v[218:221], v[14:17]
	v_mfma_f32_16x16x32_bf16 v[10:13], v[194:197], v[218:221], v[10:13]
	v_mfma_f32_16x16x32_bf16 v[6:9], v[176:179], v[226:229], v[6:9]
	v_mfma_f32_16x16x32_bf16 v[2:5], v[194:197], v[226:229], v[2:5]
	s_setprio 0
	s_barrier
	s_add_i32 s58, s58, 2
	s_add_u32 s16, s16, 0x100
	s_addc_u32 s17, s17, 0
	s_add_u32 s55, s55, 0x100
	s_addc_u32 s57, s57, 0
	s_cmp_gt_u32 s58, 5
	s_cbranch_scc0 .LBB0_1509
	s_and_b64 vcc, exec, s[4:5]
	s_cbranch_vccz .LBB0_1512
	s_barrier

.LBB0_3117:
	s_add_u32 s40, s38, 0xfff00080
	s_addc_u32 s41, s39, -1
	s_add_i32 s69, 0, 0x10000
	s_cmp_eq_u32 s68, 60
	s_cselect_b32 s41, s17, s41
	s_cselect_b32 s40, s64, s40
	v_add_u32_e32 v145, s69, v155
	s_cselect_b32 s71, s15, s67
	s_cselect_b32 s70, s65, s66
	s_add_i32 s72, 0, 0x14000
	ds_read_b128 v[130:133], v145
	ds_read_b128 v[134:137], v145 offset:1024
	ds_read_b128 v[148:151], v145 offset:2048
	ds_read_b128 v[164:167], v145 offset:3072
	v_add_u32_e32 v145, s72, v155
	ds_read_b128 v[172:175], v145
	ds_read_b128 v[176:179], v145 offset:1024
	ds_read_b128 v[190:193], v145 offset:2048
	ds_read_b128 v[194:197], v145 offset:3072
	v_lshl_add_u64 v[152:153], s[38:39], 0, v[142:143]
	s_add_i32 m0, s54, 0xc000
	ds_read_b128 v[198:201], v157
	ds_read_b128 v[202:205], v157 offset:1024
	ds_read_b128 v[206:209], v157 offset:2048
	ds_read_b128 v[210:213], v157 offset:3072
	ds_read_b128 v[214:217], v157 offset:4096
	ds_read_b128 v[218:221], v157 offset:5120
	ds_read_b128 v[222:225], v157 offset:6144
	ds_read_b128 v[226:229], v157 offset:7168
	global_load_lds_dwordx4 v[152:153], off
	v_lshl_add_u64 v[152:153], v[152:153], 0, s[24:25]
	s_add_i32 m0, s54, 0xe000
	s_nop 0
	global_load_lds_dwordx4 v[152:153], off
	s_waitcnt vmcnt(8)
	s_waitcnt lgkmcnt(0)
	s_barrier
	s_setprio 1
	s_waitcnt lgkmcnt(0)
	v_mfma_f32_16x16x32_bf16 v[126:129], v[130:133], v[198:201], v[126:129]
	v_mfma_f32_16x16x32_bf16 v[122:125], v[148:151], v[198:201], v[122:125]
	v_mfma_f32_16x16x32_bf16 v[110:113], v[130:133], v[206:209], v[110:113]
	v_mfma_f32_16x16x32_bf16 v[106:109], v[148:151], v[206:209], v[106:109]
	v_mfma_f32_16x16x32_bf16 v[94:97], v[130:133], v[214:217], v[94:97]
	v_mfma_f32_16x16x32_bf16 v[90:93], v[148:151], v[214:217], v[90:93]
	v_mfma_f32_16x16x32_bf16 v[78:81], v[130:133], v[222:225], v[78:81]
	v_mfma_f32_16x16x32_bf16 v[74:77], v[148:151], v[222:225], v[74:77]
	v_mfma_f32_16x16x32_bf16 v[126:129], v[134:137], v[202:205], v[126:129]
	v_mfma_f32_16x16x32_bf16 v[122:125], v[164:167], v[202:205], v[122:125]
	v_mfma_f32_16x16x32_bf16 v[110:113], v[134:137], v[210:213], v[110:113]
	v_mfma_f32_16x16x32_bf16 v[106:109], v[164:167], v[210:213], v[106:109]
	v_mfma_f32_16x16x32_bf16 v[94:97], v[134:137], v[218:221], v[94:97]
	v_mfma_f32_16x16x32_bf16 v[90:93], v[164:167], v[218:221], v[90:93]
	v_mfma_f32_16x16x32_bf16 v[78:81], v[134:137], v[226:229], v[78:81]
	v_mfma_f32_16x16x32_bf16 v[74:77], v[164:167], v[226:229], v[74:77]
	v_mfma_f32_16x16x32_bf16 v[118:121], v[172:175], v[198:201], v[118:121]
	v_mfma_f32_16x16x32_bf16 v[114:117], v[190:193], v[198:201], v[114:117]
	v_mfma_f32_16x16x32_bf16 v[102:105], v[172:175], v[206:209], v[102:105]
	v_mfma_f32_16x16x32_bf16 v[98:101], v[190:193], v[206:209], v[98:101]
	v_mfma_f32_16x16x32_bf16 v[86:89], v[172:175], v[214:217], v[86:89]
	v_mfma_f32_16x16x32_bf16 v[82:85], v[190:193], v[214:217], v[82:85]
	v_mfma_f32_16x16x32_bf16 v[70:73], v[172:175], v[222:225], v[70:73]
	v_mfma_f32_16x16x32_bf16 v[66:69], v[190:193], v[222:225], v[66:69]
	v_mfma_f32_16x16x32_bf16 v[118:121], v[176:179], v[202:205], v[118:121]
	v_mfma_f32_16x16x32_bf16 v[114:117], v[194:197], v[202:205], v[114:117]
	v_mfma_f32_16x16x32_bf16 v[102:105], v[176:179], v[210:213], v[102:105]
	v_mfma_f32_16x16x32_bf16 v[98:101], v[194:197], v[210:213], v[98:101]
	v_mfma_f32_16x16x32_bf16 v[86:89], v[176:179], v[218:221], v[86:89]
	v_mfma_f32_16x16x32_bf16 v[82:85], v[194:197], v[218:221], v[82:85]
	v_mfma_f32_16x16x32_bf16 v[70:73], v[176:179], v[226:229], v[70:73]
	v_mfma_f32_16x16x32_bf16 v[66:69], v[194:197], v[226:229], v[66:69]
	s_setprio 0
	s_barrier
	s_add_i32 s69, s69, s43
	v_lshl_add_u64 v[152:153], s[70:71], 0, v[140:141]
	s_mov_b32 m0, s69
	ds_read_b128 v[198:201], v157 offset:16384
	ds_read_b128 v[202:205], v157 offset:17408
	ds_read_b128 v[206:209], v157 offset:18432
	ds_read_b128 v[210:213], v157 offset:19456
	ds_read_b128 v[214:217], v157 offset:20480
	ds_read_b128 v[218:221], v157 offset:21504
	ds_read_b128 v[222:225], v157 offset:22528
	ds_read_b128 v[226:229], v157 offset:23552
	global_load_lds_dwordx4 v[152:153], off
	v_lshl_add_u64 v[180:181], v[152:153], 0, s[24:25]
	s_add_i32 m0, s69, 0x2000
	s_add_i32 s69, s72, s43
	global_load_lds_dwordx4 v[180:181], off
	v_lshl_add_u64 v[180:181], v[152:153], 0, s[22:23]
	s_mov_b32 m0, s69
	s_nop 0
	global_load_lds_dwordx4 v[180:181], off
	v_lshl_add_u64 v[180:181], v[152:153], 0, s[28:29]
	s_add_i32 m0, s69, 0x2000
	s_nop 0
	global_load_lds_dwordx4 v[180:181], off
	v_lshl_add_u64 v[180:181], s[40:41], 0, v[138:139]
	s_mov_b32 m0, s54
	v_lshl_add_u64 v[230:231], v[180:181], 0, s[24:25]
	global_load_lds_dwordx4 v[180:181], off
	s_mov_b32 m0, s55
	s_nop 0
	global_load_lds_dwordx4 v[230:231], off
	s_waitcnt vmcnt(8)
	s_waitcnt lgkmcnt(0)
	s_barrier
	s_setprio 1
	s_waitcnt lgkmcnt(0)
	v_mfma_f32_16x16x32_bf16 v[62:65], v[130:133], v[198:201], v[62:65]
	v_mfma_f32_16x16x32_bf16 v[58:61], v[148:151], v[198:201], v[58:61]
	v_mfma_f32_16x16x32_bf16 v[46:49], v[130:133], v[206:209], v[46:49]
	v_mfma_f32_16x16x32_bf16 v[42:45], v[148:151], v[206:209], v[42:45]
	v_mfma_f32_16x16x32_bf16 v[30:33], v[130:133], v[214:217], v[30:33]
	v_mfma_f32_16x16x32_bf16 v[26:29], v[148:151], v[214:217], v[26:29]
	v_mfma_f32_16x16x32_bf16 v[14:17], v[130:133], v[222:225], v[14:17]
	v_mfma_f32_16x16x32_bf16 v[10:13], v[148:151], v[222:225], v[10:13]
	v_mfma_f32_16x16x32_bf16 v[62:65], v[134:137], v[202:205], v[62:65]
	v_mfma_f32_16x16x32_bf16 v[58:61], v[164:167], v[202:205], v[58:61]
	v_mfma_f32_16x16x32_bf16 v[46:49], v[134:137], v[210:213], v[46:49]
	v_mfma_f32_16x16x32_bf16 v[42:45], v[164:167], v[210:213], v[42:45]
	v_mfma_f32_16x16x32_bf16 v[30:33], v[134:137], v[218:221], v[30:33]
	v_mfma_f32_16x16x32_bf16 v[26:29], v[164:167], v[218:221], v[26:29]
	v_mfma_f32_16x16x32_bf16 v[14:17], v[134:137], v[226:229], v[14:17]
	v_mfma_f32_16x16x32_bf16 v[10:13], v[164:167], v[226:229], v[10:13]
	v_mfma_f32_16x16x32_bf16 v[54:57], v[172:175], v[198:201], v[54:57]
	v_mfma_f32_16x16x32_bf16 v[50:53], v[190:193], v[198:201], v[50:53]
	v_mfma_f32_16x16x32_bf16 v[38:41], v[172:175], v[206:209], v[38:41]
	v_mfma_f32_16x16x32_bf16 v[34:37], v[190:193], v[206:209], v[34:37]
	v_mfma_f32_16x16x32_bf16 v[22:25], v[172:175], v[214:217], v[22:25]
	v_mfma_f32_16x16x32_bf16 v[18:21], v[190:193], v[214:217], v[18:21]
	v_mfma_f32_16x16x32_bf16 v[6:9], v[172:175], v[222:225], v[6:9]
	v_mfma_f32_16x16x32_bf16 v[2:5], v[190:193], v[222:225], v[2:5]
	v_mfma_f32_16x16x32_bf16 v[54:57], v[176:179], v[202:205], v[54:57]
	v_mfma_f32_16x16x32_bf16 v[50:53], v[194:197], v[202:205], v[50:53]
	v_mfma_f32_16x16x32_bf16 v[38:41], v[176:179], v[210:213], v[38:41]
	v_mfma_f32_16x16x32_bf16 v[34:37], v[194:197], v[210:213], v[34:37]
	v_mfma_f32_16x16x32_bf16 v[22:25], v[176:179], v[218:221], v[22:25]
	v_mfma_f32_16x16x32_bf16 v[18:21], v[194:197], v[218:221], v[18:21]
	v_mfma_f32_16x16x32_bf16 v[6:9], v[176:179], v[226:229], v[6:9]
	v_mfma_f32_16x16x32_bf16 v[2:5], v[194:197], v[226:229], v[2:5]
	s_setprio 0
	s_barrier
	s_add_i32 s40, 0, 0x18000
	v_add_u32_e32 v145, s40, v155
	s_add_i32 s41, 0, 0x1c000
	ds_read_b128 v[130:133], v145
	ds_read_b128 v[134:137], v145 offset:1024
	ds_read_b128 v[148:151], v145 offset:2048
	ds_read_b128 v[164:167], v145 offset:3072
	v_add_u32_e32 v145, s41, v155
	ds_read_b128 v[172:175], v145
	ds_read_b128 v[176:179], v145 offset:1024
	ds_read_b128 v[190:193], v145 offset:2048
	ds_read_b128 v[194:197], v145 offset:3072
	s_mov_b32 m0, s57
	v_lshl_add_u64 v[230:231], v[180:181], 0, s[22:23]
	ds_read_b128 v[198:201], v157 offset:32768
	ds_read_b128 v[202:205], v157 offset:33792
	ds_read_b128 v[206:209], v157 offset:34816
	ds_read_b128 v[210:213], v157 offset:35840
	ds_read_b128 v[214:217], v157 offset:36864
	ds_read_b128 v[218:221], v157 offset:37888
	ds_read_b128 v[222:225], v157 offset:38912
	ds_read_b128 v[226:229], v157 offset:39936
	global_load_lds_dwordx4 v[230:231], off
	v_lshl_add_u64 v[230:231], v[180:181], 0, s[28:29]
	s_mov_b32 m0, s58
	s_nop 0
	global_load_lds_dwordx4 v[230:231], off
	s_waitcnt vmcnt(8)
	s_waitcnt lgkmcnt(0)
	s_barrier
	s_setprio 1
	s_waitcnt lgkmcnt(0)
	v_mfma_f32_16x16x32_bf16 v[126:129], v[130:133], v[198:201], v[126:129]
	v_mfma_f32_16x16x32_bf16 v[122:125], v[148:151], v[198:201], v[122:125]
	v_mfma_f32_16x16x32_bf16 v[110:113], v[130:133], v[206:209], v[110:113]
	v_mfma_f32_16x16x32_bf16 v[106:109], v[148:151], v[206:209], v[106:109]
	v_mfma_f32_16x16x32_bf16 v[94:97], v[130:133], v[214:217], v[94:97]
	v_mfma_f32_16x16x32_bf16 v[90:93], v[148:151], v[214:217], v[90:93]
	v_mfma_f32_16x16x32_bf16 v[78:81], v[130:133], v[222:225], v[78:81]
	v_mfma_f32_16x16x32_bf16 v[74:77], v[148:151], v[222:225], v[74:77]
	v_mfma_f32_16x16x32_bf16 v[126:129], v[134:137], v[202:205], v[126:129]
	v_mfma_f32_16x16x32_bf16 v[122:125], v[164:167], v[202:205], v[122:125]
	v_mfma_f32_16x16x32_bf16 v[110:113], v[134:137], v[210:213], v[110:113]
	v_mfma_f32_16x16x32_bf16 v[106:109], v[164:167], v[210:213], v[106:109]
	v_mfma_f32_16x16x32_bf16 v[94:97], v[134:137], v[218:221], v[94:97]
	v_mfma_f32_16x16x32_bf16 v[90:93], v[164:167], v[218:221], v[90:93]
	v_mfma_f32_16x16x32_bf16 v[78:81], v[134:137], v[226:229], v[78:81]
	v_mfma_f32_16x16x32_bf16 v[74:77], v[164:167], v[226:229], v[74:77]
	v_mfma_f32_16x16x32_bf16 v[118:121], v[172:175], v[198:201], v[118:121]
	v_mfma_f32_16x16x32_bf16 v[114:117], v[190:193], v[198:201], v[114:117]
	v_mfma_f32_16x16x32_bf16 v[102:105], v[172:175], v[206:209], v[102:105]
	v_mfma_f32_16x16x32_bf16 v[98:101], v[190:193], v[206:209], v[98:101]
	v_mfma_f32_16x16x32_bf16 v[86:89], v[172:175], v[214:217], v[86:89]
	v_mfma_f32_16x16x32_bf16 v[82:85], v[190:193], v[214:217], v[82:85]
	v_mfma_f32_16x16x32_bf16 v[70:73], v[172:175], v[222:225], v[70:73]
	v_mfma_f32_16x16x32_bf16 v[66:69], v[190:193], v[222:225], v[66:69]
	v_mfma_f32_16x16x32_bf16 v[118:121], v[176:179], v[202:205], v[118:121]
	v_mfma_f32_16x16x32_bf16 v[114:117], v[194:197], v[202:205], v[114:117]
	v_mfma_f32_16x16x32_bf16 v[102:105], v[176:179], v[210:213], v[102:105]
	v_mfma_f32_16x16x32_bf16 v[98:101], v[194:197], v[210:213], v[98:101]
	v_mfma_f32_16x16x32_bf16 v[86:89], v[176:179], v[218:221], v[86:89]
	v_mfma_f32_16x16x32_bf16 v[82:85], v[194:197], v[218:221], v[82:85]
	v_mfma_f32_16x16x32_bf16 v[70:73], v[176:179], v[226:229], v[70:73]
	v_mfma_f32_16x16x32_bf16 v[66:69], v[194:197], v[226:229], v[66:69]
	s_setprio 0
	s_barrier
	s_add_i32 s40, s40, s43
	v_lshl_add_u64 v[230:231], v[152:153], 0, s[30:31]
	s_mov_b32 m0, s40
	ds_read_b128 v[198:201], v157 offset:49152
	ds_read_b128 v[202:205], v157 offset:50176
	ds_read_b128 v[206:209], v157 offset:51200
	ds_read_b128 v[210:213], v157 offset:52224
	ds_read_b128 v[214:217], v157 offset:53248
	ds_read_b128 v[218:221], v157 offset:54272
	ds_read_b128 v[222:225], v157 offset:55296
	ds_read_b128 v[226:229], v157 offset:56320
	global_load_lds_dwordx4 v[230:231], off
	v_lshl_add_u64 v[230:231], v[152:153], 0, s[34:35]
	s_add_i32 m0, s40, 0x2000
	s_add_i32 s40, s41, s43
	global_load_lds_dwordx4 v[230:231], off
	v_lshl_add_u64 v[230:231], v[152:153], 0, s[88:89]
	s_mov_b32 m0, s40
	v_lshl_add_u64 v[152:153], v[152:153], 0, s[90:91]
	global_load_lds_dwordx4 v[230:231], off
	s_add_i32 m0, s40, 0x2000
	s_nop 0
	global_load_lds_dwordx4 v[152:153], off
	v_lshl_add_u64 v[152:153], v[180:181], 0, s[30:31]
	s_mov_b32 m0, s59
	s_nop 0
	global_load_lds_dwordx4 v[152:153], off
	v_lshl_add_u64 v[152:153], v[180:181], 0, s[34:35]
	s_mov_b32 m0, s60
	s_nop 0
	global_load_lds_dwordx4 v[152:153], off
	s_waitcnt vmcnt(8)
	s_waitcnt lgkmcnt(0)
	s_barrier
	s_setprio 1
	s_waitcnt lgkmcnt(0)
	v_mfma_f32_16x16x32_bf16 v[62:65], v[130:133], v[198:201], v[62:65]
	v_mfma_f32_16x16x32_bf16 v[58:61], v[148:151], v[198:201], v[58:61]
	v_mfma_f32_16x16x32_bf16 v[46:49], v[130:133], v[206:209], v[46:49]
	v_mfma_f32_16x16x32_bf16 v[42:45], v[148:151], v[206:209], v[42:45]
	v_mfma_f32_16x16x32_bf16 v[30:33], v[130:133], v[214:217], v[30:33]
	v_mfma_f32_16x16x32_bf16 v[26:29], v[148:151], v[214:217], v[26:29]
	v_mfma_f32_16x16x32_bf16 v[14:17], v[130:133], v[222:225], v[14:17]
	v_mfma_f32_16x16x32_bf16 v[10:13], v[148:151], v[222:225], v[10:13]
	v_mfma_f32_16x16x32_bf16 v[62:65], v[134:137], v[202:205], v[62:65]
	v_mfma_f32_16x16x32_bf16 v[58:61], v[164:167], v[202:205], v[58:61]
	v_mfma_f32_16x16x32_bf16 v[46:49], v[134:137], v[210:213], v[46:49]
	v_mfma_f32_16x16x32_bf16 v[42:45], v[164:167], v[210:213], v[42:45]
	v_mfma_f32_16x16x32_bf16 v[30:33], v[134:137], v[218:221], v[30:33]
	v_mfma_f32_16x16x32_bf16 v[26:29], v[164:167], v[218:221], v[26:29]
	v_mfma_f32_16x16x32_bf16 v[14:17], v[134:137], v[226:229], v[14:17]
	v_mfma_f32_16x16x32_bf16 v[10:13], v[164:167], v[226:229], v[10:13]
	v_mfma_f32_16x16x32_bf16 v[54:57], v[172:175], v[198:201], v[54:57]
	v_mfma_f32_16x16x32_bf16 v[50:53], v[190:193], v[198:201], v[50:53]
	v_mfma_f32_16x16x32_bf16 v[38:41], v[172:175], v[206:209], v[38:41]
	v_mfma_f32_16x16x32_bf16 v[34:37], v[190:193], v[206:209], v[34:37]
	v_mfma_f32_16x16x32_bf16 v[22:25], v[172:175], v[214:217], v[22:25]
	v_mfma_f32_16x16x32_bf16 v[18:21], v[190:193], v[214:217], v[18:21]
	v_mfma_f32_16x16x32_bf16 v[6:9], v[172:175], v[222:225], v[6:9]
	v_mfma_f32_16x16x32_bf16 v[2:5], v[190:193], v[222:225], v[2:5]
	v_mfma_f32_16x16x32_bf16 v[54:57], v[176:179], v[202:205], v[54:57]
	v_mfma_f32_16x16x32_bf16 v[50:53], v[194:197], v[202:205], v[50:53]
	v_mfma_f32_16x16x32_bf16 v[38:41], v[176:179], v[210:213], v[38:41]
	v_mfma_f32_16x16x32_bf16 v[34:37], v[194:197], v[210:213], v[34:37]
	v_mfma_f32_16x16x32_bf16 v[22:25], v[176:179], v[218:221], v[22:25]
	v_mfma_f32_16x16x32_bf16 v[18:21], v[194:197], v[218:221], v[18:21]
	v_mfma_f32_16x16x32_bf16 v[6:9], v[176:179], v[226:229], v[6:9]
	v_mfma_f32_16x16x32_bf16 v[2:5], v[194:197], v[226:229], v[2:5]
	s_setprio 0
	s_barrier
	s_add_i32 s68, s68, 2
	s_add_u32 s38, s38, 0x100
	s_addc_u32 s39, s39, 0
	s_add_u32 s66, s66, 0x100
	s_addc_u32 s67, s67, 0
	s_cmp_gt_u32 s68, 61
	s_cbranch_scc0 .LBB0_3117
	s_and_b64 vcc, exec, s[12:13]
	s_cbranch_vccz .LBB0_3120
	s_barrier

.LBB0_3143:
	s_add_u32 s42, s40, 0xfff00080
	s_addc_u32 s43, s41, -1
	s_add_i32 s74, 0, 0x10000
	s_cmp_eq_u32 s71, 60
	s_cselect_b32 s43, s19, s43
	s_cselect_b32 s42, s39, s42
	s_cselect_b32 s73, s17, s70
	s_cselect_b32 s72, s68, s69
	s_add_i32 s75, 0, 0x14000
	v_add_u32_e32 v146, s74, v151
	v_add_u32_e32 v162, s75, v151
	ds_read_b128 v[130:133], v146
	ds_read_b128 v[134:137], v146 offset:1024
	ds_read_b128 v[142:145], v146 offset:2048
	ds_read_b128 v[146:149], v146 offset:3072
	ds_read_b128 v[154:157], v162
	ds_read_b128 v[158:161], v162 offset:1024
	ds_read_b128 v[164:167], v162 offset:2048
	ds_read_b128 v[172:175], v162 offset:3072
	v_lshl_add_u64 v[180:181], s[40:41], 0, v[140:141]
	s_add_i32 m0, s57, 0xc000
	ds_read_b128 v[176:179], v153
	ds_read_b128 v[190:193], v153 offset:1024
	ds_read_b128 v[194:197], v153 offset:2048
	ds_read_b128 v[198:201], v153 offset:3072
	ds_read_b128 v[202:205], v153 offset:4096
	ds_read_b128 v[206:209], v153 offset:5120
	ds_read_b128 v[210:213], v153 offset:6144
	ds_read_b128 v[214:217], v153 offset:7168
	global_load_lds_dwordx4 v[180:181], off
	v_lshl_add_u64 v[180:181], v[180:181], 0, s[24:25]
	s_add_i32 m0, s57, 0xe000
	s_nop 0
	global_load_lds_dwordx4 v[180:181], off
	s_waitcnt vmcnt(8)
	s_waitcnt lgkmcnt(0)
	s_barrier
	s_setprio 1
	s_waitcnt lgkmcnt(0)
	v_mfma_f32_16x16x32_bf16 v[126:129], v[130:133], v[176:179], v[126:129]
	v_mfma_f32_16x16x32_bf16 v[122:125], v[142:145], v[176:179], v[122:125]
	v_mfma_f32_16x16x32_bf16 v[110:113], v[130:133], v[194:197], v[110:113]
	v_mfma_f32_16x16x32_bf16 v[106:109], v[142:145], v[194:197], v[106:109]
	v_mfma_f32_16x16x32_bf16 v[94:97], v[130:133], v[202:205], v[94:97]
	v_mfma_f32_16x16x32_bf16 v[90:93], v[142:145], v[202:205], v[90:93]
	v_mfma_f32_16x16x32_bf16 v[78:81], v[130:133], v[210:213], v[78:81]
	v_mfma_f32_16x16x32_bf16 v[74:77], v[142:145], v[210:213], v[74:77]
	v_mfma_f32_16x16x32_bf16 v[126:129], v[134:137], v[190:193], v[126:129]
	v_mfma_f32_16x16x32_bf16 v[122:125], v[146:149], v[190:193], v[122:125]
	v_mfma_f32_16x16x32_bf16 v[110:113], v[134:137], v[198:201], v[110:113]
	v_mfma_f32_16x16x32_bf16 v[106:109], v[146:149], v[198:201], v[106:109]
	v_mfma_f32_16x16x32_bf16 v[94:97], v[134:137], v[206:209], v[94:97]
	v_mfma_f32_16x16x32_bf16 v[90:93], v[146:149], v[206:209], v[90:93]
	v_mfma_f32_16x16x32_bf16 v[78:81], v[134:137], v[214:217], v[78:81]
	v_mfma_f32_16x16x32_bf16 v[74:77], v[146:149], v[214:217], v[74:77]
	v_mfma_f32_16x16x32_bf16 v[118:121], v[154:157], v[176:179], v[118:121]
	v_mfma_f32_16x16x32_bf16 v[114:117], v[164:167], v[176:179], v[114:117]
	v_mfma_f32_16x16x32_bf16 v[102:105], v[154:157], v[194:197], v[102:105]
	v_mfma_f32_16x16x32_bf16 v[98:101], v[164:167], v[194:197], v[98:101]
	v_mfma_f32_16x16x32_bf16 v[86:89], v[154:157], v[202:205], v[86:89]
	v_mfma_f32_16x16x32_bf16 v[82:85], v[164:167], v[202:205], v[82:85]
	v_mfma_f32_16x16x32_bf16 v[70:73], v[154:157], v[210:213], v[70:73]
	v_mfma_f32_16x16x32_bf16 v[66:69], v[164:167], v[210:213], v[66:69]
	v_mfma_f32_16x16x32_bf16 v[118:121], v[158:161], v[190:193], v[118:121]
	v_mfma_f32_16x16x32_bf16 v[114:117], v[172:175], v[190:193], v[114:117]
	v_mfma_f32_16x16x32_bf16 v[102:105], v[158:161], v[198:201], v[102:105]
	v_mfma_f32_16x16x32_bf16 v[98:101], v[172:175], v[198:201], v[98:101]
	v_mfma_f32_16x16x32_bf16 v[86:89], v[158:161], v[206:209], v[86:89]
	v_mfma_f32_16x16x32_bf16 v[82:85], v[172:175], v[206:209], v[82:85]
	v_mfma_f32_16x16x32_bf16 v[70:73], v[158:161], v[214:217], v[70:73]
	v_mfma_f32_16x16x32_bf16 v[66:69], v[172:175], v[214:217], v[66:69]
	s_setprio 0
	s_barrier
	v_lshl_add_u64 v[180:181], s[72:73], 0, v[0:1]
	s_add_i32 s72, s74, s55
	s_mov_b32 m0, s72
	ds_read_b128 v[176:179], v153 offset:16384
	ds_read_b128 v[190:193], v153 offset:17408
	ds_read_b128 v[194:197], v153 offset:18432
	ds_read_b128 v[198:201], v153 offset:19456
	ds_read_b128 v[202:205], v153 offset:20480
	ds_read_b128 v[206:209], v153 offset:21504
	ds_read_b128 v[210:213], v153 offset:22528
	ds_read_b128 v[214:217], v153 offset:23552
	global_load_lds_dwordx4 v[180:181], off
	v_lshl_add_u64 v[218:219], v[180:181], 0, s[24:25]
	s_add_i32 m0, s72, 0x2000
	s_add_i32 s72, s75, s55
	global_load_lds_dwordx4 v[218:219], off
	v_lshl_add_u64 v[218:219], v[180:181], 0, s[22:23]
	s_mov_b32 m0, s72
	s_nop 0
	global_load_lds_dwordx4 v[218:219], off
	v_lshl_add_u64 v[218:219], v[180:181], 0, s[28:29]
	s_add_i32 m0, s72, 0x2000
	s_nop 0
	global_load_lds_dwordx4 v[218:219], off
	v_lshl_add_u64 v[218:219], s[42:43], 0, v[138:139]
	s_mov_b32 m0, s57
	v_lshl_add_u64 v[220:221], v[218:219], 0, s[24:25]
	global_load_lds_dwordx4 v[218:219], off
	s_mov_b32 m0, s58
	s_nop 0
	global_load_lds_dwordx4 v[220:221], off
	s_waitcnt vmcnt(8)
	s_waitcnt lgkmcnt(0)
	s_barrier
	s_setprio 1
	s_waitcnt lgkmcnt(0)
	v_mfma_f32_16x16x32_bf16 v[62:65], v[130:133], v[176:179], v[62:65]
	v_mfma_f32_16x16x32_bf16 v[58:61], v[142:145], v[176:179], v[58:61]
	v_mfma_f32_16x16x32_bf16 v[46:49], v[130:133], v[194:197], v[46:49]
	v_mfma_f32_16x16x32_bf16 v[42:45], v[142:145], v[194:197], v[42:45]
	v_mfma_f32_16x16x32_bf16 v[30:33], v[130:133], v[202:205], v[30:33]
	v_mfma_f32_16x16x32_bf16 v[26:29], v[142:145], v[202:205], v[26:29]
	v_mfma_f32_16x16x32_bf16 v[14:17], v[130:133], v[210:213], v[14:17]
	v_mfma_f32_16x16x32_bf16 v[10:13], v[142:145], v[210:213], v[10:13]
	v_mfma_f32_16x16x32_bf16 v[62:65], v[134:137], v[190:193], v[62:65]
	v_mfma_f32_16x16x32_bf16 v[58:61], v[146:149], v[190:193], v[58:61]
	v_mfma_f32_16x16x32_bf16 v[46:49], v[134:137], v[198:201], v[46:49]
	v_mfma_f32_16x16x32_bf16 v[42:45], v[146:149], v[198:201], v[42:45]
	v_mfma_f32_16x16x32_bf16 v[30:33], v[134:137], v[206:209], v[30:33]
	v_mfma_f32_16x16x32_bf16 v[26:29], v[146:149], v[206:209], v[26:29]
	v_mfma_f32_16x16x32_bf16 v[14:17], v[134:137], v[214:217], v[14:17]
	v_mfma_f32_16x16x32_bf16 v[10:13], v[146:149], v[214:217], v[10:13]
	v_mfma_f32_16x16x32_bf16 v[54:57], v[154:157], v[176:179], v[54:57]
	v_mfma_f32_16x16x32_bf16 v[50:53], v[164:167], v[176:179], v[50:53]
	v_mfma_f32_16x16x32_bf16 v[38:41], v[154:157], v[194:197], v[38:41]
	v_mfma_f32_16x16x32_bf16 v[34:37], v[164:167], v[194:197], v[34:37]
	v_mfma_f32_16x16x32_bf16 v[22:25], v[154:157], v[202:205], v[22:25]
	v_mfma_f32_16x16x32_bf16 v[18:21], v[164:167], v[202:205], v[18:21]
	v_mfma_f32_16x16x32_bf16 v[6:9], v[154:157], v[210:213], v[6:9]
	v_mfma_f32_16x16x32_bf16 v[2:5], v[164:167], v[210:213], v[2:5]
	v_mfma_f32_16x16x32_bf16 v[54:57], v[158:161], v[190:193], v[54:57]
	v_mfma_f32_16x16x32_bf16 v[50:53], v[172:175], v[190:193], v[50:53]
	v_mfma_f32_16x16x32_bf16 v[38:41], v[158:161], v[198:201], v[38:41]
	v_mfma_f32_16x16x32_bf16 v[34:37], v[172:175], v[198:201], v[34:37]
	v_mfma_f32_16x16x32_bf16 v[22:25], v[158:161], v[206:209], v[22:25]
	v_mfma_f32_16x16x32_bf16 v[18:21], v[172:175], v[206:209], v[18:21]
	v_mfma_f32_16x16x32_bf16 v[6:9], v[158:161], v[214:217], v[6:9]
	v_mfma_f32_16x16x32_bf16 v[2:5], v[172:175], v[214:217], v[2:5]
	s_setprio 0
	s_barrier
	s_add_i32 s42, 0, 0x18000
	s_add_i32 s43, 0, 0x1c000
	v_add_u32_e32 v146, s42, v151
	v_add_u32_e32 v162, s43, v151
	ds_read_b128 v[130:133], v146
	ds_read_b128 v[134:137], v146 offset:1024
	ds_read_b128 v[142:145], v146 offset:2048
	ds_read_b128 v[146:149], v146 offset:3072
	ds_read_b128 v[154:157], v162
	ds_read_b128 v[158:161], v162 offset:1024
	ds_read_b128 v[164:167], v162 offset:2048
	ds_read_b128 v[172:175], v162 offset:3072
	s_mov_b32 m0, s59
	v_lshl_add_u64 v[220:221], v[218:219], 0, s[22:23]
	ds_read_b128 v[176:179], v153 offset:32768
	ds_read_b128 v[190:193], v153 offset:33792
	ds_read_b128 v[194:197], v153 offset:34816
	ds_read_b128 v[198:201], v153 offset:35840
	ds_read_b128 v[202:205], v153 offset:36864
	ds_read_b128 v[206:209], v153 offset:37888
	ds_read_b128 v[210:213], v153 offset:38912
	ds_read_b128 v[214:217], v153 offset:39936
	global_load_lds_dwordx4 v[220:221], off
	v_lshl_add_u64 v[220:221], v[218:219], 0, s[28:29]
	s_mov_b32 m0, s60
	s_nop 0
	global_load_lds_dwordx4 v[220:221], off
	s_waitcnt vmcnt(8)
	s_waitcnt lgkmcnt(0)
	s_barrier
	s_setprio 1
	s_waitcnt lgkmcnt(0)
	v_mfma_f32_16x16x32_bf16 v[126:129], v[130:133], v[176:179], v[126:129]
	v_mfma_f32_16x16x32_bf16 v[122:125], v[142:145], v[176:179], v[122:125]
	v_mfma_f32_16x16x32_bf16 v[110:113], v[130:133], v[194:197], v[110:113]
	v_mfma_f32_16x16x32_bf16 v[106:109], v[142:145], v[194:197], v[106:109]
	v_mfma_f32_16x16x32_bf16 v[94:97], v[130:133], v[202:205], v[94:97]
	v_mfma_f32_16x16x32_bf16 v[90:93], v[142:145], v[202:205], v[90:93]
	v_mfma_f32_16x16x32_bf16 v[78:81], v[130:133], v[210:213], v[78:81]
	v_mfma_f32_16x16x32_bf16 v[74:77], v[142:145], v[210:213], v[74:77]
	v_mfma_f32_16x16x32_bf16 v[126:129], v[134:137], v[190:193], v[126:129]
	v_mfma_f32_16x16x32_bf16 v[122:125], v[146:149], v[190:193], v[122:125]
	v_mfma_f32_16x16x32_bf16 v[110:113], v[134:137], v[198:201], v[110:113]
	v_mfma_f32_16x16x32_bf16 v[106:109], v[146:149], v[198:201], v[106:109]
	v_mfma_f32_16x16x32_bf16 v[94:97], v[134:137], v[206:209], v[94:97]
	v_mfma_f32_16x16x32_bf16 v[90:93], v[146:149], v[206:209], v[90:93]
	v_mfma_f32_16x16x32_bf16 v[78:81], v[134:137], v[214:217], v[78:81]
	v_mfma_f32_16x16x32_bf16 v[74:77], v[146:149], v[214:217], v[74:77]
	v_mfma_f32_16x16x32_bf16 v[118:121], v[154:157], v[176:179], v[118:121]
	v_mfma_f32_16x16x32_bf16 v[114:117], v[164:167], v[176:179], v[114:117]
	v_mfma_f32_16x16x32_bf16 v[102:105], v[154:157], v[194:197], v[102:105]
	v_mfma_f32_16x16x32_bf16 v[98:101], v[164:167], v[194:197], v[98:101]
	v_mfma_f32_16x16x32_bf16 v[86:89], v[154:157], v[202:205], v[86:89]
	v_mfma_f32_16x16x32_bf16 v[82:85], v[164:167], v[202:205], v[82:85]
	v_mfma_f32_16x16x32_bf16 v[70:73], v[154:157], v[210:213], v[70:73]
	v_mfma_f32_16x16x32_bf16 v[66:69], v[164:167], v[210:213], v[66:69]
	v_mfma_f32_16x16x32_bf16 v[118:121], v[158:161], v[190:193], v[118:121]
	v_mfma_f32_16x16x32_bf16 v[114:117], v[172:175], v[190:193], v[114:117]
	v_mfma_f32_16x16x32_bf16 v[102:105], v[158:161], v[198:201], v[102:105]
	v_mfma_f32_16x16x32_bf16 v[98:101], v[172:175], v[198:201], v[98:101]
	v_mfma_f32_16x16x32_bf16 v[86:89], v[158:161], v[206:209], v[86:89]
	v_mfma_f32_16x16x32_bf16 v[82:85], v[172:175], v[206:209], v[82:85]
	v_mfma_f32_16x16x32_bf16 v[70:73], v[158:161], v[214:217], v[70:73]
	v_mfma_f32_16x16x32_bf16 v[66:69], v[172:175], v[214:217], v[66:69]
	s_setprio 0
	s_barrier
	s_add_i32 s42, s42, s55
	v_lshl_add_u64 v[220:221], v[180:181], 0, s[30:31]
	s_mov_b32 m0, s42
	ds_read_b128 v[176:179], v153 offset:49152
	ds_read_b128 v[190:193], v153 offset:50176
	ds_read_b128 v[194:197], v153 offset:51200
	ds_read_b128 v[198:201], v153 offset:52224
	ds_read_b128 v[202:205], v153 offset:53248
	ds_read_b128 v[206:209], v153 offset:54272
	ds_read_b128 v[210:213], v153 offset:55296
	ds_read_b128 v[214:217], v153 offset:56320
	global_load_lds_dwordx4 v[220:221], off
	v_lshl_add_u64 v[220:221], v[180:181], 0, s[34:35]
	s_add_i32 m0, s42, 0x2000
	s_add_i32 s42, s43, s55
	global_load_lds_dwordx4 v[220:221], off
	v_lshl_add_u64 v[220:221], v[180:181], 0, s[88:89]
	s_mov_b32 m0, s42
	v_lshl_add_u64 v[180:181], v[180:181], 0, s[90:91]
	global_load_lds_dwordx4 v[220:221], off
	s_add_i32 m0, s42, 0x2000
	s_nop 0
	global_load_lds_dwordx4 v[180:181], off
	v_lshl_add_u64 v[180:181], v[218:219], 0, s[30:31]
	s_mov_b32 m0, s65
	s_nop 0
	global_load_lds_dwordx4 v[180:181], off
	v_lshl_add_u64 v[180:181], v[218:219], 0, s[34:35]
	s_mov_b32 m0, s66
	s_nop 0
	global_load_lds_dwordx4 v[180:181], off
	s_waitcnt vmcnt(8)
	s_waitcnt lgkmcnt(0)
	s_barrier
	s_setprio 1
	s_waitcnt lgkmcnt(0)
	v_mfma_f32_16x16x32_bf16 v[62:65], v[130:133], v[176:179], v[62:65]
	v_mfma_f32_16x16x32_bf16 v[58:61], v[142:145], v[176:179], v[58:61]
	v_mfma_f32_16x16x32_bf16 v[46:49], v[130:133], v[194:197], v[46:49]
	v_mfma_f32_16x16x32_bf16 v[42:45], v[142:145], v[194:197], v[42:45]
	v_mfma_f32_16x16x32_bf16 v[30:33], v[130:133], v[202:205], v[30:33]
	v_mfma_f32_16x16x32_bf16 v[26:29], v[142:145], v[202:205], v[26:29]
	v_mfma_f32_16x16x32_bf16 v[14:17], v[130:133], v[210:213], v[14:17]
	v_mfma_f32_16x16x32_bf16 v[10:13], v[142:145], v[210:213], v[10:13]
	v_mfma_f32_16x16x32_bf16 v[62:65], v[134:137], v[190:193], v[62:65]
	v_mfma_f32_16x16x32_bf16 v[58:61], v[146:149], v[190:193], v[58:61]
	v_mfma_f32_16x16x32_bf16 v[46:49], v[134:137], v[198:201], v[46:49]
	v_mfma_f32_16x16x32_bf16 v[42:45], v[146:149], v[198:201], v[42:45]
	v_mfma_f32_16x16x32_bf16 v[30:33], v[134:137], v[206:209], v[30:33]
	v_mfma_f32_16x16x32_bf16 v[26:29], v[146:149], v[206:209], v[26:29]
	v_mfma_f32_16x16x32_bf16 v[14:17], v[134:137], v[214:217], v[14:17]
	v_mfma_f32_16x16x32_bf16 v[10:13], v[146:149], v[214:217], v[10:13]
	v_mfma_f32_16x16x32_bf16 v[54:57], v[154:157], v[176:179], v[54:57]
	v_mfma_f32_16x16x32_bf16 v[50:53], v[164:167], v[176:179], v[50:53]
	v_mfma_f32_16x16x32_bf16 v[38:41], v[154:157], v[194:197], v[38:41]
	v_mfma_f32_16x16x32_bf16 v[34:37], v[164:167], v[194:197], v[34:37]
	v_mfma_f32_16x16x32_bf16 v[22:25], v[154:157], v[202:205], v[22:25]
	v_mfma_f32_16x16x32_bf16 v[18:21], v[164:167], v[202:205], v[18:21]
	v_mfma_f32_16x16x32_bf16 v[6:9], v[154:157], v[210:213], v[6:9]
	v_mfma_f32_16x16x32_bf16 v[2:5], v[164:167], v[210:213], v[2:5]
	v_mfma_f32_16x16x32_bf16 v[54:57], v[158:161], v[190:193], v[54:57]
	v_mfma_f32_16x16x32_bf16 v[50:53], v[172:175], v[190:193], v[50:53]
	v_mfma_f32_16x16x32_bf16 v[38:41], v[158:161], v[198:201], v[38:41]
	v_mfma_f32_16x16x32_bf16 v[34:37], v[172:175], v[198:201], v[34:37]
	v_mfma_f32_16x16x32_bf16 v[22:25], v[158:161], v[206:209], v[22:25]
	v_mfma_f32_16x16x32_bf16 v[18:21], v[172:175], v[206:209], v[18:21]
	v_mfma_f32_16x16x32_bf16 v[6:9], v[158:161], v[214:217], v[6:9]
	v_mfma_f32_16x16x32_bf16 v[2:5], v[172:175], v[214:217], v[2:5]
	s_setprio 0
	s_barrier
	s_add_i32 s71, s71, 2
	s_add_u32 s40, s40, 0x100
	s_addc_u32 s41, s41, 0
	s_add_u32 s69, s69, 0x100
	s_addc_u32 s70, s70, 0
	s_cmp_gt_u32 s71, 61
	s_cbranch_scc0 .LBB0_3143
	s_and_b64 vcc, exec, s[14:15]
	s_cbranch_vccz .LBB0_3146
	s_barrier
